# removed the no-op s_setprio 0 / s_setprio 1 pair in the middle of each 32-MFMA block (on top of chain+shared-src1 order)
# speedup vs baseline: 1.0002x; 1.0002x over previous
; #define PG8_STAGE(bufoff, gbase, voff) do { _Pragma("unroll") for (int _i = 0; _i < 2; ++_i) \
;         __builtin_amdgcn_global_load_lds((const unsigned*)((const char*)(gbase) + (voff)[_i]), (LAS unsigned*)(lds + (bufoff) + ldsw + _i * 8192), 16, 0, 0); } while (0)
; #define PG8_LDA(dst, b, h) do { _Pragma("unroll") for (int m = 0; m < 4; ++m) _Pragma("unroll") for (int k = 0; k < 2; ++k) dst[m][k] = *(const LAS bf16x8*)(lds + PG8_SA(b, h) + aoff + m * 2048 + k * 1024); } while (0)
; #define PG8_LDB(dst, b, h) do { _Pragma("unroll") for (int n = 0; n < 2; ++n) _Pragma("unroll") for (int k = 0; k < 2; ++k) dst[n][k] = *(const LAS bf16x8*)(lds + PG8_SB(b, h) + boff + n * 2048 + k * 1024); } while (0)
; #define PG8_MMA(ai, bj, At, Bt) do { __builtin_amdgcn_s_setprio(1); _Pragma("unroll") for (int m = 0; m < 4; ++m) _Pragma("unroll") for (int n = 0; n < 2; ++n) _Pragma("unroll") for (int k = 0; k < 2; ++k) \
;         acc[ai][bj][m][n] = __builtin_amdgcn_mfma_f32_16x16x32_bf16(Bt[n][k], At[m][k], acc[ai][bj][m][n], 0, 0, 0); __builtin_amdgcn_s_setprio(0); } while (0)
; #define PG8_WAIT_V(n) asm volatile("s_waitcnt vmcnt(" #n ")" ::: "memory")
; #define PG8_WAIT_L(n) asm volatile("s_waitcnt lgkmcnt(" #n ")" ::: "memory")
; #define PG8_BAR __builtin_amdgcn_s_barrier()
; #define PG8_SCHED __builtin_amdgcn_sched_barrier(0)
; template <class Epi>
; __device__ __forceinline__ void gemm_phase(LAS unsigned char* lds, const Gemm g, const StaticOrder& S, const Epi& E) {
;     ...
;             const bool last = (t == nt - 2);
;             const char* a1 = cA + (size_t)(t + 1) * kstep;
;             const char* a2 = last ? nA : cA + (size_t)(t + 2) * kstep; const char* b2 = last ? nB : cB + (size_t)(t + 2) * kstep;
;             const char* a3 = a2 + kstep; const char* b3 = b2 + kstep;
;             PG8_LDB(B0, 0, 0); PG8_LDB(B1, 0, 1); PG8_SCHED; PG8_LDA(At, 0, 0); PG8_STAGE(PG8_SA(1, 1), a1 + hstepA, voffA);
;             PG8_WAIT_V(8); PG8_WAIT_L(0); PG8_BAR; PG8_MMA(0, 0, At, B0); PG8_MMA(0, 1, At, B1); PG8_BAR; PG8_SCHED;
;             PG8_LDA(At, 0, 1); PG8_STAGE(PG8_SB(0, 0), b2, voffB); PG8_STAGE(PG8_SB(0, 1), b2 + hstepB, voffB); PG8_STAGE(PG8_SA(0, 0), a2, voffA);
;             PG8_WAIT_V(8); PG8_WAIT_L(0); PG8_BAR; PG8_MMA(1, 0, At, B0); PG8_MMA(1, 1, At, B1); PG8_BAR; PG8_SCHED;
.LBB0_245:
	ds_read_b128 v[152:155], v148
	ds_read_b128 v[156:159], v148 offset:1024
	ds_read_b128 v[160:163], v148 offset:2048
	ds_read_b128 v[164:167], v148 offset:3072
	ds_read_b128 v[168:171], v149
	ds_read_b128 v[172:175], v149 offset:1024
	ds_read_b128 v[176:179], v149 offset:2048
	ds_read_b128 v[180:183], v149 offset:3072
	s_add_i32 s64, s26, 2
	s_add_u32 s27, s24, 0xfff80080
	s_addc_u32 s30, s25, -1
	s_cmp_eq_u32 s54, s26
	s_cselect_b32 s26, s61, s62
	s_cselect_b32 s31, s15, s30
	s_cselect_b32 s30, s17, s27
	s_cselect_b32 s27, s60, s63
	v_lshl_add_u64 v[220:221], s[24:25], 0, v[138:139]
	s_add_i32 m0, s44, 0xc000
	ds_read_b128 v[184:187], v150
	ds_read_b128 v[188:191], v150 offset:1024
	ds_read_b128 v[192:195], v150 offset:2048
	ds_read_b128 v[196:199], v150 offset:3072
	ds_read_b128 v[200:203], v150 offset:4096
	ds_read_b128 v[208:211], v150 offset:5120
	ds_read_b128 v[212:215], v150 offset:6144
	ds_read_b128 v[216:219], v150 offset:7168
	global_load_lds_dwordx4 v[220:221], off
	v_lshl_add_u64 v[220:221], s[24:25], 0, v[140:141]
	s_add_i32 m0, s44, 0xe000
	s_nop 0
	global_load_lds_dwordx4 v[220:221], off
	s_waitcnt vmcnt(8)
	s_waitcnt lgkmcnt(0)
	s_barrier
	s_setprio 1
	s_waitcnt lgkmcnt(0)
	v_mfma_f32_16x16x32_bf16 v[120:123], v[152:155], v[184:187], v[120:123]
	v_mfma_f32_16x16x32_bf16 v[120:123], v[156:159], v[188:191], v[120:123]
	v_mfma_f32_16x16x32_bf16 v[116:119], v[164:167], v[188:191], v[116:119]
	v_mfma_f32_16x16x32_bf16 v[116:119], v[160:163], v[184:187], v[116:119]
	v_mfma_f32_16x16x32_bf16 v[124:127], v[168:171], v[184:187], v[124:127]
	v_mfma_f32_16x16x32_bf16 v[124:127], v[172:175], v[188:191], v[124:127]
	v_mfma_f32_16x16x32_bf16 v[112:115], v[180:183], v[188:191], v[112:115]
	v_mfma_f32_16x16x32_bf16 v[112:115], v[176:179], v[184:187], v[112:115]
	v_mfma_f32_16x16x32_bf16 v[96:99], v[176:179], v[192:195], v[96:99]
	v_mfma_f32_16x16x32_bf16 v[96:99], v[180:183], v[196:199], v[96:99]
	v_mfma_f32_16x16x32_bf16 v[104:107], v[172:175], v[196:199], v[104:107]
	v_mfma_f32_16x16x32_bf16 v[104:107], v[168:171], v[192:195], v[104:107]
	v_mfma_f32_16x16x32_bf16 v[100:103], v[160:163], v[192:195], v[100:103]
	v_mfma_f32_16x16x32_bf16 v[100:103], v[164:167], v[196:199], v[100:103]
	v_mfma_f32_16x16x32_bf16 v[108:111], v[156:159], v[196:199], v[108:111]
	v_mfma_f32_16x16x32_bf16 v[108:111], v[152:155], v[192:195], v[108:111]
	v_mfma_f32_16x16x32_bf16 v[92:95], v[152:155], v[200:203], v[92:95]
	v_mfma_f32_16x16x32_bf16 v[92:95], v[156:159], v[208:211], v[92:95]
	v_mfma_f32_16x16x32_bf16 v[84:87], v[164:167], v[208:211], v[84:87]
	v_mfma_f32_16x16x32_bf16 v[84:87], v[160:163], v[200:203], v[84:87]
	v_mfma_f32_16x16x32_bf16 v[88:91], v[168:171], v[200:203], v[88:91]
	v_mfma_f32_16x16x32_bf16 v[88:91], v[172:175], v[208:211], v[88:91]
	v_mfma_f32_16x16x32_bf16 v[80:83], v[180:183], v[208:211], v[80:83]
	v_mfma_f32_16x16x32_bf16 v[80:83], v[176:179], v[200:203], v[80:83]
	v_mfma_f32_16x16x32_bf16 v[64:67], v[176:179], v[212:215], v[64:67]
	v_mfma_f32_16x16x32_bf16 v[64:67], v[180:183], v[216:219], v[64:67]
	v_mfma_f32_16x16x32_bf16 v[72:75], v[172:175], v[216:219], v[72:75]
	v_mfma_f32_16x16x32_bf16 v[72:75], v[168:171], v[212:215], v[72:75]
	v_mfma_f32_16x16x32_bf16 v[68:71], v[160:163], v[212:215], v[68:71]
	v_mfma_f32_16x16x32_bf16 v[68:71], v[164:167], v[216:219], v[68:71]
	v_mfma_f32_16x16x32_bf16 v[76:79], v[156:159], v[216:219], v[76:79]
	v_mfma_f32_16x16x32_bf16 v[76:79], v[152:155], v[212:215], v[76:79]
	s_setprio 0
	s_barrier
	s_add_i32 s65, s57, s33
	v_lshl_add_u64 v[220:221], s[26:27], 0, v[132:133]
	s_mov_b32 m0, s65
	ds_read_b128 v[184:187], v150 offset:16384
	ds_read_b128 v[188:191], v150 offset:17408
	ds_read_b128 v[192:195], v150 offset:18432
	ds_read_b128 v[196:199], v150 offset:19456
	ds_read_b128 v[200:203], v150 offset:20480
	ds_read_b128 v[208:211], v150 offset:21504
	ds_read_b128 v[212:215], v150 offset:22528
	ds_read_b128 v[216:219], v150 offset:23552
	global_load_lds_dwordx4 v[220:221], off
	s_add_i32 m0, s65, 0x2000
	s_add_u32 s66, s26, 0x80000
	v_lshl_add_u64 v[222:223], s[26:27], 0, v[128:129]
	s_addc_u32 s67, s27, 0
	s_add_i32 s65, s58, s33
	global_load_lds_dwordx4 v[222:223], off
	v_lshl_add_u64 v[224:225], s[66:67], 0, v[132:133]
	s_mov_b32 m0, s65
	v_lshl_add_u64 v[226:227], s[30:31], 0, v[130:131]
	global_load_lds_dwordx4 v[224:225], off
	v_lshl_add_u64 v[224:225], s[66:67], 0, v[128:129]
	s_add_i32 m0, s65, 0x2000
	s_nop 0
	global_load_lds_dwordx4 v[224:225], off
	v_lshl_add_u64 v[224:225], s[30:31], 0, v[134:135]
	s_mov_b32 m0, s44
	s_nop 0
	global_load_lds_dwordx4 v[224:225], off
	s_mov_b32 m0, s45
	s_nop 0
	global_load_lds_dwordx4 v[226:227], off
	s_waitcnt vmcnt(8)
	s_waitcnt lgkmcnt(0)
	s_barrier
; #define PG8_STAGE(bufoff, gbase, voff) do { _Pragma("unroll") for (int _i = 0; _i < 2; ++_i) \
;         __builtin_amdgcn_global_load_lds((const unsigned*)((const char*)(gbase) + (voff)[_i]), (LAS unsigned*)(lds + (bufoff) + ldsw + _i * 8192), 16, 0, 0); } while (0)
; #define PG8_LDA(dst, b, h) do { _Pragma("unroll") for (int m = 0; m < 4; ++m) _Pragma("unroll") for (int k = 0; k < 2; ++k) dst[m][k] = *(const LAS bf16x8*)(lds + PG8_SA(b, h) + aoff + m * 2048 + k * 1024); } while (0)
; #define PG8_LDB(dst, b, h) do { _Pragma("unroll") for (int n = 0; n < 2; ++n) _Pragma("unroll") for (int k = 0; k < 2; ++k) dst[n][k] = *(const LAS bf16x8*)(lds + PG8_SB(b, h) + boff + n * 2048 + k * 1024); } while (0)
; #define PG8_MMA(ai, bj, At, Bt) do { __builtin_amdgcn_s_setprio(1); _Pragma("unroll") for (int m = 0; m < 4; ++m) _Pragma("unroll") for (int n = 0; n < 2; ++n) _Pragma("unroll") for (int k = 0; k < 2; ++k) \
;         acc[ai][bj][m][n] = __builtin_amdgcn_mfma_f32_16x16x32_bf16(Bt[n][k], At[m][k], acc[ai][bj][m][n], 0, 0, 0); __builtin_amdgcn_s_setprio(0); } while (0)
; #define PG8_WAIT_V(n) asm volatile("s_waitcnt vmcnt(" #n ")" ::: "memory")
; #define PG8_WAIT_L(n) asm volatile("s_waitcnt lgkmcnt(" #n ")" ::: "memory")
; #define PG8_BAR __builtin_amdgcn_s_barrier()
; #define PG8_SCHED __builtin_amdgcn_sched_barrier(0)
; template <class Epi>
; __device__ __forceinline__ void gemm_phase(LAS unsigned char* lds, const Gemm g, const StaticOrder& S, const Epi& E) {
;     ...
;             PG8_WAIT_V(8); PG8_WAIT_L(0); PG8_BAR; PG8_MMA(1, 0, At, B0); PG8_MMA(1, 1, At, B1); PG8_BAR; PG8_SCHED;
;             PG8_LDB(B0, 1, 0); PG8_LDB(B1, 1, 1); PG8_SCHED; PG8_LDA(At, 1, 0); PG8_STAGE(PG8_SA(0, 1), a2 + hstepA, voffA);
;             PG8_WAIT_V(8); PG8_WAIT_L(0); PG8_BAR; PG8_MMA(0, 0, At, B0); PG8_MMA(0, 1, At, B1); PG8_BAR; PG8_SCHED;
	s_setprio 1
	s_waitcnt lgkmcnt(0)
	v_mfma_f32_16x16x32_bf16 v[60:63], v[152:155], v[184:187], v[60:63]
	v_mfma_f32_16x16x32_bf16 v[60:63], v[156:159], v[188:191], v[60:63]
	v_mfma_f32_16x16x32_bf16 v[52:55], v[164:167], v[188:191], v[52:55]
	v_mfma_f32_16x16x32_bf16 v[52:55], v[160:163], v[184:187], v[52:55]
	v_mfma_f32_16x16x32_bf16 v[56:59], v[168:171], v[184:187], v[56:59]
	v_mfma_f32_16x16x32_bf16 v[56:59], v[172:175], v[188:191], v[56:59]
	v_mfma_f32_16x16x32_bf16 v[48:51], v[180:183], v[188:191], v[48:51]
	v_mfma_f32_16x16x32_bf16 v[48:51], v[176:179], v[184:187], v[48:51]
	v_mfma_f32_16x16x32_bf16 v[32:35], v[176:179], v[192:195], v[32:35]
	v_mfma_f32_16x16x32_bf16 v[32:35], v[180:183], v[196:199], v[32:35]
	v_mfma_f32_16x16x32_bf16 v[40:43], v[172:175], v[196:199], v[40:43]
	v_mfma_f32_16x16x32_bf16 v[40:43], v[168:171], v[192:195], v[40:43]
	v_mfma_f32_16x16x32_bf16 v[36:39], v[160:163], v[192:195], v[36:39]
	v_mfma_f32_16x16x32_bf16 v[36:39], v[164:167], v[196:199], v[36:39]
	v_mfma_f32_16x16x32_bf16 v[44:47], v[156:159], v[196:199], v[44:47]
	v_mfma_f32_16x16x32_bf16 v[44:47], v[152:155], v[192:195], v[44:47]
	v_mfma_f32_16x16x32_bf16 v[28:31], v[152:155], v[200:203], v[28:31]
	v_mfma_f32_16x16x32_bf16 v[28:31], v[156:159], v[208:211], v[28:31]
	v_mfma_f32_16x16x32_bf16 v[20:23], v[164:167], v[208:211], v[20:23]
	v_mfma_f32_16x16x32_bf16 v[20:23], v[160:163], v[200:203], v[20:23]
	v_mfma_f32_16x16x32_bf16 v[24:27], v[168:171], v[200:203], v[24:27]
	v_mfma_f32_16x16x32_bf16 v[24:27], v[172:175], v[208:211], v[24:27]
	v_mfma_f32_16x16x32_bf16 v[16:19], v[180:183], v[208:211], v[16:19]
	v_mfma_f32_16x16x32_bf16 v[16:19], v[176:179], v[200:203], v[16:19]
	v_mfma_f32_16x16x32_bf16 v[0:3], v[176:179], v[212:215], v[0:3]
	v_mfma_f32_16x16x32_bf16 v[0:3], v[180:183], v[216:219], v[0:3]
	v_mfma_f32_16x16x32_bf16 v[8:11], v[172:175], v[216:219], v[8:11]
	v_mfma_f32_16x16x32_bf16 v[8:11], v[168:171], v[212:215], v[8:11]
	v_mfma_f32_16x16x32_bf16 v[4:7], v[160:163], v[212:215], v[4:7]
	v_mfma_f32_16x16x32_bf16 v[4:7], v[164:167], v[216:219], v[4:7]
	v_mfma_f32_16x16x32_bf16 v[12:15], v[156:159], v[216:219], v[12:15]
	v_mfma_f32_16x16x32_bf16 v[12:15], v[152:155], v[212:215], v[12:15]
	s_setprio 0
	s_barrier
	s_add_i32 s65, 0, 0x18000
	v_add_u32_e32 v151, s65, v146
	s_add_i32 s66, 0, 0x1c000
	ds_read_b128 v[152:155], v151
	ds_read_b128 v[156:159], v151 offset:1024
	ds_read_b128 v[160:163], v151 offset:2048
	ds_read_b128 v[164:167], v151 offset:3072
	v_add_u32_e32 v151, s66, v146
	ds_read_b128 v[168:171], v151
	ds_read_b128 v[172:175], v151 offset:1024
	ds_read_b128 v[176:179], v151 offset:2048
	ds_read_b128 v[180:183], v151 offset:3072
	s_add_u32 s30, s30, 0x80000
	s_addc_u32 s31, s31, 0
	s_mov_b32 m0, s46
	v_lshl_add_u64 v[230:231], s[30:31], 0, v[134:135]
	ds_read_b128 v[184:187], v150 offset:32768
	ds_read_b128 v[188:191], v150 offset:33792
	ds_read_b128 v[192:195], v150 offset:34816
	ds_read_b128 v[196:199], v150 offset:35840
	ds_read_b128 v[200:203], v150 offset:36864
	ds_read_b128 v[208:211], v150 offset:37888
	ds_read_b128 v[212:215], v150 offset:38912
	ds_read_b128 v[216:219], v150 offset:39936
	global_load_lds_dwordx4 v[230:231], off
	v_lshl_add_u64 v[230:231], s[30:31], 0, v[130:131]
	s_mov_b32 m0, s47
	s_nop 0
	global_load_lds_dwordx4 v[230:231], off
	s_waitcnt vmcnt(8)
	s_waitcnt lgkmcnt(0)
	s_barrier
	s_setprio 1
	s_waitcnt lgkmcnt(0)
	v_mfma_f32_16x16x32_bf16 v[120:123], v[152:155], v[184:187], v[120:123]
	v_mfma_f32_16x16x32_bf16 v[120:123], v[156:159], v[188:191], v[120:123]
	v_mfma_f32_16x16x32_bf16 v[116:119], v[164:167], v[188:191], v[116:119]
	v_mfma_f32_16x16x32_bf16 v[116:119], v[160:163], v[184:187], v[116:119]
	v_mfma_f32_16x16x32_bf16 v[124:127], v[168:171], v[184:187], v[124:127]
	v_mfma_f32_16x16x32_bf16 v[124:127], v[172:175], v[188:191], v[124:127]
	v_mfma_f32_16x16x32_bf16 v[112:115], v[180:183], v[188:191], v[112:115]
	v_mfma_f32_16x16x32_bf16 v[112:115], v[176:179], v[184:187], v[112:115]
	v_mfma_f32_16x16x32_bf16 v[96:99], v[176:179], v[192:195], v[96:99]
	v_mfma_f32_16x16x32_bf16 v[96:99], v[180:183], v[196:199], v[96:99]
	v_mfma_f32_16x16x32_bf16 v[104:107], v[172:175], v[196:199], v[104:107]
	v_mfma_f32_16x16x32_bf16 v[104:107], v[168:171], v[192:195], v[104:107]
	v_mfma_f32_16x16x32_bf16 v[100:103], v[160:163], v[192:195], v[100:103]
	v_mfma_f32_16x16x32_bf16 v[100:103], v[164:167], v[196:199], v[100:103]
	v_mfma_f32_16x16x32_bf16 v[108:111], v[156:159], v[196:199], v[108:111]
	v_mfma_f32_16x16x32_bf16 v[108:111], v[152:155], v[192:195], v[108:111]
	v_mfma_f32_16x16x32_bf16 v[92:95], v[152:155], v[200:203], v[92:95]
	v_mfma_f32_16x16x32_bf16 v[92:95], v[156:159], v[208:211], v[92:95]
	v_mfma_f32_16x16x32_bf16 v[84:87], v[164:167], v[208:211], v[84:87]
	v_mfma_f32_16x16x32_bf16 v[84:87], v[160:163], v[200:203], v[84:87]
	v_mfma_f32_16x16x32_bf16 v[88:91], v[168:171], v[200:203], v[88:91]
	v_mfma_f32_16x16x32_bf16 v[88:91], v[172:175], v[208:211], v[88:91]
	v_mfma_f32_16x16x32_bf16 v[80:83], v[180:183], v[208:211], v[80:83]
	v_mfma_f32_16x16x32_bf16 v[80:83], v[176:179], v[200:203], v[80:83]
	v_mfma_f32_16x16x32_bf16 v[64:67], v[176:179], v[212:215], v[64:67]
	v_mfma_f32_16x16x32_bf16 v[64:67], v[180:183], v[216:219], v[64:67]
	v_mfma_f32_16x16x32_bf16 v[72:75], v[172:175], v[216:219], v[72:75]
	v_mfma_f32_16x16x32_bf16 v[72:75], v[168:171], v[212:215], v[72:75]
	v_mfma_f32_16x16x32_bf16 v[68:71], v[160:163], v[212:215], v[68:71]
	v_mfma_f32_16x16x32_bf16 v[68:71], v[164:167], v[216:219], v[68:71]
	v_mfma_f32_16x16x32_bf16 v[76:79], v[156:159], v[216:219], v[76:79]
	v_mfma_f32_16x16x32_bf16 v[76:79], v[152:155], v[212:215], v[76:79]
	s_setprio 0
	s_barrier
; #define PG8_STAGE(bufoff, gbase, voff) do { _Pragma("unroll") for (int _i = 0; _i < 2; ++_i) \
;         __builtin_amdgcn_global_load_lds((const unsigned*)((const char*)(gbase) + (voff)[_i]), (LAS unsigned*)(lds + (bufoff) + ldsw + _i * 8192), 16, 0, 0); } while (0)
; #define PG8_LDA(dst, b, h) do { _Pragma("unroll") for (int m = 0; m < 4; ++m) _Pragma("unroll") for (int k = 0; k < 2; ++k) dst[m][k] = *(const LAS bf16x8*)(lds + PG8_SA(b, h) + aoff + m * 2048 + k * 1024); } while (0)
; #define PG8_MMA(ai, bj, At, Bt) do { __builtin_amdgcn_s_setprio(1); _Pragma("unroll") for (int m = 0; m < 4; ++m) _Pragma("unroll") for (int n = 0; n < 2; ++n) _Pragma("unroll") for (int k = 0; k < 2; ++k) \
;         acc[ai][bj][m][n] = __builtin_amdgcn_mfma_f32_16x16x32_bf16(Bt[n][k], At[m][k], acc[ai][bj][m][n], 0, 0, 0); __builtin_amdgcn_s_setprio(0); } while (0)
; #define PG8_WAIT_V(n) asm volatile("s_waitcnt vmcnt(" #n ")" ::: "memory")
; #define PG8_WAIT_L(n) asm volatile("s_waitcnt lgkmcnt(" #n ")" ::: "memory")
; #define PG8_BAR __builtin_amdgcn_s_barrier()
; #define PG8_SCHED __builtin_amdgcn_sched_barrier(0)
; template <class Epi>
; __device__ __forceinline__ void gemm_phase(LAS unsigned char* lds, const Gemm g, const StaticOrder& S, const Epi& E) {
;     ...
;             PG8_LDA(At, 1, 1); PG8_STAGE(PG8_SB(1, 0), b3, voffB); PG8_STAGE(PG8_SB(1, 1), b3 + hstepB, voffB); PG8_STAGE(PG8_SA(1, 0), a3, voffA);
;             PG8_WAIT_V(8); PG8_WAIT_L(0); PG8_BAR; PG8_MMA(1, 0, At, B0); PG8_MMA(1, 1, At, B1); PG8_BAR; PG8_SCHED;
;         }
	s_add_i32 s30, s65, s33
	v_lshl_add_u64 v[220:221], v[220:221], 0, s[8:9]
	s_mov_b32 m0, s30
	ds_read_b128 v[184:187], v150 offset:49152
	ds_read_b128 v[188:191], v150 offset:50176
	ds_read_b128 v[192:195], v150 offset:51200
	ds_read_b128 v[196:199], v150 offset:52224
	ds_read_b128 v[200:203], v150 offset:53248
	ds_read_b128 v[208:211], v150 offset:54272
	ds_read_b128 v[212:215], v150 offset:55296
	ds_read_b128 v[216:219], v150 offset:56320
	global_load_lds_dwordx4 v[220:221], off
	s_add_i32 m0, s30, 0x2000
	s_add_u32 s26, s26, 0x80080
	v_lshl_add_u64 v[220:221], v[222:223], 0, s[8:9]
	s_addc_u32 s27, s27, 0
	s_add_i32 s30, s66, s33
	global_load_lds_dwordx4 v[220:221], off
	v_lshl_add_u64 v[220:221], s[26:27], 0, v[132:133]
	s_mov_b32 m0, s30
	s_nop 0
	global_load_lds_dwordx4 v[220:221], off
	v_lshl_add_u64 v[220:221], s[26:27], 0, v[128:129]
	s_add_i32 m0, s30, 0x2000
	s_nop 0
	global_load_lds_dwordx4 v[220:221], off
	v_lshl_add_u64 v[220:221], v[224:225], 0, s[8:9]
	s_mov_b32 m0, s52
	s_nop 0
	global_load_lds_dwordx4 v[220:221], off
	v_lshl_add_u64 v[220:221], v[226:227], 0, s[8:9]
	s_mov_b32 m0, s53
	s_nop 0
	global_load_lds_dwordx4 v[220:221], off
	s_waitcnt vmcnt(8)
	s_waitcnt lgkmcnt(0)
	s_barrier
	s_setprio 1
	s_waitcnt lgkmcnt(0)
	v_mfma_f32_16x16x32_bf16 v[60:63], v[152:155], v[184:187], v[60:63]
	v_mfma_f32_16x16x32_bf16 v[60:63], v[156:159], v[188:191], v[60:63]
	v_mfma_f32_16x16x32_bf16 v[52:55], v[164:167], v[188:191], v[52:55]
	v_mfma_f32_16x16x32_bf16 v[52:55], v[160:163], v[184:187], v[52:55]
	v_mfma_f32_16x16x32_bf16 v[56:59], v[168:171], v[184:187], v[56:59]
	v_mfma_f32_16x16x32_bf16 v[56:59], v[172:175], v[188:191], v[56:59]
	v_mfma_f32_16x16x32_bf16 v[48:51], v[180:183], v[188:191], v[48:51]
	v_mfma_f32_16x16x32_bf16 v[48:51], v[176:179], v[184:187], v[48:51]
	v_mfma_f32_16x16x32_bf16 v[32:35], v[176:179], v[192:195], v[32:35]
	v_mfma_f32_16x16x32_bf16 v[32:35], v[180:183], v[196:199], v[32:35]
	v_mfma_f32_16x16x32_bf16 v[40:43], v[172:175], v[196:199], v[40:43]
	v_mfma_f32_16x16x32_bf16 v[40:43], v[168:171], v[192:195], v[40:43]
	v_mfma_f32_16x16x32_bf16 v[36:39], v[160:163], v[192:195], v[36:39]
	v_mfma_f32_16x16x32_bf16 v[36:39], v[164:167], v[196:199], v[36:39]
	v_mfma_f32_16x16x32_bf16 v[44:47], v[156:159], v[196:199], v[44:47]
	v_mfma_f32_16x16x32_bf16 v[44:47], v[152:155], v[192:195], v[44:47]
	v_mfma_f32_16x16x32_bf16 v[28:31], v[152:155], v[200:203], v[28:31]
	v_mfma_f32_16x16x32_bf16 v[28:31], v[156:159], v[208:211], v[28:31]
	v_mfma_f32_16x16x32_bf16 v[20:23], v[164:167], v[208:211], v[20:23]
	v_mfma_f32_16x16x32_bf16 v[20:23], v[160:163], v[200:203], v[20:23]
	v_mfma_f32_16x16x32_bf16 v[24:27], v[168:171], v[200:203], v[24:27]
	v_mfma_f32_16x16x32_bf16 v[24:27], v[172:175], v[208:211], v[24:27]
	v_mfma_f32_16x16x32_bf16 v[16:19], v[180:183], v[208:211], v[16:19]
	v_mfma_f32_16x16x32_bf16 v[16:19], v[176:179], v[200:203], v[16:19]
	v_mfma_f32_16x16x32_bf16 v[0:3], v[176:179], v[212:215], v[0:3]
	v_mfma_f32_16x16x32_bf16 v[0:3], v[180:183], v[216:219], v[0:3]
	v_mfma_f32_16x16x32_bf16 v[8:11], v[172:175], v[216:219], v[8:11]
	v_mfma_f32_16x16x32_bf16 v[8:11], v[168:171], v[212:215], v[8:11]
	v_mfma_f32_16x16x32_bf16 v[4:7], v[160:163], v[212:215], v[4:7]
	v_mfma_f32_16x16x32_bf16 v[4:7], v[164:167], v[216:219], v[4:7]
	v_mfma_f32_16x16x32_bf16 v[12:15], v[156:159], v[216:219], v[12:15]
	v_mfma_f32_16x16x32_bf16 v[12:15], v[152:155], v[212:215], v[12:15]
	s_setprio 0
	s_barrier
	s_add_u32 s24, s24, 0x100
	s_addc_u32 s25, s25, 0
	s_add_u32 s62, s62, 0x100
	s_addc_u32 s63, s63, 0
	s_cmp_ge_i32 s64, s49
	s_mov_b32 s26, s64
	s_cbranch_scc0 .LBB0_245

; #define PG8_STAGE(bufoff, gbase, voff) do { _Pragma("unroll") for (int _i = 0; _i < 2; ++_i) \
;         __builtin_amdgcn_global_load_lds((const unsigned*)((const char*)(gbase) + (voff)[_i]), (LAS unsigned*)(lds + (bufoff) + ldsw + _i * 8192), 16, 0, 0); } while (0)
; #define PG8_LDA(dst, b, h) do { _Pragma("unroll") for (int m = 0; m < 4; ++m) _Pragma("unroll") for (int k = 0; k < 2; ++k) dst[m][k] = *(const LAS bf16x8*)(lds + PG8_SA(b, h) + aoff + m * 2048 + k * 1024); } while (0)
; #define PG8_LDB(dst, b, h) do { _Pragma("unroll") for (int n = 0; n < 2; ++n) _Pragma("unroll") for (int k = 0; k < 2; ++k) dst[n][k] = *(const LAS bf16x8*)(lds + PG8_SB(b, h) + boff + n * 2048 + k * 1024); } while (0)
; #define PG8_MMA(ai, bj, At, Bt) do { __builtin_amdgcn_s_setprio(1); _Pragma("unroll") for (int m = 0; m < 4; ++m) _Pragma("unroll") for (int n = 0; n < 2; ++n) _Pragma("unroll") for (int k = 0; k < 2; ++k) \
;         acc[ai][bj][m][n] = __builtin_amdgcn_mfma_f32_16x16x32_bf16(Bt[n][k], At[m][k], acc[ai][bj][m][n], 0, 0, 0); __builtin_amdgcn_s_setprio(0); } while (0)
; #define PG8_WAIT_V(n) asm volatile("s_waitcnt vmcnt(" #n ")" ::: "memory")
; #define PG8_WAIT_L(n) asm volatile("s_waitcnt lgkmcnt(" #n ")" ::: "memory")
; #define PG8_BAR __builtin_amdgcn_s_barrier()
; #define PG8_SCHED __builtin_amdgcn_sched_barrier(0)
; template <class Epi>
; __device__ __forceinline__ void gemm_phase(LAS unsigned char* lds, const Gemm g, const StaticOrder& S, const Epi& E) {
;     ...
;             const bool last = (t == nt - 2);
;             const char* a1 = cA + (size_t)(t + 1) * kstep;
;             const char* a2 = last ? nA : cA + (size_t)(t + 2) * kstep; const char* b2 = last ? nB : cB + (size_t)(t + 2) * kstep;
;             const char* a3 = a2 + kstep; const char* b3 = b2 + kstep;
;             PG8_LDB(B0, 0, 0); PG8_LDB(B1, 0, 1); PG8_SCHED; PG8_LDA(At, 0, 0); PG8_STAGE(PG8_SA(1, 1), a1 + hstepA, voffA);
;             PG8_WAIT_V(8); PG8_WAIT_L(0); PG8_BAR; PG8_MMA(0, 0, At, B0); PG8_MMA(0, 1, At, B1); PG8_BAR; PG8_SCHED;
;             PG8_LDA(At, 0, 1); PG8_STAGE(PG8_SB(0, 0), b2, voffB); PG8_STAGE(PG8_SB(0, 1), b2 + hstepB, voffB); PG8_STAGE(PG8_SA(0, 0), a2, voffA);
;             PG8_WAIT_V(8); PG8_WAIT_L(0); PG8_BAR; PG8_MMA(1, 0, At, B0); PG8_MMA(1, 1, At, B1); PG8_BAR; PG8_SCHED;
.LBB0_445:
	ds_read_b128 v[148:151], v218
	ds_read_b128 v[152:155], v218 offset:1024
	ds_read_b128 v[156:159], v218 offset:2048
	ds_read_b128 v[160:163], v218 offset:3072
	ds_read_b128 v[164:167], v219
	ds_read_b128 v[168:171], v219 offset:1024
	ds_read_b128 v[172:175], v219 offset:2048
	ds_read_b128 v[176:179], v219 offset:3072
	s_add_i32 s65, s34, 2
	s_add_u32 s30, s4, 0x100
	s_addc_u32 s31, s5, 0
	s_cmp_eq_u32 s49, s34
	s_cselect_b32 s34, s26, s1
	s_cselect_b32 s37, s11, s31
	s_cselect_b32 s36, s10, s30
	s_cselect_b32 s35, s27, s64
	v_lshl_add_u64 v[216:217], s[4:5], 0, v[140:141]
	s_add_i32 m0, s41, 0xc000
	ds_read_b128 v[180:183], v220
	ds_read_b128 v[184:187], v220 offset:1024
	ds_read_b128 v[188:191], v220 offset:2048
	ds_read_b128 v[192:195], v220 offset:3072
	ds_read_b128 v[196:199], v220 offset:4096
	ds_read_b128 v[200:203], v220 offset:5120
	ds_read_b128 v[208:211], v220 offset:6144
	ds_read_b128 v[212:215], v220 offset:7168
	global_load_lds_dwordx4 v[216:217], off
	v_lshl_add_u64 v[216:217], s[4:5], 0, v[142:143]
	s_add_i32 m0, s41, 0xe000
	s_nop 0
	global_load_lds_dwordx4 v[216:217], off
	s_waitcnt vmcnt(8)
	s_waitcnt lgkmcnt(0)
	s_barrier
	s_setprio 1
	s_waitcnt lgkmcnt(0)
	v_mfma_f32_16x16x32_bf16 v[124:127], v[148:151], v[180:183], v[124:127]
	v_mfma_f32_16x16x32_bf16 v[124:127], v[152:155], v[184:187], v[124:127]
	v_mfma_f32_16x16x32_bf16 v[120:123], v[160:163], v[184:187], v[120:123]
	v_mfma_f32_16x16x32_bf16 v[120:123], v[156:159], v[180:183], v[120:123]
	v_mfma_f32_16x16x32_bf16 v[108:111], v[164:167], v[180:183], v[108:111]
	v_mfma_f32_16x16x32_bf16 v[108:111], v[168:171], v[184:187], v[108:111]
	v_mfma_f32_16x16x32_bf16 v[100:103], v[176:179], v[184:187], v[100:103]
	v_mfma_f32_16x16x32_bf16 v[100:103], v[172:175], v[180:183], v[100:103]
	v_mfma_f32_16x16x32_bf16 v[84:87], v[172:175], v[188:191], v[84:87]
	v_mfma_f32_16x16x32_bf16 v[84:87], v[176:179], v[192:195], v[84:87]
	v_mfma_f32_16x16x32_bf16 v[92:95], v[168:171], v[192:195], v[92:95]
	v_mfma_f32_16x16x32_bf16 v[92:95], v[164:167], v[188:191], v[92:95]
	v_mfma_f32_16x16x32_bf16 v[112:115], v[156:159], v[188:191], v[112:115]
	v_mfma_f32_16x16x32_bf16 v[112:115], v[160:163], v[192:195], v[112:115]
	v_mfma_f32_16x16x32_bf16 v[116:119], v[152:155], v[192:195], v[116:119]
	v_mfma_f32_16x16x32_bf16 v[116:119], v[148:151], v[188:191], v[116:119]
	v_mfma_f32_16x16x32_bf16 v[104:107], v[148:151], v[196:199], v[104:107]
	v_mfma_f32_16x16x32_bf16 v[104:107], v[152:155], v[200:203], v[104:107]
	v_mfma_f32_16x16x32_bf16 v[96:99], v[160:163], v[200:203], v[96:99]
	v_mfma_f32_16x16x32_bf16 v[96:99], v[156:159], v[196:199], v[96:99]
	v_mfma_f32_16x16x32_bf16 v[76:79], v[164:167], v[196:199], v[76:79]
	v_mfma_f32_16x16x32_bf16 v[76:79], v[168:171], v[200:203], v[76:79]
	v_mfma_f32_16x16x32_bf16 v[72:75], v[176:179], v[200:203], v[72:75]
	v_mfma_f32_16x16x32_bf16 v[72:75], v[172:175], v[196:199], v[72:75]
	v_mfma_f32_16x16x32_bf16 v[64:67], v[172:175], v[208:211], v[64:67]
	v_mfma_f32_16x16x32_bf16 v[64:67], v[176:179], v[212:215], v[64:67]
	v_mfma_f32_16x16x32_bf16 v[68:71], v[168:171], v[212:215], v[68:71]
	v_mfma_f32_16x16x32_bf16 v[68:71], v[164:167], v[208:211], v[68:71]
	v_mfma_f32_16x16x32_bf16 v[80:83], v[156:159], v[208:211], v[80:83]
	v_mfma_f32_16x16x32_bf16 v[80:83], v[160:163], v[212:215], v[80:83]
	v_mfma_f32_16x16x32_bf16 v[88:91], v[152:155], v[212:215], v[88:91]
	v_mfma_f32_16x16x32_bf16 v[88:91], v[148:151], v[208:211], v[88:91]
	s_setprio 0
	s_barrier
	s_add_i32 s4, s54, s40
	v_lshl_add_u64 v[216:217], s[34:35], 0, v[130:131]
	s_mov_b32 m0, s4
	ds_read_b128 v[180:183], v220 offset:16384
	ds_read_b128 v[184:187], v220 offset:17408
	ds_read_b128 v[188:191], v220 offset:18432
	ds_read_b128 v[192:195], v220 offset:19456
	ds_read_b128 v[196:199], v220 offset:20480
	ds_read_b128 v[200:203], v220 offset:21504
	ds_read_b128 v[208:211], v220 offset:22528
	ds_read_b128 v[212:215], v220 offset:23552
	global_load_lds_dwordx4 v[216:217], off
	s_add_i32 m0, s4, 0x2000
	s_add_u32 s4, s34, 0x158000
	v_lshl_add_u64 v[222:223], s[34:35], 0, v[134:135]
	s_addc_u32 s5, s35, 0
	s_add_i32 s66, s55, s40
	global_load_lds_dwordx4 v[222:223], off
	v_lshl_add_u64 v[224:225], s[4:5], 0, v[130:131]
	s_mov_b32 m0, s66
	v_lshl_add_u64 v[226:227], s[36:37], 0, v[132:133]
	global_load_lds_dwordx4 v[224:225], off
	v_lshl_add_u64 v[224:225], s[4:5], 0, v[134:135]
	s_add_i32 m0, s66, 0x2000
	s_nop 0
	global_load_lds_dwordx4 v[224:225], off
	v_lshl_add_u64 v[224:225], s[36:37], 0, v[128:129]
	s_mov_b32 m0, s41
	s_nop 0
	global_load_lds_dwordx4 v[224:225], off
	s_mov_b32 m0, s42
	s_nop 0
	global_load_lds_dwordx4 v[226:227], off
	s_waitcnt vmcnt(8)
	s_waitcnt lgkmcnt(0)
	s_barrier
; #define PG8_STAGE(bufoff, gbase, voff) do { _Pragma("unroll") for (int _i = 0; _i < 2; ++_i) \
;         __builtin_amdgcn_global_load_lds((const unsigned*)((const char*)(gbase) + (voff)[_i]), (LAS unsigned*)(lds + (bufoff) + ldsw + _i * 8192), 16, 0, 0); } while (0)
; #define PG8_LDA(dst, b, h) do { _Pragma("unroll") for (int m = 0; m < 4; ++m) _Pragma("unroll") for (int k = 0; k < 2; ++k) dst[m][k] = *(const LAS bf16x8*)(lds + PG8_SA(b, h) + aoff + m * 2048 + k * 1024); } while (0)
; #define PG8_LDB(dst, b, h) do { _Pragma("unroll") for (int n = 0; n < 2; ++n) _Pragma("unroll") for (int k = 0; k < 2; ++k) dst[n][k] = *(const LAS bf16x8*)(lds + PG8_SB(b, h) + boff + n * 2048 + k * 1024); } while (0)
; #define PG8_MMA(ai, bj, At, Bt) do { __builtin_amdgcn_s_setprio(1); _Pragma("unroll") for (int m = 0; m < 4; ++m) _Pragma("unroll") for (int n = 0; n < 2; ++n) _Pragma("unroll") for (int k = 0; k < 2; ++k) \
;         acc[ai][bj][m][n] = __builtin_amdgcn_mfma_f32_16x16x32_bf16(Bt[n][k], At[m][k], acc[ai][bj][m][n], 0, 0, 0); __builtin_amdgcn_s_setprio(0); } while (0)
; #define PG8_WAIT_V(n) asm volatile("s_waitcnt vmcnt(" #n ")" ::: "memory")
; #define PG8_WAIT_L(n) asm volatile("s_waitcnt lgkmcnt(" #n ")" ::: "memory")
; #define PG8_BAR __builtin_amdgcn_s_barrier()
; #define PG8_SCHED __builtin_amdgcn_sched_barrier(0)
; template <class Epi>
; __device__ __forceinline__ void gemm_phase(LAS unsigned char* lds, const Gemm g, const StaticOrder& S, const Epi& E) {
;     ...
;             PG8_WAIT_V(8); PG8_WAIT_L(0); PG8_BAR; PG8_MMA(1, 0, At, B0); PG8_MMA(1, 1, At, B1); PG8_BAR; PG8_SCHED;
;             PG8_LDB(B0, 1, 0); PG8_LDB(B1, 1, 1); PG8_SCHED; PG8_LDA(At, 1, 0); PG8_STAGE(PG8_SA(0, 1), a2 + hstepA, voffA);
;             PG8_WAIT_V(8); PG8_WAIT_L(0); PG8_BAR; PG8_MMA(0, 0, At, B0); PG8_MMA(0, 1, At, B1); PG8_BAR; PG8_SCHED;
	s_setprio 1
	s_waitcnt lgkmcnt(0)
	v_mfma_f32_16x16x32_bf16 v[60:63], v[148:151], v[180:183], v[60:63]
	v_mfma_f32_16x16x32_bf16 v[60:63], v[152:155], v[184:187], v[60:63]
	v_mfma_f32_16x16x32_bf16 v[56:59], v[160:163], v[184:187], v[56:59]
	v_mfma_f32_16x16x32_bf16 v[56:59], v[156:159], v[180:183], v[56:59]
	v_mfma_f32_16x16x32_bf16 v[44:47], v[164:167], v[180:183], v[44:47]
	v_mfma_f32_16x16x32_bf16 v[44:47], v[168:171], v[184:187], v[44:47]
	v_mfma_f32_16x16x32_bf16 v[36:39], v[176:179], v[184:187], v[36:39]
	v_mfma_f32_16x16x32_bf16 v[36:39], v[172:175], v[180:183], v[36:39]
	v_mfma_f32_16x16x32_bf16 v[20:23], v[172:175], v[188:191], v[20:23]
	v_mfma_f32_16x16x32_bf16 v[20:23], v[176:179], v[192:195], v[20:23]
	v_mfma_f32_16x16x32_bf16 v[28:31], v[168:171], v[192:195], v[28:31]
	v_mfma_f32_16x16x32_bf16 v[28:31], v[164:167], v[188:191], v[28:31]
	v_mfma_f32_16x16x32_bf16 v[48:51], v[156:159], v[188:191], v[48:51]
	v_mfma_f32_16x16x32_bf16 v[48:51], v[160:163], v[192:195], v[48:51]
	v_mfma_f32_16x16x32_bf16 v[52:55], v[152:155], v[192:195], v[52:55]
	v_mfma_f32_16x16x32_bf16 v[52:55], v[148:151], v[188:191], v[52:55]
	v_mfma_f32_16x16x32_bf16 v[40:43], v[148:151], v[196:199], v[40:43]
	v_mfma_f32_16x16x32_bf16 v[40:43], v[152:155], v[200:203], v[40:43]
	v_mfma_f32_16x16x32_bf16 v[32:35], v[160:163], v[200:203], v[32:35]
	v_mfma_f32_16x16x32_bf16 v[32:35], v[156:159], v[196:199], v[32:35]
	v_mfma_f32_16x16x32_bf16 v[12:15], v[164:167], v[196:199], v[12:15]
	v_mfma_f32_16x16x32_bf16 v[12:15], v[168:171], v[200:203], v[12:15]
	v_mfma_f32_16x16x32_bf16 v[8:11], v[176:179], v[200:203], v[8:11]
	v_mfma_f32_16x16x32_bf16 v[8:11], v[172:175], v[196:199], v[8:11]
	v_mfma_f32_16x16x32_bf16 v[0:3], v[172:175], v[208:211], v[0:3]
	v_mfma_f32_16x16x32_bf16 v[0:3], v[176:179], v[212:215], v[0:3]
	v_mfma_f32_16x16x32_bf16 v[4:7], v[168:171], v[212:215], v[4:7]
	v_mfma_f32_16x16x32_bf16 v[4:7], v[164:167], v[208:211], v[4:7]
	v_mfma_f32_16x16x32_bf16 v[16:19], v[156:159], v[208:211], v[16:19]
	v_mfma_f32_16x16x32_bf16 v[16:19], v[160:163], v[212:215], v[16:19]
	v_mfma_f32_16x16x32_bf16 v[24:27], v[152:155], v[212:215], v[24:27]
	v_mfma_f32_16x16x32_bf16 v[24:27], v[148:151], v[208:211], v[24:27]
	s_setprio 0
	s_barrier
	s_add_i32 s66, 0, 0x18000
	s_add_i32 s67, 0, 0x1c000
	v_add_u32_e32 v160, s66, v207
	v_add_u32_e32 v176, s67, v207
	ds_read_b128 v[148:151], v160
	ds_read_b128 v[152:155], v160 offset:1024
	ds_read_b128 v[156:159], v160 offset:2048
	ds_read_b128 v[160:163], v160 offset:3072
	ds_read_b128 v[164:167], v176
	ds_read_b128 v[168:171], v176 offset:1024
	ds_read_b128 v[172:175], v176 offset:2048
	ds_read_b128 v[176:179], v176 offset:3072
	s_add_u32 s4, s36, 0x158000
	s_addc_u32 s5, s37, 0
	s_mov_b32 m0, s43
	v_lshl_add_u64 v[230:231], s[4:5], 0, v[128:129]
	ds_read_b128 v[180:183], v220 offset:32768
	ds_read_b128 v[184:187], v220 offset:33792
	ds_read_b128 v[188:191], v220 offset:34816
	ds_read_b128 v[192:195], v220 offset:35840
	ds_read_b128 v[196:199], v220 offset:36864
	ds_read_b128 v[200:203], v220 offset:37888
	ds_read_b128 v[208:211], v220 offset:38912
	ds_read_b128 v[212:215], v220 offset:39936
	global_load_lds_dwordx4 v[230:231], off
	v_lshl_add_u64 v[230:231], s[4:5], 0, v[132:133]
	s_mov_b32 m0, s44
	s_nop 0
	global_load_lds_dwordx4 v[230:231], off
	s_waitcnt vmcnt(8)
	s_waitcnt lgkmcnt(0)
	s_barrier
	s_setprio 1
	s_waitcnt lgkmcnt(0)
	v_mfma_f32_16x16x32_bf16 v[124:127], v[148:151], v[180:183], v[124:127]
	v_mfma_f32_16x16x32_bf16 v[124:127], v[152:155], v[184:187], v[124:127]
	v_mfma_f32_16x16x32_bf16 v[120:123], v[160:163], v[184:187], v[120:123]
	v_mfma_f32_16x16x32_bf16 v[120:123], v[156:159], v[180:183], v[120:123]
	v_mfma_f32_16x16x32_bf16 v[108:111], v[164:167], v[180:183], v[108:111]
	v_mfma_f32_16x16x32_bf16 v[108:111], v[168:171], v[184:187], v[108:111]
	v_mfma_f32_16x16x32_bf16 v[100:103], v[176:179], v[184:187], v[100:103]
	v_mfma_f32_16x16x32_bf16 v[100:103], v[172:175], v[180:183], v[100:103]
	v_mfma_f32_16x16x32_bf16 v[84:87], v[172:175], v[188:191], v[84:87]
	v_mfma_f32_16x16x32_bf16 v[84:87], v[176:179], v[192:195], v[84:87]
	v_mfma_f32_16x16x32_bf16 v[92:95], v[168:171], v[192:195], v[92:95]
	v_mfma_f32_16x16x32_bf16 v[92:95], v[164:167], v[188:191], v[92:95]
	v_mfma_f32_16x16x32_bf16 v[112:115], v[156:159], v[188:191], v[112:115]
	v_mfma_f32_16x16x32_bf16 v[112:115], v[160:163], v[192:195], v[112:115]
	v_mfma_f32_16x16x32_bf16 v[116:119], v[152:155], v[192:195], v[116:119]
	v_mfma_f32_16x16x32_bf16 v[116:119], v[148:151], v[188:191], v[116:119]
	v_mfma_f32_16x16x32_bf16 v[104:107], v[148:151], v[196:199], v[104:107]
	v_mfma_f32_16x16x32_bf16 v[104:107], v[152:155], v[200:203], v[104:107]
	v_mfma_f32_16x16x32_bf16 v[96:99], v[160:163], v[200:203], v[96:99]
	v_mfma_f32_16x16x32_bf16 v[96:99], v[156:159], v[196:199], v[96:99]
	v_mfma_f32_16x16x32_bf16 v[76:79], v[164:167], v[196:199], v[76:79]
	v_mfma_f32_16x16x32_bf16 v[76:79], v[168:171], v[200:203], v[76:79]
	v_mfma_f32_16x16x32_bf16 v[72:75], v[176:179], v[200:203], v[72:75]
	v_mfma_f32_16x16x32_bf16 v[72:75], v[172:175], v[196:199], v[72:75]
	v_mfma_f32_16x16x32_bf16 v[64:67], v[172:175], v[208:211], v[64:67]
	v_mfma_f32_16x16x32_bf16 v[64:67], v[176:179], v[212:215], v[64:67]
	v_mfma_f32_16x16x32_bf16 v[68:71], v[168:171], v[212:215], v[68:71]
	v_mfma_f32_16x16x32_bf16 v[68:71], v[164:167], v[208:211], v[68:71]
	v_mfma_f32_16x16x32_bf16 v[80:83], v[156:159], v[208:211], v[80:83]
	v_mfma_f32_16x16x32_bf16 v[80:83], v[160:163], v[212:215], v[80:83]
	v_mfma_f32_16x16x32_bf16 v[88:91], v[152:155], v[212:215], v[88:91]
	v_mfma_f32_16x16x32_bf16 v[88:91], v[148:151], v[208:211], v[88:91]
	s_setprio 0
	s_barrier
; #define PG8_STAGE(bufoff, gbase, voff) do { _Pragma("unroll") for (int _i = 0; _i < 2; ++_i) \
;         __builtin_amdgcn_global_load_lds((const unsigned*)((const char*)(gbase) + (voff)[_i]), (LAS unsigned*)(lds + (bufoff) + ldsw + _i * 8192), 16, 0, 0); } while (0)
; #define PG8_LDA(dst, b, h) do { _Pragma("unroll") for (int m = 0; m < 4; ++m) _Pragma("unroll") for (int k = 0; k < 2; ++k) dst[m][k] = *(const LAS bf16x8*)(lds + PG8_SA(b, h) + aoff + m * 2048 + k * 1024); } while (0)
; #define PG8_MMA(ai, bj, At, Bt) do { __builtin_amdgcn_s_setprio(1); _Pragma("unroll") for (int m = 0; m < 4; ++m) _Pragma("unroll") for (int n = 0; n < 2; ++n) _Pragma("unroll") for (int k = 0; k < 2; ++k) \
;         acc[ai][bj][m][n] = __builtin_amdgcn_mfma_f32_16x16x32_bf16(Bt[n][k], At[m][k], acc[ai][bj][m][n], 0, 0, 0); __builtin_amdgcn_s_setprio(0); } while (0)
; #define PG8_WAIT_V(n) asm volatile("s_waitcnt vmcnt(" #n ")" ::: "memory")
; #define PG8_WAIT_L(n) asm volatile("s_waitcnt lgkmcnt(" #n ")" ::: "memory")
; #define PG8_BAR __builtin_amdgcn_s_barrier()
; #define PG8_SCHED __builtin_amdgcn_sched_barrier(0)
; template <class Epi>
; __device__ __forceinline__ void gemm_phase(LAS unsigned char* lds, const Gemm g, const StaticOrder& S, const Epi& E) {
;     ...
;             PG8_LDA(At, 1, 1); PG8_STAGE(PG8_SB(1, 0), b3, voffB); PG8_STAGE(PG8_SB(1, 1), b3 + hstepB, voffB); PG8_STAGE(PG8_SA(1, 0), a3, voffA);
;             PG8_WAIT_V(8); PG8_WAIT_L(0); PG8_BAR; PG8_MMA(1, 0, At, B0); PG8_MMA(1, 1, At, B1); PG8_BAR; PG8_SCHED;
;         }
	s_add_i32 s4, s66, s40
	v_lshl_add_u64 v[216:217], v[216:217], 0, s[16:17]
	s_mov_b32 m0, s4
	ds_read_b128 v[180:183], v220 offset:49152
	ds_read_b128 v[184:187], v220 offset:50176
	ds_read_b128 v[188:191], v220 offset:51200
	ds_read_b128 v[192:195], v220 offset:52224
	ds_read_b128 v[196:199], v220 offset:53248
	ds_read_b128 v[200:203], v220 offset:54272
	ds_read_b128 v[208:211], v220 offset:55296
	ds_read_b128 v[212:215], v220 offset:56320
	global_load_lds_dwordx4 v[216:217], off
	s_add_i32 m0, s4, 0x2000
	s_add_u32 s4, s34, 0x158080
	v_lshl_add_u64 v[216:217], v[222:223], 0, s[16:17]
	s_addc_u32 s5, s35, 0
	s_add_i32 s34, s67, s40
	global_load_lds_dwordx4 v[216:217], off
	v_lshl_add_u64 v[216:217], s[4:5], 0, v[130:131]
	s_mov_b32 m0, s34
	s_nop 0
	global_load_lds_dwordx4 v[216:217], off
	v_lshl_add_u64 v[216:217], s[4:5], 0, v[134:135]
	s_add_i32 m0, s34, 0x2000
	s_nop 0
	global_load_lds_dwordx4 v[216:217], off
	v_lshl_add_u64 v[216:217], v[224:225], 0, s[16:17]
	s_mov_b32 m0, s47
	s_nop 0
	global_load_lds_dwordx4 v[216:217], off
	v_lshl_add_u64 v[216:217], v[226:227], 0, s[16:17]
	s_mov_b32 m0, s48
	s_nop 0
	global_load_lds_dwordx4 v[216:217], off
	s_waitcnt vmcnt(8)
	s_waitcnt lgkmcnt(0)
	s_barrier
	s_setprio 1
	s_waitcnt lgkmcnt(0)
	v_mfma_f32_16x16x32_bf16 v[60:63], v[148:151], v[180:183], v[60:63]
	v_mfma_f32_16x16x32_bf16 v[60:63], v[152:155], v[184:187], v[60:63]
	v_mfma_f32_16x16x32_bf16 v[56:59], v[160:163], v[184:187], v[56:59]
	v_mfma_f32_16x16x32_bf16 v[56:59], v[156:159], v[180:183], v[56:59]
	v_mfma_f32_16x16x32_bf16 v[44:47], v[164:167], v[180:183], v[44:47]
	v_mfma_f32_16x16x32_bf16 v[44:47], v[168:171], v[184:187], v[44:47]
	v_mfma_f32_16x16x32_bf16 v[36:39], v[176:179], v[184:187], v[36:39]
	v_mfma_f32_16x16x32_bf16 v[36:39], v[172:175], v[180:183], v[36:39]
	v_mfma_f32_16x16x32_bf16 v[20:23], v[172:175], v[188:191], v[20:23]
	v_mfma_f32_16x16x32_bf16 v[20:23], v[176:179], v[192:195], v[20:23]
	v_mfma_f32_16x16x32_bf16 v[28:31], v[168:171], v[192:195], v[28:31]
	v_mfma_f32_16x16x32_bf16 v[28:31], v[164:167], v[188:191], v[28:31]
	v_mfma_f32_16x16x32_bf16 v[48:51], v[156:159], v[188:191], v[48:51]
	v_mfma_f32_16x16x32_bf16 v[48:51], v[160:163], v[192:195], v[48:51]
	v_mfma_f32_16x16x32_bf16 v[52:55], v[152:155], v[192:195], v[52:55]
	v_mfma_f32_16x16x32_bf16 v[52:55], v[148:151], v[188:191], v[52:55]
	v_mfma_f32_16x16x32_bf16 v[40:43], v[148:151], v[196:199], v[40:43]
	v_mfma_f32_16x16x32_bf16 v[40:43], v[152:155], v[200:203], v[40:43]
	v_mfma_f32_16x16x32_bf16 v[32:35], v[160:163], v[200:203], v[32:35]
	v_mfma_f32_16x16x32_bf16 v[32:35], v[156:159], v[196:199], v[32:35]
	v_mfma_f32_16x16x32_bf16 v[12:15], v[164:167], v[196:199], v[12:15]
	v_mfma_f32_16x16x32_bf16 v[12:15], v[168:171], v[200:203], v[12:15]
	v_mfma_f32_16x16x32_bf16 v[8:11], v[176:179], v[200:203], v[8:11]
	v_mfma_f32_16x16x32_bf16 v[8:11], v[172:175], v[196:199], v[8:11]
	v_mfma_f32_16x16x32_bf16 v[0:3], v[172:175], v[208:211], v[0:3]
	v_mfma_f32_16x16x32_bf16 v[0:3], v[176:179], v[212:215], v[0:3]
	v_mfma_f32_16x16x32_bf16 v[4:7], v[168:171], v[212:215], v[4:7]
	v_mfma_f32_16x16x32_bf16 v[4:7], v[164:167], v[208:211], v[4:7]
	v_mfma_f32_16x16x32_bf16 v[16:19], v[156:159], v[208:211], v[16:19]
	v_mfma_f32_16x16x32_bf16 v[16:19], v[160:163], v[212:215], v[16:19]
	v_mfma_f32_16x16x32_bf16 v[24:27], v[152:155], v[212:215], v[24:27]
	v_mfma_f32_16x16x32_bf16 v[24:27], v[148:151], v[208:211], v[24:27]
	s_setprio 0
	s_barrier
	s_add_u32 s1, s1, 0x100
	s_addc_u32 s64, s64, 0
	s_cmp_ge_i32 s65, s46
	s_mov_b64 s[4:5], s[30:31]
	s_mov_b32 s34, s65
	s_cbranch_scc0 .LBB0_445
	v_pk_mul_f32 v[164:165], v[126:127], 0.5 op_sel_hi:[1,0]
	v_pk_mul_f32 v[200:201], v[124:125], 0.5 op_sel_hi:[1,0]
	v_pk_mul_f32 v[202:203], v[122:123], 0.5 op_sel_hi:[1,0]
	v_pk_mul_f32 v[208:209], v[120:121], 0.5 op_sel_hi:[1,0]
	v_pk_mul_f32 v[210:211], v[110:111], 0.5 op_sel_hi:[1,0]
	v_pk_mul_f32 v[212:213], v[108:109], 0.5 op_sel_hi:[1,0]
	v_pk_mul_f32 v[214:215], v[102:103], 0.5 op_sel_hi:[1,0]
	v_pk_mul_f32 v[216:217], v[100:101], 0.5 op_sel_hi:[1,0]
	v_pk_mul_f32 v[188:189], v[118:119], 0.5 op_sel_hi:[1,0]
	v_pk_mul_f32 v[186:187], v[116:117], 0.5 op_sel_hi:[1,0]
	v_pk_mul_f32 v[184:185], v[114:115], 0.5 op_sel_hi:[1,0]
	v_pk_mul_f32 v[182:183], v[112:113], 0.5 op_sel_hi:[1,0]
	v_pk_mul_f32 v[196:197], v[94:95], 0.5 op_sel_hi:[1,0]
	v_pk_mul_f32 v[194:195], v[92:93], 0.5 op_sel_hi:[1,0]
	v_pk_mul_f32 v[192:193], v[86:87], 0.5 op_sel_hi:[1,0]
	v_pk_mul_f32 v[190:191], v[84:85], 0.5 op_sel_hi:[1,0]
	v_pk_mul_f32 v[166:167], v[106:107], 0.5 op_sel_hi:[1,0]
	v_pk_mul_f32 v[168:169], v[104:105], 0.5 op_sel_hi:[1,0]
	v_pk_mul_f32 v[170:171], v[98:99], 0.5 op_sel_hi:[1,0]
	v_pk_mul_f32 v[172:173], v[96:97], 0.5 op_sel_hi:[1,0]
	v_pk_mul_f32 v[174:175], v[78:79], 0.5 op_sel_hi:[1,0]
	v_pk_mul_f32 v[176:177], v[76:77], 0.5 op_sel_hi:[1,0]
	v_pk_mul_f32 v[178:179], v[74:75], 0.5 op_sel_hi:[1,0]
	v_pk_mul_f32 v[180:181], v[72:73], 0.5 op_sel_hi:[1,0]
	v_pk_mul_f32 v[154:155], v[90:91], 0.5 op_sel_hi:[1,0]
	v_pk_mul_f32 v[152:153], v[88:89], 0.5 op_sel_hi:[1,0]
	v_pk_mul_f32 v[150:151], v[82:83], 0.5 op_sel_hi:[1,0]
	v_pk_mul_f32 v[148:149], v[80:81], 0.5 op_sel_hi:[1,0]
	v_pk_mul_f32 v[162:163], v[70:71], 0.5 op_sel_hi:[1,0]
	v_pk_mul_f32 v[160:161], v[68:69], 0.5 op_sel_hi:[1,0]
	v_pk_mul_f32 v[158:159], v[66:67], 0.5 op_sel_hi:[1,0]
	v_pk_mul_f32 v[156:157], v[64:65], 0.5 op_sel_hi:[1,0]
	v_pk_mul_f32 v[112:113], v[62:63], 0.5 op_sel_hi:[1,0]
	v_pk_mul_f32 v[114:115], v[60:61], 0.5 op_sel_hi:[1,0]
	v_pk_mul_f32 v[116:117], v[58:59], 0.5 op_sel_hi:[1,0]
	v_pk_mul_f32 v[118:119], v[56:57], 0.5 op_sel_hi:[1,0]
	v_pk_mul_f32 v[120:121], v[46:47], 0.5 op_sel_hi:[1,0]
	v_pk_mul_f32 v[122:123], v[44:45], 0.5 op_sel_hi:[1,0]
	v_pk_mul_f32 v[124:125], v[38:39], 0.5 op_sel_hi:[1,0]
	v_pk_mul_f32 v[126:127], v[36:37], 0.5 op_sel_hi:[1,0]
	v_pk_mul_f32 v[102:103], v[54:55], 0.5 op_sel_hi:[1,0]
	v_pk_mul_f32 v[100:101], v[52:53], 0.5 op_sel_hi:[1,0]
	v_pk_mul_f32 v[98:99], v[50:51], 0.5 op_sel_hi:[1,0]
	v_pk_mul_f32 v[96:97], v[48:49], 0.5 op_sel_hi:[1,0]
	v_pk_mul_f32 v[110:111], v[30:31], 0.5 op_sel_hi:[1,0]
	v_pk_mul_f32 v[108:109], v[28:29], 0.5 op_sel_hi:[1,0]
	v_pk_mul_f32 v[106:107], v[22:23], 0.5 op_sel_hi:[1,0]
	v_pk_mul_f32 v[104:105], v[20:21], 0.5 op_sel_hi:[1,0]
	v_pk_mul_f32 v[86:87], v[42:43], 0.5 op_sel_hi:[1,0]
	v_pk_mul_f32 v[84:85], v[40:41], 0.5 op_sel_hi:[1,0]
	v_pk_mul_f32 v[82:83], v[34:35], 0.5 op_sel_hi:[1,0]
	v_pk_mul_f32 v[80:81], v[32:33], 0.5 op_sel_hi:[1,0]
	v_pk_mul_f32 v[94:95], v[14:15], 0.5 op_sel_hi:[1,0]
	v_pk_mul_f32 v[92:93], v[12:13], 0.5 op_sel_hi:[1,0]
	v_pk_mul_f32 v[90:91], v[10:11], 0.5 op_sel_hi:[1,0]
	v_pk_mul_f32 v[88:89], v[8:9], 0.5 op_sel_hi:[1,0]
	v_pk_mul_f32 v[70:71], v[26:27], 0.5 op_sel_hi:[1,0]
	v_pk_mul_f32 v[68:69], v[24:25], 0.5 op_sel_hi:[1,0]
	v_pk_mul_f32 v[66:67], v[18:19], 0.5 op_sel_hi:[1,0]
	v_pk_mul_f32 v[64:65], v[16:17], 0.5 op_sel_hi:[1,0]
	v_pk_mul_f32 v[78:79], v[6:7], 0.5 op_sel_hi:[1,0]
	v_pk_mul_f32 v[76:77], v[4:5], 0.5 op_sel_hi:[1,0]
	v_pk_mul_f32 v[74:75], v[2:3], 0.5 op_sel_hi:[1,0]
	v_pk_mul_f32 v[72:73], v[0:1], 0.5 op_sel_hi:[1,0]

; #define PG8_STAGE(bufoff, gbase, voff) do { _Pragma("unroll") for (int _i = 0; _i < 2; ++_i) \
;         __builtin_amdgcn_global_load_lds((const unsigned*)((const char*)(gbase) + (voff)[_i]), (LAS unsigned*)(lds + (bufoff) + ldsw + _i * 8192), 16, 0, 0); } while (0)
; #define PG8_LDA(dst, b, h) do { _Pragma("unroll") for (int m = 0; m < 4; ++m) _Pragma("unroll") for (int k = 0; k < 2; ++k) dst[m][k] = *(const LAS bf16x8*)(lds + PG8_SA(b, h) + aoff + m * 2048 + k * 1024); } while (0)
; #define PG8_LDB(dst, b, h) do { _Pragma("unroll") for (int n = 0; n < 2; ++n) _Pragma("unroll") for (int k = 0; k < 2; ++k) dst[n][k] = *(const LAS bf16x8*)(lds + PG8_SB(b, h) + boff + n * 2048 + k * 1024); } while (0)
; #define PG8_MMA(ai, bj, At, Bt) do { __builtin_amdgcn_s_setprio(1); _Pragma("unroll") for (int m = 0; m < 4; ++m) _Pragma("unroll") for (int n = 0; n < 2; ++n) _Pragma("unroll") for (int k = 0; k < 2; ++k) \
;         acc[ai][bj][m][n] = __builtin_amdgcn_mfma_f32_16x16x32_bf16(Bt[n][k], At[m][k], acc[ai][bj][m][n], 0, 0, 0); __builtin_amdgcn_s_setprio(0); } while (0)
; #define PG8_WAIT_V(n) asm volatile("s_waitcnt vmcnt(" #n ")" ::: "memory")
; #define PG8_WAIT_L(n) asm volatile("s_waitcnt lgkmcnt(" #n ")" ::: "memory")
; #define PG8_BAR __builtin_amdgcn_s_barrier()
; #define PG8_SCHED __builtin_amdgcn_sched_barrier(0)
; template <class Epi>
; __device__ __forceinline__ void gemm_phase(LAS unsigned char* lds, const Gemm g, const StaticOrder& S, const Epi& E) {
;     ...
;             const bool last = (t == nt - 2);
;             const char* a1 = cA + (size_t)(t + 1) * kstep;
;             const char* a2 = last ? nA : cA + (size_t)(t + 2) * kstep; const char* b2 = last ? nB : cB + (size_t)(t + 2) * kstep;
;             const char* a3 = a2 + kstep; const char* b3 = b2 + kstep;
;             PG8_LDB(B0, 0, 0); PG8_LDB(B1, 0, 1); PG8_SCHED; PG8_LDA(At, 0, 0); PG8_STAGE(PG8_SA(1, 1), a1 + hstepA, voffA);
;             PG8_WAIT_V(8); PG8_WAIT_L(0); PG8_BAR; PG8_MMA(0, 0, At, B0); PG8_MMA(0, 1, At, B1); PG8_BAR; PG8_SCHED;
;             PG8_LDA(At, 0, 1); PG8_STAGE(PG8_SB(0, 0), b2, voffB); PG8_STAGE(PG8_SB(0, 1), b2 + hstepB, voffB); PG8_STAGE(PG8_SA(0, 0), a2, voffA);
;             PG8_WAIT_V(8); PG8_WAIT_L(0); PG8_BAR; PG8_MMA(1, 0, At, B0); PG8_MMA(1, 1, At, B1); PG8_BAR; PG8_SCHED;
.LBB0_541:
	ds_read_b128 v[148:151], v155
	ds_read_b128 v[160:163], v155 offset:1024
	ds_read_b128 v[164:167], v155 offset:2048
	ds_read_b128 v[168:171], v155 offset:3072
	ds_read_b128 v[172:175], v156
	ds_read_b128 v[176:179], v156 offset:1024
	ds_read_b128 v[180:183], v156 offset:2048
	ds_read_b128 v[184:187], v156 offset:3072
	s_add_i32 s35, s26, 2
	s_add_u32 s27, s8, 0xfff80080
	s_addc_u32 s30, s9, -1
	s_cmp_eq_u32 s49, s26
	s_cselect_b32 s26, s21, s33
	s_cselect_b32 s31, s1, s30
	s_cselect_b32 s30, s5, s27
	s_cselect_b32 s27, s19, s34
	v_lshl_add_u64 v[224:225], s[8:9], 0, v[140:141]
	s_add_i32 m0, s39, 0xc000
	ds_read_b128 v[188:191], v157
	ds_read_b128 v[192:195], v157 offset:1024
	ds_read_b128 v[196:199], v157 offset:2048
	ds_read_b128 v[200:203], v157 offset:3072
	ds_read_b128 v[208:211], v157 offset:4096
	ds_read_b128 v[212:215], v157 offset:5120
	ds_read_b128 v[216:219], v157 offset:6144
	ds_read_b128 v[220:223], v157 offset:7168
	global_load_lds_dwordx4 v[224:225], off
	v_lshl_add_u64 v[224:225], s[8:9], 0, v[142:143]
	s_add_i32 m0, s39, 0xe000
	s_nop 0
	global_load_lds_dwordx4 v[224:225], off
	s_waitcnt vmcnt(8)
	s_waitcnt lgkmcnt(0)
	s_barrier
	s_setprio 1
	s_waitcnt lgkmcnt(0)
	v_mfma_f32_16x16x32_bf16 v[120:123], v[148:151], v[188:191], v[120:123]
	v_mfma_f32_16x16x32_bf16 v[120:123], v[160:163], v[192:195], v[120:123]
	v_mfma_f32_16x16x32_bf16 v[124:127], v[168:171], v[192:195], v[124:127]
	v_mfma_f32_16x16x32_bf16 v[124:127], v[164:167], v[188:191], v[124:127]
	v_mfma_f32_16x16x32_bf16 v[116:119], v[172:175], v[188:191], v[116:119]
	v_mfma_f32_16x16x32_bf16 v[116:119], v[176:179], v[192:195], v[116:119]
	v_mfma_f32_16x16x32_bf16 v[112:115], v[184:187], v[192:195], v[112:115]
	v_mfma_f32_16x16x32_bf16 v[112:115], v[180:183], v[188:191], v[112:115]
	v_mfma_f32_16x16x32_bf16 v[96:99], v[180:183], v[196:199], v[96:99]
	v_mfma_f32_16x16x32_bf16 v[96:99], v[184:187], v[200:203], v[96:99]
	v_mfma_f32_16x16x32_bf16 v[100:103], v[176:179], v[200:203], v[100:103]
	v_mfma_f32_16x16x32_bf16 v[100:103], v[172:175], v[196:199], v[100:103]
	v_mfma_f32_16x16x32_bf16 v[104:107], v[164:167], v[196:199], v[104:107]
	v_mfma_f32_16x16x32_bf16 v[104:107], v[168:171], v[200:203], v[104:107]
	v_mfma_f32_16x16x32_bf16 v[108:111], v[160:163], v[200:203], v[108:111]
	v_mfma_f32_16x16x32_bf16 v[108:111], v[148:151], v[196:199], v[108:111]
	v_mfma_f32_16x16x32_bf16 v[92:95], v[148:151], v[208:211], v[92:95]
	v_mfma_f32_16x16x32_bf16 v[92:95], v[160:163], v[212:215], v[92:95]
	v_mfma_f32_16x16x32_bf16 v[88:91], v[168:171], v[212:215], v[88:91]
	v_mfma_f32_16x16x32_bf16 v[88:91], v[164:167], v[208:211], v[88:91]
	v_mfma_f32_16x16x32_bf16 v[84:87], v[172:175], v[208:211], v[84:87]
	v_mfma_f32_16x16x32_bf16 v[84:87], v[176:179], v[212:215], v[84:87]
	v_mfma_f32_16x16x32_bf16 v[80:83], v[184:187], v[212:215], v[80:83]
	v_mfma_f32_16x16x32_bf16 v[80:83], v[180:183], v[208:211], v[80:83]
	v_mfma_f32_16x16x32_bf16 v[64:67], v[180:183], v[216:219], v[64:67]
	v_mfma_f32_16x16x32_bf16 v[64:67], v[184:187], v[220:223], v[64:67]
	v_mfma_f32_16x16x32_bf16 v[68:71], v[176:179], v[220:223], v[68:71]
	v_mfma_f32_16x16x32_bf16 v[68:71], v[172:175], v[216:219], v[68:71]
	v_mfma_f32_16x16x32_bf16 v[72:75], v[164:167], v[216:219], v[72:75]
	v_mfma_f32_16x16x32_bf16 v[72:75], v[168:171], v[220:223], v[72:75]
	v_mfma_f32_16x16x32_bf16 v[76:79], v[160:163], v[220:223], v[76:79]
	v_mfma_f32_16x16x32_bf16 v[76:79], v[148:151], v[216:219], v[76:79]
	s_setprio 0
	s_barrier
	s_add_i32 s58, s54, s38
	v_lshl_add_u64 v[224:225], s[26:27], 0, v[130:131]
	s_mov_b32 m0, s58
	ds_read_b128 v[188:191], v157 offset:16384
	ds_read_b128 v[192:195], v157 offset:17408
	ds_read_b128 v[196:199], v157 offset:18432
	ds_read_b128 v[200:203], v157 offset:19456
	ds_read_b128 v[208:211], v157 offset:20480
	ds_read_b128 v[212:215], v157 offset:21504
	ds_read_b128 v[216:219], v157 offset:22528
	ds_read_b128 v[220:223], v157 offset:23552
	global_load_lds_dwordx4 v[224:225], off
	s_add_i32 m0, s58, 0x2000
	s_add_u32 s58, s26, 0x80000
	v_lshl_add_u64 v[226:227], s[26:27], 0, v[134:135]
	s_addc_u32 s59, s27, 0
	s_add_i32 s60, s55, s38
	global_load_lds_dwordx4 v[226:227], off
	v_lshl_add_u64 v[230:231], s[58:59], 0, v[130:131]
	s_mov_b32 m0, s60
	v_lshl_add_u64 v[232:233], s[30:31], 0, v[132:133]
	global_load_lds_dwordx4 v[230:231], off
	v_lshl_add_u64 v[230:231], s[58:59], 0, v[134:135]
	s_add_i32 m0, s60, 0x2000
	s_nop 0
	global_load_lds_dwordx4 v[230:231], off
	v_lshl_add_u64 v[230:231], s[30:31], 0, v[128:129]
	s_mov_b32 m0, s39
	s_nop 0
	global_load_lds_dwordx4 v[230:231], off
	s_mov_b32 m0, s40
	s_nop 0
	global_load_lds_dwordx4 v[232:233], off
	s_waitcnt vmcnt(8)
	s_waitcnt lgkmcnt(0)
	s_barrier
; #define PG8_STAGE(bufoff, gbase, voff) do { _Pragma("unroll") for (int _i = 0; _i < 2; ++_i) \
;         __builtin_amdgcn_global_load_lds((const unsigned*)((const char*)(gbase) + (voff)[_i]), (LAS unsigned*)(lds + (bufoff) + ldsw + _i * 8192), 16, 0, 0); } while (0)
; #define PG8_LDA(dst, b, h) do { _Pragma("unroll") for (int m = 0; m < 4; ++m) _Pragma("unroll") for (int k = 0; k < 2; ++k) dst[m][k] = *(const LAS bf16x8*)(lds + PG8_SA(b, h) + aoff + m * 2048 + k * 1024); } while (0)
; #define PG8_LDB(dst, b, h) do { _Pragma("unroll") for (int n = 0; n < 2; ++n) _Pragma("unroll") for (int k = 0; k < 2; ++k) dst[n][k] = *(const LAS bf16x8*)(lds + PG8_SB(b, h) + boff + n * 2048 + k * 1024); } while (0)
; #define PG8_MMA(ai, bj, At, Bt) do { __builtin_amdgcn_s_setprio(1); _Pragma("unroll") for (int m = 0; m < 4; ++m) _Pragma("unroll") for (int n = 0; n < 2; ++n) _Pragma("unroll") for (int k = 0; k < 2; ++k) \
;         acc[ai][bj][m][n] = __builtin_amdgcn_mfma_f32_16x16x32_bf16(Bt[n][k], At[m][k], acc[ai][bj][m][n], 0, 0, 0); __builtin_amdgcn_s_setprio(0); } while (0)
; #define PG8_WAIT_V(n) asm volatile("s_waitcnt vmcnt(" #n ")" ::: "memory")
; #define PG8_WAIT_L(n) asm volatile("s_waitcnt lgkmcnt(" #n ")" ::: "memory")
; #define PG8_BAR __builtin_amdgcn_s_barrier()
; #define PG8_SCHED __builtin_amdgcn_sched_barrier(0)
; template <class Epi>
; __device__ __forceinline__ void gemm_phase(LAS unsigned char* lds, const Gemm g, const StaticOrder& S, const Epi& E) {
;     ...
;             PG8_WAIT_V(8); PG8_WAIT_L(0); PG8_BAR; PG8_MMA(1, 0, At, B0); PG8_MMA(1, 1, At, B1); PG8_BAR; PG8_SCHED;
;             PG8_LDB(B0, 1, 0); PG8_LDB(B1, 1, 1); PG8_SCHED; PG8_LDA(At, 1, 0); PG8_STAGE(PG8_SA(0, 1), a2 + hstepA, voffA);
;             PG8_WAIT_V(8); PG8_WAIT_L(0); PG8_BAR; PG8_MMA(0, 0, At, B0); PG8_MMA(0, 1, At, B1); PG8_BAR; PG8_SCHED;
	s_setprio 1
	s_waitcnt lgkmcnt(0)
	v_mfma_f32_16x16x32_bf16 v[60:63], v[148:151], v[188:191], v[60:63]
	v_mfma_f32_16x16x32_bf16 v[60:63], v[160:163], v[192:195], v[60:63]
	v_mfma_f32_16x16x32_bf16 v[56:59], v[168:171], v[192:195], v[56:59]
	v_mfma_f32_16x16x32_bf16 v[56:59], v[164:167], v[188:191], v[56:59]
	v_mfma_f32_16x16x32_bf16 v[52:55], v[172:175], v[188:191], v[52:55]
	v_mfma_f32_16x16x32_bf16 v[52:55], v[176:179], v[192:195], v[52:55]
	v_mfma_f32_16x16x32_bf16 v[48:51], v[184:187], v[192:195], v[48:51]
	v_mfma_f32_16x16x32_bf16 v[48:51], v[180:183], v[188:191], v[48:51]
	v_mfma_f32_16x16x32_bf16 v[32:35], v[180:183], v[196:199], v[32:35]
	v_mfma_f32_16x16x32_bf16 v[32:35], v[184:187], v[200:203], v[32:35]
	v_mfma_f32_16x16x32_bf16 v[36:39], v[176:179], v[200:203], v[36:39]
	v_mfma_f32_16x16x32_bf16 v[36:39], v[172:175], v[196:199], v[36:39]
	v_mfma_f32_16x16x32_bf16 v[40:43], v[164:167], v[196:199], v[40:43]
	v_mfma_f32_16x16x32_bf16 v[40:43], v[168:171], v[200:203], v[40:43]
	v_mfma_f32_16x16x32_bf16 v[44:47], v[160:163], v[200:203], v[44:47]
	v_mfma_f32_16x16x32_bf16 v[44:47], v[148:151], v[196:199], v[44:47]
	v_mfma_f32_16x16x32_bf16 v[28:31], v[148:151], v[208:211], v[28:31]
	v_mfma_f32_16x16x32_bf16 v[28:31], v[160:163], v[212:215], v[28:31]
	v_mfma_f32_16x16x32_bf16 v[24:27], v[168:171], v[212:215], v[24:27]
	v_mfma_f32_16x16x32_bf16 v[24:27], v[164:167], v[208:211], v[24:27]
	v_mfma_f32_16x16x32_bf16 v[20:23], v[172:175], v[208:211], v[20:23]
	v_mfma_f32_16x16x32_bf16 v[20:23], v[176:179], v[212:215], v[20:23]
	v_mfma_f32_16x16x32_bf16 v[16:19], v[184:187], v[212:215], v[16:19]
	v_mfma_f32_16x16x32_bf16 v[16:19], v[180:183], v[208:211], v[16:19]
	v_mfma_f32_16x16x32_bf16 v[0:3], v[180:183], v[216:219], v[0:3]
	v_mfma_f32_16x16x32_bf16 v[0:3], v[184:187], v[220:223], v[0:3]
	v_mfma_f32_16x16x32_bf16 v[4:7], v[176:179], v[220:223], v[4:7]
	v_mfma_f32_16x16x32_bf16 v[4:7], v[172:175], v[216:219], v[4:7]
	v_mfma_f32_16x16x32_bf16 v[8:11], v[164:167], v[216:219], v[8:11]
	v_mfma_f32_16x16x32_bf16 v[8:11], v[168:171], v[220:223], v[8:11]
	v_mfma_f32_16x16x32_bf16 v[12:15], v[160:163], v[220:223], v[12:15]
	v_mfma_f32_16x16x32_bf16 v[12:15], v[148:151], v[216:219], v[12:15]
	s_setprio 0
	s_barrier
	s_add_i32 s58, 0, 0x18000
	v_add_u32_e32 v136, s58, v154
	s_add_i32 s59, 0, 0x1c000
	ds_read_b128 v[148:151], v136
	ds_read_b128 v[160:163], v136 offset:1024
	ds_read_b128 v[164:167], v136 offset:2048
	ds_read_b128 v[168:171], v136 offset:3072
	v_add_u32_e32 v136, s59, v154
	ds_read_b128 v[172:175], v136
	ds_read_b128 v[176:179], v136 offset:1024
	ds_read_b128 v[180:183], v136 offset:2048
	ds_read_b128 v[184:187], v136 offset:3072
	s_add_u32 s30, s30, 0x80000
	s_addc_u32 s31, s31, 0
	s_mov_b32 m0, s41
	v_lshl_add_u64 v[234:235], s[30:31], 0, v[128:129]
	ds_read_b128 v[188:191], v157 offset:32768
	ds_read_b128 v[192:195], v157 offset:33792
	ds_read_b128 v[196:199], v157 offset:34816
	ds_read_b128 v[200:203], v157 offset:35840
	ds_read_b128 v[208:211], v157 offset:36864
	ds_read_b128 v[212:215], v157 offset:37888
	ds_read_b128 v[216:219], v157 offset:38912
	ds_read_b128 v[220:223], v157 offset:39936
	global_load_lds_dwordx4 v[234:235], off
	v_lshl_add_u64 v[234:235], s[30:31], 0, v[132:133]
	s_mov_b32 m0, s42
	s_nop 0
	global_load_lds_dwordx4 v[234:235], off
	s_waitcnt vmcnt(8)
	s_waitcnt lgkmcnt(0)
	s_barrier
	s_setprio 1
	s_waitcnt lgkmcnt(0)
	v_mfma_f32_16x16x32_bf16 v[120:123], v[148:151], v[188:191], v[120:123]
	v_mfma_f32_16x16x32_bf16 v[120:123], v[160:163], v[192:195], v[120:123]
	v_mfma_f32_16x16x32_bf16 v[124:127], v[168:171], v[192:195], v[124:127]
	v_mfma_f32_16x16x32_bf16 v[124:127], v[164:167], v[188:191], v[124:127]
	v_mfma_f32_16x16x32_bf16 v[116:119], v[172:175], v[188:191], v[116:119]
	v_mfma_f32_16x16x32_bf16 v[116:119], v[176:179], v[192:195], v[116:119]
	v_mfma_f32_16x16x32_bf16 v[112:115], v[184:187], v[192:195], v[112:115]
	v_mfma_f32_16x16x32_bf16 v[112:115], v[180:183], v[188:191], v[112:115]
	v_mfma_f32_16x16x32_bf16 v[96:99], v[180:183], v[196:199], v[96:99]
	v_mfma_f32_16x16x32_bf16 v[96:99], v[184:187], v[200:203], v[96:99]
	v_mfma_f32_16x16x32_bf16 v[100:103], v[176:179], v[200:203], v[100:103]
	v_mfma_f32_16x16x32_bf16 v[100:103], v[172:175], v[196:199], v[100:103]
	v_mfma_f32_16x16x32_bf16 v[104:107], v[164:167], v[196:199], v[104:107]
	v_mfma_f32_16x16x32_bf16 v[104:107], v[168:171], v[200:203], v[104:107]
	v_mfma_f32_16x16x32_bf16 v[108:111], v[160:163], v[200:203], v[108:111]
	v_mfma_f32_16x16x32_bf16 v[108:111], v[148:151], v[196:199], v[108:111]
	v_mfma_f32_16x16x32_bf16 v[92:95], v[148:151], v[208:211], v[92:95]
	v_mfma_f32_16x16x32_bf16 v[92:95], v[160:163], v[212:215], v[92:95]
	v_mfma_f32_16x16x32_bf16 v[88:91], v[168:171], v[212:215], v[88:91]
	v_mfma_f32_16x16x32_bf16 v[88:91], v[164:167], v[208:211], v[88:91]
	v_mfma_f32_16x16x32_bf16 v[84:87], v[172:175], v[208:211], v[84:87]
	v_mfma_f32_16x16x32_bf16 v[84:87], v[176:179], v[212:215], v[84:87]
	v_mfma_f32_16x16x32_bf16 v[80:83], v[184:187], v[212:215], v[80:83]
	v_mfma_f32_16x16x32_bf16 v[80:83], v[180:183], v[208:211], v[80:83]
	v_mfma_f32_16x16x32_bf16 v[64:67], v[180:183], v[216:219], v[64:67]
	v_mfma_f32_16x16x32_bf16 v[64:67], v[184:187], v[220:223], v[64:67]
	v_mfma_f32_16x16x32_bf16 v[68:71], v[176:179], v[220:223], v[68:71]
	v_mfma_f32_16x16x32_bf16 v[68:71], v[172:175], v[216:219], v[68:71]
	v_mfma_f32_16x16x32_bf16 v[72:75], v[164:167], v[216:219], v[72:75]
	v_mfma_f32_16x16x32_bf16 v[72:75], v[168:171], v[220:223], v[72:75]
	v_mfma_f32_16x16x32_bf16 v[76:79], v[160:163], v[220:223], v[76:79]
	v_mfma_f32_16x16x32_bf16 v[76:79], v[148:151], v[216:219], v[76:79]
	s_setprio 0
	s_barrier
; #define PG8_STAGE(bufoff, gbase, voff) do { _Pragma("unroll") for (int _i = 0; _i < 2; ++_i) \
;         __builtin_amdgcn_global_load_lds((const unsigned*)((const char*)(gbase) + (voff)[_i]), (LAS unsigned*)(lds + (bufoff) + ldsw + _i * 8192), 16, 0, 0); } while (0)
; #define PG8_LDA(dst, b, h) do { _Pragma("unroll") for (int m = 0; m < 4; ++m) _Pragma("unroll") for (int k = 0; k < 2; ++k) dst[m][k] = *(const LAS bf16x8*)(lds + PG8_SA(b, h) + aoff + m * 2048 + k * 1024); } while (0)
; #define PG8_MMA(ai, bj, At, Bt) do { __builtin_amdgcn_s_setprio(1); _Pragma("unroll") for (int m = 0; m < 4; ++m) _Pragma("unroll") for (int n = 0; n < 2; ++n) _Pragma("unroll") for (int k = 0; k < 2; ++k) \
;         acc[ai][bj][m][n] = __builtin_amdgcn_mfma_f32_16x16x32_bf16(Bt[n][k], At[m][k], acc[ai][bj][m][n], 0, 0, 0); __builtin_amdgcn_s_setprio(0); } while (0)
; #define PG8_WAIT_V(n) asm volatile("s_waitcnt vmcnt(" #n ")" ::: "memory")
; #define PG8_WAIT_L(n) asm volatile("s_waitcnt lgkmcnt(" #n ")" ::: "memory")
; #define PG8_BAR __builtin_amdgcn_s_barrier()
; #define PG8_SCHED __builtin_amdgcn_sched_barrier(0)
; template <class Epi>
; __device__ __forceinline__ void gemm_phase(LAS unsigned char* lds, const Gemm g, const StaticOrder& S, const Epi& E) {
;     ...
;             PG8_LDA(At, 1, 1); PG8_STAGE(PG8_SB(1, 0), b3, voffB); PG8_STAGE(PG8_SB(1, 1), b3 + hstepB, voffB); PG8_STAGE(PG8_SA(1, 0), a3, voffA);
;             PG8_WAIT_V(8); PG8_WAIT_L(0); PG8_BAR; PG8_MMA(1, 0, At, B0); PG8_MMA(1, 1, At, B1); PG8_BAR; PG8_SCHED;
;         }
	s_add_i32 s30, s58, s38
	v_lshl_add_u64 v[224:225], v[224:225], 0, s[12:13]
	s_mov_b32 m0, s30
	ds_read_b128 v[188:191], v157 offset:49152
	ds_read_b128 v[192:195], v157 offset:50176
	ds_read_b128 v[196:199], v157 offset:51200
	ds_read_b128 v[200:203], v157 offset:52224
	ds_read_b128 v[208:211], v157 offset:53248
	ds_read_b128 v[212:215], v157 offset:54272
	ds_read_b128 v[216:219], v157 offset:55296
	ds_read_b128 v[220:223], v157 offset:56320
	global_load_lds_dwordx4 v[224:225], off
	s_add_i32 m0, s30, 0x2000
	s_add_u32 s26, s26, 0x80080
	v_lshl_add_u64 v[224:225], v[226:227], 0, s[12:13]
	s_addc_u32 s27, s27, 0
	s_add_i32 s30, s59, s38
	global_load_lds_dwordx4 v[224:225], off
	v_lshl_add_u64 v[224:225], s[26:27], 0, v[130:131]
	s_mov_b32 m0, s30
	s_nop 0
	global_load_lds_dwordx4 v[224:225], off
	v_lshl_add_u64 v[224:225], s[26:27], 0, v[134:135]
	s_add_i32 m0, s30, 0x2000
	s_nop 0
	global_load_lds_dwordx4 v[224:225], off
	v_lshl_add_u64 v[224:225], v[230:231], 0, s[12:13]
	s_mov_b32 m0, s47
	s_nop 0
	global_load_lds_dwordx4 v[224:225], off
	v_lshl_add_u64 v[224:225], v[232:233], 0, s[12:13]
	s_mov_b32 m0, s48
	s_nop 0
	global_load_lds_dwordx4 v[224:225], off
	s_waitcnt vmcnt(8)
	s_waitcnt lgkmcnt(0)
	s_barrier
	s_setprio 1
	s_waitcnt lgkmcnt(0)
	v_mfma_f32_16x16x32_bf16 v[60:63], v[148:151], v[188:191], v[60:63]
	v_mfma_f32_16x16x32_bf16 v[60:63], v[160:163], v[192:195], v[60:63]
	v_mfma_f32_16x16x32_bf16 v[56:59], v[168:171], v[192:195], v[56:59]
	v_mfma_f32_16x16x32_bf16 v[56:59], v[164:167], v[188:191], v[56:59]
	v_mfma_f32_16x16x32_bf16 v[52:55], v[172:175], v[188:191], v[52:55]
	v_mfma_f32_16x16x32_bf16 v[52:55], v[176:179], v[192:195], v[52:55]
	v_mfma_f32_16x16x32_bf16 v[48:51], v[184:187], v[192:195], v[48:51]
	v_mfma_f32_16x16x32_bf16 v[48:51], v[180:183], v[188:191], v[48:51]
	v_mfma_f32_16x16x32_bf16 v[32:35], v[180:183], v[196:199], v[32:35]
	v_mfma_f32_16x16x32_bf16 v[32:35], v[184:187], v[200:203], v[32:35]
	v_mfma_f32_16x16x32_bf16 v[36:39], v[176:179], v[200:203], v[36:39]
	v_mfma_f32_16x16x32_bf16 v[36:39], v[172:175], v[196:199], v[36:39]
	v_mfma_f32_16x16x32_bf16 v[40:43], v[164:167], v[196:199], v[40:43]
	v_mfma_f32_16x16x32_bf16 v[40:43], v[168:171], v[200:203], v[40:43]
	v_mfma_f32_16x16x32_bf16 v[44:47], v[160:163], v[200:203], v[44:47]
	v_mfma_f32_16x16x32_bf16 v[44:47], v[148:151], v[196:199], v[44:47]
	v_mfma_f32_16x16x32_bf16 v[28:31], v[148:151], v[208:211], v[28:31]
	v_mfma_f32_16x16x32_bf16 v[28:31], v[160:163], v[212:215], v[28:31]
	v_mfma_f32_16x16x32_bf16 v[24:27], v[168:171], v[212:215], v[24:27]
	v_mfma_f32_16x16x32_bf16 v[24:27], v[164:167], v[208:211], v[24:27]
	v_mfma_f32_16x16x32_bf16 v[20:23], v[172:175], v[208:211], v[20:23]
	v_mfma_f32_16x16x32_bf16 v[20:23], v[176:179], v[212:215], v[20:23]
	v_mfma_f32_16x16x32_bf16 v[16:19], v[184:187], v[212:215], v[16:19]
	v_mfma_f32_16x16x32_bf16 v[16:19], v[180:183], v[208:211], v[16:19]
	v_mfma_f32_16x16x32_bf16 v[0:3], v[180:183], v[216:219], v[0:3]
	v_mfma_f32_16x16x32_bf16 v[0:3], v[184:187], v[220:223], v[0:3]
	v_mfma_f32_16x16x32_bf16 v[4:7], v[176:179], v[220:223], v[4:7]
	v_mfma_f32_16x16x32_bf16 v[4:7], v[172:175], v[216:219], v[4:7]
	v_mfma_f32_16x16x32_bf16 v[8:11], v[164:167], v[216:219], v[8:11]
	v_mfma_f32_16x16x32_bf16 v[8:11], v[168:171], v[220:223], v[8:11]
	v_mfma_f32_16x16x32_bf16 v[12:15], v[160:163], v[220:223], v[12:15]
	v_mfma_f32_16x16x32_bf16 v[12:15], v[148:151], v[216:219], v[12:15]
	s_setprio 0
	s_barrier
	s_add_u32 s8, s8, 0x100
	s_addc_u32 s9, s9, 0
	s_add_u32 s33, s33, 0x100
	s_addc_u32 s34, s34, 0
	s_cmp_ge_i32 s35, s44
	s_mov_b32 s26, s35
	s_cbranch_scc0 .LBB0_541

; #define PG8_STAGE(bufoff, gbase, voff) do { _Pragma("unroll") for (int _i = 0; _i < 2; ++_i) \
;         __builtin_amdgcn_global_load_lds((const unsigned*)((const char*)(gbase) + (voff)[_i]), (LAS unsigned*)(lds + (bufoff) + ldsw + _i * 8192), 16, 0, 0); } while (0)
; #define PG8_LDA(dst, b, h) do { _Pragma("unroll") for (int m = 0; m < 4; ++m) _Pragma("unroll") for (int k = 0; k < 2; ++k) dst[m][k] = *(const LAS bf16x8*)(lds + PG8_SA(b, h) + aoff + m * 2048 + k * 1024); } while (0)
; #define PG8_LDB(dst, b, h) do { _Pragma("unroll") for (int n = 0; n < 2; ++n) _Pragma("unroll") for (int k = 0; k < 2; ++k) dst[n][k] = *(const LAS bf16x8*)(lds + PG8_SB(b, h) + boff + n * 2048 + k * 1024); } while (0)
; #define PG8_MMA(ai, bj, At, Bt) do { __builtin_amdgcn_s_setprio(1); _Pragma("unroll") for (int m = 0; m < 4; ++m) _Pragma("unroll") for (int n = 0; n < 2; ++n) _Pragma("unroll") for (int k = 0; k < 2; ++k) \
;         acc[ai][bj][m][n] = __builtin_amdgcn_mfma_f32_16x16x32_bf16(Bt[n][k], At[m][k], acc[ai][bj][m][n], 0, 0, 0); __builtin_amdgcn_s_setprio(0); } while (0)
; #define PG8_WAIT_V(n) asm volatile("s_waitcnt vmcnt(" #n ")" ::: "memory")
; #define PG8_WAIT_L(n) asm volatile("s_waitcnt lgkmcnt(" #n ")" ::: "memory")
; #define PG8_BAR __builtin_amdgcn_s_barrier()
; #define PG8_SCHED __builtin_amdgcn_sched_barrier(0)
; template <class Epi>
; __device__ __forceinline__ void gemm_phase(LAS unsigned char* lds, const Gemm g, const StaticOrder& S, const Epi& E) {
;     ...
;             const bool last = (t == nt - 2);
;             const char* a1 = cA + (size_t)(t + 1) * kstep;
;             const char* a2 = last ? nA : cA + (size_t)(t + 2) * kstep; const char* b2 = last ? nB : cB + (size_t)(t + 2) * kstep;
;             const char* a3 = a2 + kstep; const char* b3 = b2 + kstep;
;             PG8_LDB(B0, 0, 0); PG8_LDB(B1, 0, 1); PG8_SCHED; PG8_LDA(At, 0, 0); PG8_STAGE(PG8_SA(1, 1), a1 + hstepA, voffA);
;             PG8_WAIT_V(8); PG8_WAIT_L(0); PG8_BAR; PG8_MMA(0, 0, At, B0); PG8_MMA(0, 1, At, B1); PG8_BAR; PG8_SCHED;
;             PG8_LDA(At, 0, 1); PG8_STAGE(PG8_SB(0, 0), b2, voffB); PG8_STAGE(PG8_SB(0, 1), b2 + hstepB, voffB); PG8_STAGE(PG8_SA(0, 0), a2, voffA);
;             PG8_WAIT_V(8); PG8_WAIT_L(0); PG8_BAR; PG8_MMA(1, 0, At, B0); PG8_MMA(1, 1, At, B1); PG8_BAR; PG8_SCHED;
.LBB0_834:
	ds_read_b128 v[156:159], v152
	ds_read_b128 v[160:163], v152 offset:1024
	ds_read_b128 v[164:167], v152 offset:2048
	ds_read_b128 v[168:171], v152 offset:3072
	ds_read_b128 v[172:175], v153
	ds_read_b128 v[176:179], v153 offset:1024
	ds_read_b128 v[180:183], v153 offset:2048
	ds_read_b128 v[184:187], v153 offset:3072
	s_add_i32 s49, s22, 2
	s_add_u32 s4, s0, 0x100
	s_addc_u32 s5, s1, 0
	s_cmp_eq_u32 s40, s22
	s_cselect_b32 s22, s20, s47
	s_cselect_b32 s25, s11, s5
	s_cselect_b32 s24, s10, s4
	s_cselect_b32 s23, s21, s48
	v_lshl_add_u64 v[224:225], s[0:1], 0, v[138:139]
	s_add_i32 m0, s29, 0xc000
	ds_read_b128 v[188:191], v154
	ds_read_b128 v[192:195], v154 offset:1024
	ds_read_b128 v[196:199], v154 offset:2048
	ds_read_b128 v[200:203], v154 offset:3072
	ds_read_b128 v[208:211], v154 offset:4096
	ds_read_b128 v[212:215], v154 offset:5120
	ds_read_b128 v[216:219], v154 offset:6144
	ds_read_b128 v[220:223], v154 offset:7168
	global_load_lds_dwordx4 v[224:225], off
	v_lshl_add_u64 v[224:225], s[0:1], 0, v[140:141]
	s_add_i32 m0, s29, 0xe000
	s_nop 0
	global_load_lds_dwordx4 v[224:225], off
	s_waitcnt vmcnt(8)
	s_waitcnt lgkmcnt(0)
	s_barrier
	s_setprio 1
	s_waitcnt lgkmcnt(0)
	v_mfma_f32_16x16x32_bf16 v[124:127], v[156:159], v[188:191], v[124:127]
	v_mfma_f32_16x16x32_bf16 v[124:127], v[160:163], v[192:195], v[124:127]
	v_mfma_f32_16x16x32_bf16 v[120:123], v[168:171], v[192:195], v[120:123]
	v_mfma_f32_16x16x32_bf16 v[120:123], v[164:167], v[188:191], v[120:123]
	v_mfma_f32_16x16x32_bf16 v[116:119], v[172:175], v[188:191], v[116:119]
	v_mfma_f32_16x16x32_bf16 v[116:119], v[176:179], v[192:195], v[116:119]
	v_mfma_f32_16x16x32_bf16 v[112:115], v[184:187], v[192:195], v[112:115]
	v_mfma_f32_16x16x32_bf16 v[112:115], v[180:183], v[188:191], v[112:115]
	v_mfma_f32_16x16x32_bf16 v[96:99], v[180:183], v[196:199], v[96:99]
	v_mfma_f32_16x16x32_bf16 v[96:99], v[184:187], v[200:203], v[96:99]
	v_mfma_f32_16x16x32_bf16 v[100:103], v[176:179], v[200:203], v[100:103]
	v_mfma_f32_16x16x32_bf16 v[100:103], v[172:175], v[196:199], v[100:103]
	v_mfma_f32_16x16x32_bf16 v[104:107], v[164:167], v[196:199], v[104:107]
	v_mfma_f32_16x16x32_bf16 v[104:107], v[168:171], v[200:203], v[104:107]
	v_mfma_f32_16x16x32_bf16 v[108:111], v[160:163], v[200:203], v[108:111]
	v_mfma_f32_16x16x32_bf16 v[108:111], v[156:159], v[196:199], v[108:111]
	v_mfma_f32_16x16x32_bf16 v[92:95], v[156:159], v[208:211], v[92:95]
	v_mfma_f32_16x16x32_bf16 v[92:95], v[160:163], v[212:215], v[92:95]
	v_mfma_f32_16x16x32_bf16 v[88:91], v[168:171], v[212:215], v[88:91]
	v_mfma_f32_16x16x32_bf16 v[88:91], v[164:167], v[208:211], v[88:91]
	v_mfma_f32_16x16x32_bf16 v[84:87], v[172:175], v[208:211], v[84:87]
	v_mfma_f32_16x16x32_bf16 v[84:87], v[176:179], v[212:215], v[84:87]
	v_mfma_f32_16x16x32_bf16 v[80:83], v[184:187], v[212:215], v[80:83]
	v_mfma_f32_16x16x32_bf16 v[80:83], v[180:183], v[208:211], v[80:83]
	v_mfma_f32_16x16x32_bf16 v[64:67], v[180:183], v[216:219], v[64:67]
	v_mfma_f32_16x16x32_bf16 v[64:67], v[184:187], v[220:223], v[64:67]
	v_mfma_f32_16x16x32_bf16 v[68:71], v[176:179], v[220:223], v[68:71]
	v_mfma_f32_16x16x32_bf16 v[68:71], v[172:175], v[216:219], v[68:71]
	v_mfma_f32_16x16x32_bf16 v[72:75], v[164:167], v[216:219], v[72:75]
	v_mfma_f32_16x16x32_bf16 v[72:75], v[168:171], v[220:223], v[72:75]
	v_mfma_f32_16x16x32_bf16 v[76:79], v[160:163], v[220:223], v[76:79]
	v_mfma_f32_16x16x32_bf16 v[76:79], v[156:159], v[216:219], v[76:79]
	s_setprio 0
	s_barrier
	s_add_i32 s0, s43, s28
	v_lshl_add_u64 v[224:225], s[22:23], 0, v[130:131]
	s_mov_b32 m0, s0
	ds_read_b128 v[188:191], v154 offset:16384
	ds_read_b128 v[192:195], v154 offset:17408
	ds_read_b128 v[196:199], v154 offset:18432
	ds_read_b128 v[200:203], v154 offset:19456
	ds_read_b128 v[208:211], v154 offset:20480
	ds_read_b128 v[212:215], v154 offset:21504
	ds_read_b128 v[216:219], v154 offset:22528
	ds_read_b128 v[220:223], v154 offset:23552
	global_load_lds_dwordx4 v[224:225], off
	s_add_i32 m0, s0, 0x2000
	s_add_u32 s0, s22, 0x18000
	v_lshl_add_u64 v[226:227], s[22:23], 0, v[134:135]
	s_addc_u32 s1, s23, 0
	s_add_i32 s50, s44, s28
	global_load_lds_dwordx4 v[226:227], off
	v_lshl_add_u64 v[230:231], s[0:1], 0, v[130:131]
	s_mov_b32 m0, s50
	v_lshl_add_u64 v[232:233], s[24:25], 0, v[132:133]
	global_load_lds_dwordx4 v[230:231], off
	v_lshl_add_u64 v[230:231], s[0:1], 0, v[134:135]
	s_add_i32 m0, s50, 0x2000
	s_nop 0
	global_load_lds_dwordx4 v[230:231], off
	v_lshl_add_u64 v[230:231], s[24:25], 0, v[128:129]
	s_mov_b32 m0, s29
	s_nop 0
	global_load_lds_dwordx4 v[230:231], off
	s_mov_b32 m0, s30
	s_nop 0
	global_load_lds_dwordx4 v[232:233], off
	s_waitcnt vmcnt(8)
	s_waitcnt lgkmcnt(0)
	s_barrier
; #define PG8_STAGE(bufoff, gbase, voff) do { _Pragma("unroll") for (int _i = 0; _i < 2; ++_i) \
;         __builtin_amdgcn_global_load_lds((const unsigned*)((const char*)(gbase) + (voff)[_i]), (LAS unsigned*)(lds + (bufoff) + ldsw + _i * 8192), 16, 0, 0); } while (0)
; #define PG8_LDA(dst, b, h) do { _Pragma("unroll") for (int m = 0; m < 4; ++m) _Pragma("unroll") for (int k = 0; k < 2; ++k) dst[m][k] = *(const LAS bf16x8*)(lds + PG8_SA(b, h) + aoff + m * 2048 + k * 1024); } while (0)
; #define PG8_LDB(dst, b, h) do { _Pragma("unroll") for (int n = 0; n < 2; ++n) _Pragma("unroll") for (int k = 0; k < 2; ++k) dst[n][k] = *(const LAS bf16x8*)(lds + PG8_SB(b, h) + boff + n * 2048 + k * 1024); } while (0)
; #define PG8_MMA(ai, bj, At, Bt) do { __builtin_amdgcn_s_setprio(1); _Pragma("unroll") for (int m = 0; m < 4; ++m) _Pragma("unroll") for (int n = 0; n < 2; ++n) _Pragma("unroll") for (int k = 0; k < 2; ++k) \
;         acc[ai][bj][m][n] = __builtin_amdgcn_mfma_f32_16x16x32_bf16(Bt[n][k], At[m][k], acc[ai][bj][m][n], 0, 0, 0); __builtin_amdgcn_s_setprio(0); } while (0)
; #define PG8_WAIT_V(n) asm volatile("s_waitcnt vmcnt(" #n ")" ::: "memory")
; #define PG8_WAIT_L(n) asm volatile("s_waitcnt lgkmcnt(" #n ")" ::: "memory")
; #define PG8_BAR __builtin_amdgcn_s_barrier()
; #define PG8_SCHED __builtin_amdgcn_sched_barrier(0)
; template <class Epi>
; __device__ __forceinline__ void gemm_phase(LAS unsigned char* lds, const Gemm g, const StaticOrder& S, const Epi& E) {
;     ...
;             PG8_WAIT_V(8); PG8_WAIT_L(0); PG8_BAR; PG8_MMA(1, 0, At, B0); PG8_MMA(1, 1, At, B1); PG8_BAR; PG8_SCHED;
;             PG8_LDB(B0, 1, 0); PG8_LDB(B1, 1, 1); PG8_SCHED; PG8_LDA(At, 1, 0); PG8_STAGE(PG8_SA(0, 1), a2 + hstepA, voffA);
;             PG8_WAIT_V(8); PG8_WAIT_L(0); PG8_BAR; PG8_MMA(0, 0, At, B0); PG8_MMA(0, 1, At, B1); PG8_BAR; PG8_SCHED;
	s_setprio 1
	s_waitcnt lgkmcnt(0)
	v_mfma_f32_16x16x32_bf16 v[60:63], v[156:159], v[188:191], v[60:63]
	v_mfma_f32_16x16x32_bf16 v[60:63], v[160:163], v[192:195], v[60:63]
	v_mfma_f32_16x16x32_bf16 v[56:59], v[168:171], v[192:195], v[56:59]
	v_mfma_f32_16x16x32_bf16 v[56:59], v[164:167], v[188:191], v[56:59]
	v_mfma_f32_16x16x32_bf16 v[52:55], v[172:175], v[188:191], v[52:55]
	v_mfma_f32_16x16x32_bf16 v[52:55], v[176:179], v[192:195], v[52:55]
	v_mfma_f32_16x16x32_bf16 v[48:51], v[184:187], v[192:195], v[48:51]
	v_mfma_f32_16x16x32_bf16 v[48:51], v[180:183], v[188:191], v[48:51]
	v_mfma_f32_16x16x32_bf16 v[32:35], v[180:183], v[196:199], v[32:35]
	v_mfma_f32_16x16x32_bf16 v[32:35], v[184:187], v[200:203], v[32:35]
	v_mfma_f32_16x16x32_bf16 v[36:39], v[176:179], v[200:203], v[36:39]
	v_mfma_f32_16x16x32_bf16 v[36:39], v[172:175], v[196:199], v[36:39]
	v_mfma_f32_16x16x32_bf16 v[40:43], v[164:167], v[196:199], v[40:43]
	v_mfma_f32_16x16x32_bf16 v[40:43], v[168:171], v[200:203], v[40:43]
	v_mfma_f32_16x16x32_bf16 v[44:47], v[160:163], v[200:203], v[44:47]
	v_mfma_f32_16x16x32_bf16 v[44:47], v[156:159], v[196:199], v[44:47]
	v_mfma_f32_16x16x32_bf16 v[28:31], v[156:159], v[208:211], v[28:31]
	v_mfma_f32_16x16x32_bf16 v[28:31], v[160:163], v[212:215], v[28:31]
	v_mfma_f32_16x16x32_bf16 v[24:27], v[168:171], v[212:215], v[24:27]
	v_mfma_f32_16x16x32_bf16 v[24:27], v[164:167], v[208:211], v[24:27]
	v_mfma_f32_16x16x32_bf16 v[20:23], v[172:175], v[208:211], v[20:23]
	v_mfma_f32_16x16x32_bf16 v[20:23], v[176:179], v[212:215], v[20:23]
	v_mfma_f32_16x16x32_bf16 v[16:19], v[184:187], v[212:215], v[16:19]
	v_mfma_f32_16x16x32_bf16 v[16:19], v[180:183], v[208:211], v[16:19]
	v_mfma_f32_16x16x32_bf16 v[0:3], v[180:183], v[216:219], v[0:3]
	v_mfma_f32_16x16x32_bf16 v[0:3], v[184:187], v[220:223], v[0:3]
	v_mfma_f32_16x16x32_bf16 v[4:7], v[176:179], v[220:223], v[4:7]
	v_mfma_f32_16x16x32_bf16 v[4:7], v[172:175], v[216:219], v[4:7]
	v_mfma_f32_16x16x32_bf16 v[8:11], v[164:167], v[216:219], v[8:11]
	v_mfma_f32_16x16x32_bf16 v[8:11], v[168:171], v[220:223], v[8:11]
	v_mfma_f32_16x16x32_bf16 v[12:15], v[160:163], v[220:223], v[12:15]
	v_mfma_f32_16x16x32_bf16 v[12:15], v[156:159], v[216:219], v[12:15]
	s_setprio 0
	s_barrier
	s_add_i32 s50, 0, 0x18000
	v_add_u32_e32 v136, s50, v149
	s_add_i32 s51, 0, 0x1c000
	ds_read_b128 v[156:159], v136
	ds_read_b128 v[160:163], v136 offset:1024
	ds_read_b128 v[164:167], v136 offset:2048
	ds_read_b128 v[168:171], v136 offset:3072
	v_add_u32_e32 v136, s51, v149
	ds_read_b128 v[172:175], v136
	ds_read_b128 v[176:179], v136 offset:1024
	ds_read_b128 v[180:183], v136 offset:2048
	ds_read_b128 v[184:187], v136 offset:3072
	s_add_u32 s0, s24, 0x18000
	s_addc_u32 s1, s25, 0
	s_mov_b32 m0, s31
	v_lshl_add_u64 v[234:235], s[0:1], 0, v[128:129]
	ds_read_b128 v[188:191], v154 offset:32768
	ds_read_b128 v[192:195], v154 offset:33792
	ds_read_b128 v[196:199], v154 offset:34816
	ds_read_b128 v[200:203], v154 offset:35840
	ds_read_b128 v[208:211], v154 offset:36864
	ds_read_b128 v[212:215], v154 offset:37888
	ds_read_b128 v[216:219], v154 offset:38912
	ds_read_b128 v[220:223], v154 offset:39936
	global_load_lds_dwordx4 v[234:235], off
	v_lshl_add_u64 v[234:235], s[0:1], 0, v[132:133]
	s_mov_b32 m0, s34
	s_nop 0
	global_load_lds_dwordx4 v[234:235], off
	s_waitcnt vmcnt(8)
	s_waitcnt lgkmcnt(0)
	s_barrier
	s_setprio 1
	s_waitcnt lgkmcnt(0)
	v_mfma_f32_16x16x32_bf16 v[124:127], v[156:159], v[188:191], v[124:127]
	v_mfma_f32_16x16x32_bf16 v[124:127], v[160:163], v[192:195], v[124:127]
	v_mfma_f32_16x16x32_bf16 v[120:123], v[168:171], v[192:195], v[120:123]
	v_mfma_f32_16x16x32_bf16 v[120:123], v[164:167], v[188:191], v[120:123]
	v_mfma_f32_16x16x32_bf16 v[116:119], v[172:175], v[188:191], v[116:119]
	v_mfma_f32_16x16x32_bf16 v[116:119], v[176:179], v[192:195], v[116:119]
	v_mfma_f32_16x16x32_bf16 v[112:115], v[184:187], v[192:195], v[112:115]
	v_mfma_f32_16x16x32_bf16 v[112:115], v[180:183], v[188:191], v[112:115]
	v_mfma_f32_16x16x32_bf16 v[96:99], v[180:183], v[196:199], v[96:99]
	v_mfma_f32_16x16x32_bf16 v[96:99], v[184:187], v[200:203], v[96:99]
	v_mfma_f32_16x16x32_bf16 v[100:103], v[176:179], v[200:203], v[100:103]
	v_mfma_f32_16x16x32_bf16 v[100:103], v[172:175], v[196:199], v[100:103]
	v_mfma_f32_16x16x32_bf16 v[104:107], v[164:167], v[196:199], v[104:107]
	v_mfma_f32_16x16x32_bf16 v[104:107], v[168:171], v[200:203], v[104:107]
	v_mfma_f32_16x16x32_bf16 v[108:111], v[160:163], v[200:203], v[108:111]
	v_mfma_f32_16x16x32_bf16 v[108:111], v[156:159], v[196:199], v[108:111]
	v_mfma_f32_16x16x32_bf16 v[92:95], v[156:159], v[208:211], v[92:95]
	v_mfma_f32_16x16x32_bf16 v[92:95], v[160:163], v[212:215], v[92:95]
	v_mfma_f32_16x16x32_bf16 v[88:91], v[168:171], v[212:215], v[88:91]
	v_mfma_f32_16x16x32_bf16 v[88:91], v[164:167], v[208:211], v[88:91]
	v_mfma_f32_16x16x32_bf16 v[84:87], v[172:175], v[208:211], v[84:87]
	v_mfma_f32_16x16x32_bf16 v[84:87], v[176:179], v[212:215], v[84:87]
	v_mfma_f32_16x16x32_bf16 v[80:83], v[184:187], v[212:215], v[80:83]
	v_mfma_f32_16x16x32_bf16 v[80:83], v[180:183], v[208:211], v[80:83]
	v_mfma_f32_16x16x32_bf16 v[64:67], v[180:183], v[216:219], v[64:67]
	v_mfma_f32_16x16x32_bf16 v[64:67], v[184:187], v[220:223], v[64:67]
	v_mfma_f32_16x16x32_bf16 v[68:71], v[176:179], v[220:223], v[68:71]
	v_mfma_f32_16x16x32_bf16 v[68:71], v[172:175], v[216:219], v[68:71]
	v_mfma_f32_16x16x32_bf16 v[72:75], v[164:167], v[216:219], v[72:75]
	v_mfma_f32_16x16x32_bf16 v[72:75], v[168:171], v[220:223], v[72:75]
	v_mfma_f32_16x16x32_bf16 v[76:79], v[160:163], v[220:223], v[76:79]
	v_mfma_f32_16x16x32_bf16 v[76:79], v[156:159], v[216:219], v[76:79]
	s_setprio 0
	s_barrier
; #define PG8_STAGE(bufoff, gbase, voff) do { _Pragma("unroll") for (int _i = 0; _i < 2; ++_i) \
;         __builtin_amdgcn_global_load_lds((const unsigned*)((const char*)(gbase) + (voff)[_i]), (LAS unsigned*)(lds + (bufoff) + ldsw + _i * 8192), 16, 0, 0); } while (0)
; #define PG8_LDA(dst, b, h) do { _Pragma("unroll") for (int m = 0; m < 4; ++m) _Pragma("unroll") for (int k = 0; k < 2; ++k) dst[m][k] = *(const LAS bf16x8*)(lds + PG8_SA(b, h) + aoff + m * 2048 + k * 1024); } while (0)
; #define PG8_MMA(ai, bj, At, Bt) do { __builtin_amdgcn_s_setprio(1); _Pragma("unroll") for (int m = 0; m < 4; ++m) _Pragma("unroll") for (int n = 0; n < 2; ++n) _Pragma("unroll") for (int k = 0; k < 2; ++k) \
;         acc[ai][bj][m][n] = __builtin_amdgcn_mfma_f32_16x16x32_bf16(Bt[n][k], At[m][k], acc[ai][bj][m][n], 0, 0, 0); __builtin_amdgcn_s_setprio(0); } while (0)
; #define PG8_WAIT_V(n) asm volatile("s_waitcnt vmcnt(" #n ")" ::: "memory")
; #define PG8_WAIT_L(n) asm volatile("s_waitcnt lgkmcnt(" #n ")" ::: "memory")
; #define PG8_BAR __builtin_amdgcn_s_barrier()
; #define PG8_SCHED __builtin_amdgcn_sched_barrier(0)
; template <class Epi>
; __device__ __forceinline__ void gemm_phase(LAS unsigned char* lds, const Gemm g, const StaticOrder& S, const Epi& E) {
;     ...
;             PG8_LDA(At, 1, 1); PG8_STAGE(PG8_SB(1, 0), b3, voffB); PG8_STAGE(PG8_SB(1, 1), b3 + hstepB, voffB); PG8_STAGE(PG8_SA(1, 0), a3, voffA);
;             PG8_WAIT_V(8); PG8_WAIT_L(0); PG8_BAR; PG8_MMA(1, 0, At, B0); PG8_MMA(1, 1, At, B1); PG8_BAR; PG8_SCHED;
;         }
	s_add_i32 s0, s50, s28
	v_lshl_add_u64 v[224:225], v[224:225], 0, s[14:15]
	s_mov_b32 m0, s0
	ds_read_b128 v[188:191], v154 offset:49152
	ds_read_b128 v[192:195], v154 offset:50176
	ds_read_b128 v[196:199], v154 offset:51200
	ds_read_b128 v[200:203], v154 offset:52224
	ds_read_b128 v[208:211], v154 offset:53248
	ds_read_b128 v[212:215], v154 offset:54272
	ds_read_b128 v[216:219], v154 offset:55296
	ds_read_b128 v[220:223], v154 offset:56320
	global_load_lds_dwordx4 v[224:225], off
	s_add_i32 m0, s0, 0x2000
	s_add_u32 s0, s22, 0x18080
	v_lshl_add_u64 v[224:225], v[226:227], 0, s[14:15]
	s_addc_u32 s1, s23, 0
	s_add_i32 s22, s51, s28
	global_load_lds_dwordx4 v[224:225], off
	v_lshl_add_u64 v[224:225], s[0:1], 0, v[130:131]
	s_mov_b32 m0, s22
	s_nop 0
	global_load_lds_dwordx4 v[224:225], off
	v_lshl_add_u64 v[224:225], s[0:1], 0, v[134:135]
	s_add_i32 m0, s22, 0x2000
	s_nop 0
	global_load_lds_dwordx4 v[224:225], off
	v_lshl_add_u64 v[224:225], v[230:231], 0, s[14:15]
	s_mov_b32 m0, s38
	s_nop 0
	global_load_lds_dwordx4 v[224:225], off
	v_lshl_add_u64 v[224:225], v[232:233], 0, s[14:15]
	s_mov_b32 m0, s39
	s_nop 0
	global_load_lds_dwordx4 v[224:225], off
	s_waitcnt vmcnt(8)
	s_waitcnt lgkmcnt(0)
	s_barrier
	s_setprio 1
	s_waitcnt lgkmcnt(0)
	v_mfma_f32_16x16x32_bf16 v[60:63], v[156:159], v[188:191], v[60:63]
	v_mfma_f32_16x16x32_bf16 v[60:63], v[160:163], v[192:195], v[60:63]
	v_mfma_f32_16x16x32_bf16 v[56:59], v[168:171], v[192:195], v[56:59]
	v_mfma_f32_16x16x32_bf16 v[56:59], v[164:167], v[188:191], v[56:59]
	v_mfma_f32_16x16x32_bf16 v[52:55], v[172:175], v[188:191], v[52:55]
	v_mfma_f32_16x16x32_bf16 v[52:55], v[176:179], v[192:195], v[52:55]
	v_mfma_f32_16x16x32_bf16 v[48:51], v[184:187], v[192:195], v[48:51]
	v_mfma_f32_16x16x32_bf16 v[48:51], v[180:183], v[188:191], v[48:51]
	v_mfma_f32_16x16x32_bf16 v[32:35], v[180:183], v[196:199], v[32:35]
	v_mfma_f32_16x16x32_bf16 v[32:35], v[184:187], v[200:203], v[32:35]
	v_mfma_f32_16x16x32_bf16 v[36:39], v[176:179], v[200:203], v[36:39]
	v_mfma_f32_16x16x32_bf16 v[36:39], v[172:175], v[196:199], v[36:39]
	v_mfma_f32_16x16x32_bf16 v[40:43], v[164:167], v[196:199], v[40:43]
	v_mfma_f32_16x16x32_bf16 v[40:43], v[168:171], v[200:203], v[40:43]
	v_mfma_f32_16x16x32_bf16 v[44:47], v[160:163], v[200:203], v[44:47]
	v_mfma_f32_16x16x32_bf16 v[44:47], v[156:159], v[196:199], v[44:47]
	v_mfma_f32_16x16x32_bf16 v[28:31], v[156:159], v[208:211], v[28:31]
	v_mfma_f32_16x16x32_bf16 v[28:31], v[160:163], v[212:215], v[28:31]
	v_mfma_f32_16x16x32_bf16 v[24:27], v[168:171], v[212:215], v[24:27]
	v_mfma_f32_16x16x32_bf16 v[24:27], v[164:167], v[208:211], v[24:27]
	v_mfma_f32_16x16x32_bf16 v[20:23], v[172:175], v[208:211], v[20:23]
	v_mfma_f32_16x16x32_bf16 v[20:23], v[176:179], v[212:215], v[20:23]
	v_mfma_f32_16x16x32_bf16 v[16:19], v[184:187], v[212:215], v[16:19]
	v_mfma_f32_16x16x32_bf16 v[16:19], v[180:183], v[208:211], v[16:19]
	v_mfma_f32_16x16x32_bf16 v[0:3], v[180:183], v[216:219], v[0:3]
	v_mfma_f32_16x16x32_bf16 v[0:3], v[184:187], v[220:223], v[0:3]
	v_mfma_f32_16x16x32_bf16 v[4:7], v[176:179], v[220:223], v[4:7]
	v_mfma_f32_16x16x32_bf16 v[4:7], v[172:175], v[216:219], v[4:7]
	v_mfma_f32_16x16x32_bf16 v[8:11], v[164:167], v[216:219], v[8:11]
	v_mfma_f32_16x16x32_bf16 v[8:11], v[168:171], v[220:223], v[8:11]
	v_mfma_f32_16x16x32_bf16 v[12:15], v[160:163], v[220:223], v[12:15]
	v_mfma_f32_16x16x32_bf16 v[12:15], v[156:159], v[216:219], v[12:15]
	s_setprio 0
	s_barrier
	s_add_u32 s47, s47, 0x100
	s_addc_u32 s48, s48, 0
	s_cmp_ge_i32 s49, s36
	s_mov_b64 s[0:1], s[4:5]
	s_mov_b32 s22, s49
	s_cbranch_scc0 .LBB0_834

; #define PG8_STAGE(bufoff, gbase, voff) do { _Pragma("unroll") for (int _i = 0; _i < 2; ++_i) \
;         __builtin_amdgcn_global_load_lds((const unsigned*)((const char*)(gbase) + (voff)[_i]), (LAS unsigned*)(lds + (bufoff) + ldsw + _i * 8192), 16, 0, 0); } while (0)
; #define PG8_LDA(dst, b, h) do { _Pragma("unroll") for (int m = 0; m < 4; ++m) _Pragma("unroll") for (int k = 0; k < 2; ++k) dst[m][k] = *(const LAS bf16x8*)(lds + PG8_SA(b, h) + aoff + m * 2048 + k * 1024); } while (0)
; #define PG8_LDB(dst, b, h) do { _Pragma("unroll") for (int n = 0; n < 2; ++n) _Pragma("unroll") for (int k = 0; k < 2; ++k) dst[n][k] = *(const LAS bf16x8*)(lds + PG8_SB(b, h) + boff + n * 2048 + k * 1024); } while (0)
; #define PG8_MMA(ai, bj, At, Bt) do { __builtin_amdgcn_s_setprio(1); _Pragma("unroll") for (int m = 0; m < 4; ++m) _Pragma("unroll") for (int n = 0; n < 2; ++n) _Pragma("unroll") for (int k = 0; k < 2; ++k) \
;         acc[ai][bj][m][n] = __builtin_amdgcn_mfma_f32_16x16x32_bf16(Bt[n][k], At[m][k], acc[ai][bj][m][n], 0, 0, 0); __builtin_amdgcn_s_setprio(0); } while (0)
; #define PG8_WAIT_V(n) asm volatile("s_waitcnt vmcnt(" #n ")" ::: "memory")
; #define PG8_WAIT_L(n) asm volatile("s_waitcnt lgkmcnt(" #n ")" ::: "memory")
; #define PG8_BAR __builtin_amdgcn_s_barrier()
; #define PG8_SCHED __builtin_amdgcn_sched_barrier(0)
; template <class Epi>
; __device__ __forceinline__ void gemm_phase(LAS unsigned char* lds, const Gemm g, const StaticOrder& S, const Epi& E) {
;     ...
;             PG8_LDB(B0, 0, 0); PG8_LDB(B1, 0, 1); PG8_SCHED; PG8_LDA(At, 0, 0); PG8_STAGE(PG8_SA(1, 1), a1 + hstepA, voffA);
;             PG8_WAIT_V(8); PG8_WAIT_L(0); PG8_BAR; PG8_MMA(0, 0, At, B0); PG8_MMA(0, 1, At, B1); PG8_BAR; PG8_SCHED;
;             PG8_LDA(At, 0, 1); PG8_STAGE(PG8_SB(0, 0), b2, voffB); PG8_STAGE(PG8_SB(0, 1), b2 + hstepB, voffB); PG8_STAGE(PG8_SA(0, 0), a2, voffA);
;             PG8_WAIT_V(8); PG8_WAIT_L(0); PG8_BAR; PG8_MMA(1, 0, At, B0); PG8_MMA(1, 1, At, B1); PG8_BAR; PG8_SCHED;
.LBB0_912:
	ds_read_b128 v[96:99], v230
	ds_read_b128 v[100:103], v230 offset:1024
	ds_read_b128 v[104:107], v230 offset:2048
	ds_read_b128 v[116:119], v230 offset:3072
	ds_read_b128 v[120:123], v231
	ds_read_b128 v[124:127], v231 offset:1024
	ds_read_b128 v[136:139], v231 offset:2048
	ds_read_b128 v[148:151], v231 offset:3072
	s_add_i32 s56, s24, 2
	s_add_u32 s25, s4, 0xfffc0080
	s_addc_u32 s26, s5, -1
	s_cmp_eq_u32 s44, s24
	s_cselect_b32 s24, s53, s54
	s_cselect_b32 s27, s17, s26
	s_cselect_b32 s26, s19, s25
	s_cselect_b32 s25, s33, s55
	v_lshl_add_u64 v[192:193], s[4:5], 0, v[220:221]
	s_add_i32 m0, s31, 0xc000
	ds_read_b128 v[160:163], v232
	ds_read_b128 v[164:167], v232 offset:1024
	ds_read_b128 v[168:171], v232 offset:2048
	ds_read_b128 v[172:175], v232 offset:3072
	ds_read_b128 v[176:179], v232 offset:4096
	ds_read_b128 v[180:183], v232 offset:5120
	ds_read_b128 v[184:187], v232 offset:6144
	ds_read_b128 v[188:191], v232 offset:7168
	global_load_lds_dwordx4 v[192:193], off
	v_lshl_add_u64 v[192:193], s[4:5], 0, v[222:223]
	s_add_i32 m0, s31, 0xe000
	s_nop 0
	global_load_lds_dwordx4 v[192:193], off
	s_waitcnt vmcnt(8)
	s_waitcnt lgkmcnt(0)
	s_barrier
	s_setprio 1
	s_waitcnt lgkmcnt(0)
	v_mfma_f32_16x16x32_bf16 v[156:159], v[96:99], v[160:163], v[156:159]
	v_mfma_f32_16x16x32_bf16 v[156:159], v[100:103], v[164:167], v[156:159]
	v_mfma_f32_16x16x32_bf16 v[152:155], v[116:119], v[164:167], v[152:155]
	v_mfma_f32_16x16x32_bf16 v[152:155], v[104:107], v[160:163], v[152:155]
	v_mfma_f32_16x16x32_bf16 v[144:147], v[120:123], v[160:163], v[144:147]
	v_mfma_f32_16x16x32_bf16 v[144:147], v[124:127], v[164:167], v[144:147]
	v_mfma_f32_16x16x32_bf16 v[140:143], v[148:151], v[164:167], v[140:143]
	v_mfma_f32_16x16x32_bf16 v[140:143], v[136:139], v[160:163], v[140:143]
	v_mfma_f32_16x16x32_bf16 v[108:111], v[136:139], v[168:171], v[108:111]
	v_mfma_f32_16x16x32_bf16 v[108:111], v[148:151], v[172:175], v[108:111]
	v_mfma_f32_16x16x32_bf16 v[112:115], v[124:127], v[172:175], v[112:115]
	v_mfma_f32_16x16x32_bf16 v[112:115], v[120:123], v[168:171], v[112:115]
	v_mfma_f32_16x16x32_bf16 v[128:131], v[104:107], v[168:171], v[128:131]
	v_mfma_f32_16x16x32_bf16 v[128:131], v[116:119], v[172:175], v[128:131]
	v_mfma_f32_16x16x32_bf16 v[132:135], v[100:103], v[172:175], v[132:135]
	v_mfma_f32_16x16x32_bf16 v[132:135], v[96:99], v[168:171], v[132:135]
	v_mfma_f32_16x16x32_bf16 v[92:95], v[96:99], v[176:179], v[92:95]
	v_mfma_f32_16x16x32_bf16 v[92:95], v[100:103], v[180:183], v[92:95]
	v_mfma_f32_16x16x32_bf16 v[88:91], v[116:119], v[180:183], v[88:91]
	v_mfma_f32_16x16x32_bf16 v[88:91], v[104:107], v[176:179], v[88:91]
	v_mfma_f32_16x16x32_bf16 v[84:87], v[120:123], v[176:179], v[84:87]
	v_mfma_f32_16x16x32_bf16 v[84:87], v[124:127], v[180:183], v[84:87]
	v_mfma_f32_16x16x32_bf16 v[80:83], v[148:151], v[180:183], v[80:83]
	v_mfma_f32_16x16x32_bf16 v[80:83], v[136:139], v[176:179], v[80:83]
	v_mfma_f32_16x16x32_bf16 v[64:67], v[136:139], v[184:187], v[64:67]
	v_mfma_f32_16x16x32_bf16 v[64:67], v[148:151], v[188:191], v[64:67]
	v_mfma_f32_16x16x32_bf16 v[68:71], v[124:127], v[188:191], v[68:71]
	v_mfma_f32_16x16x32_bf16 v[68:71], v[120:123], v[184:187], v[68:71]
	v_mfma_f32_16x16x32_bf16 v[72:75], v[104:107], v[184:187], v[72:75]
	v_mfma_f32_16x16x32_bf16 v[72:75], v[116:119], v[188:191], v[72:75]
	v_mfma_f32_16x16x32_bf16 v[76:79], v[100:103], v[188:191], v[76:79]
	v_mfma_f32_16x16x32_bf16 v[76:79], v[96:99], v[184:187], v[76:79]
	s_setprio 0
	s_barrier
	s_add_i32 s57, s47, s30
	v_lshl_add_u64 v[192:193], s[24:25], 0, v[210:211]
	s_mov_b32 m0, s57
	ds_read_b128 v[160:163], v232 offset:16384
	ds_read_b128 v[164:167], v232 offset:17408
	ds_read_b128 v[168:171], v232 offset:18432
	ds_read_b128 v[172:175], v232 offset:19456
	ds_read_b128 v[176:179], v232 offset:20480
	ds_read_b128 v[180:183], v232 offset:21504
	ds_read_b128 v[184:187], v232 offset:22528
	ds_read_b128 v[188:191], v232 offset:23552
	global_load_lds_dwordx4 v[192:193], off
	s_add_i32 m0, s57, 0x2000
	s_add_u32 s58, s24, 0x40000
	v_lshl_add_u64 v[194:195], s[24:25], 0, v[214:215]
	s_addc_u32 s59, s25, 0
	s_add_i32 s57, s48, s30
	global_load_lds_dwordx4 v[194:195], off
	v_lshl_add_u64 v[196:197], s[58:59], 0, v[210:211]
	s_mov_b32 m0, s57
	v_lshl_add_u64 v[198:199], s[26:27], 0, v[212:213]
	global_load_lds_dwordx4 v[196:197], off
	v_lshl_add_u64 v[196:197], s[58:59], 0, v[214:215]
	s_add_i32 m0, s57, 0x2000
	s_nop 0
	global_load_lds_dwordx4 v[196:197], off
	v_lshl_add_u64 v[196:197], s[26:27], 0, v[208:209]
	s_mov_b32 m0, s31
	s_nop 0
	global_load_lds_dwordx4 v[196:197], off
	s_mov_b32 m0, s34
	s_nop 0
	global_load_lds_dwordx4 v[198:199], off
	s_waitcnt vmcnt(8)
	s_waitcnt lgkmcnt(0)
	s_barrier
; #define PG8_STAGE(bufoff, gbase, voff) do { _Pragma("unroll") for (int _i = 0; _i < 2; ++_i) \
;         __builtin_amdgcn_global_load_lds((const unsigned*)((const char*)(gbase) + (voff)[_i]), (LAS unsigned*)(lds + (bufoff) + ldsw + _i * 8192), 16, 0, 0); } while (0)
; #define PG8_LDA(dst, b, h) do { _Pragma("unroll") for (int m = 0; m < 4; ++m) _Pragma("unroll") for (int k = 0; k < 2; ++k) dst[m][k] = *(const LAS bf16x8*)(lds + PG8_SA(b, h) + aoff + m * 2048 + k * 1024); } while (0)
; #define PG8_LDB(dst, b, h) do { _Pragma("unroll") for (int n = 0; n < 2; ++n) _Pragma("unroll") for (int k = 0; k < 2; ++k) dst[n][k] = *(const LAS bf16x8*)(lds + PG8_SB(b, h) + boff + n * 2048 + k * 1024); } while (0)
; #define PG8_MMA(ai, bj, At, Bt) do { __builtin_amdgcn_s_setprio(1); _Pragma("unroll") for (int m = 0; m < 4; ++m) _Pragma("unroll") for (int n = 0; n < 2; ++n) _Pragma("unroll") for (int k = 0; k < 2; ++k) \
;         acc[ai][bj][m][n] = __builtin_amdgcn_mfma_f32_16x16x32_bf16(Bt[n][k], At[m][k], acc[ai][bj][m][n], 0, 0, 0); __builtin_amdgcn_s_setprio(0); } while (0)
; #define PG8_WAIT_V(n) asm volatile("s_waitcnt vmcnt(" #n ")" ::: "memory")
; #define PG8_WAIT_L(n) asm volatile("s_waitcnt lgkmcnt(" #n ")" ::: "memory")
; #define PG8_BAR __builtin_amdgcn_s_barrier()
; #define PG8_SCHED __builtin_amdgcn_sched_barrier(0)
; template <class Epi>
; __device__ __forceinline__ void gemm_phase(LAS unsigned char* lds, const Gemm g, const StaticOrder& S, const Epi& E) {
;     ...
;             PG8_WAIT_V(8); PG8_WAIT_L(0); PG8_BAR; PG8_MMA(1, 0, At, B0); PG8_MMA(1, 1, At, B1); PG8_BAR; PG8_SCHED;
;             PG8_LDB(B0, 1, 0); PG8_LDB(B1, 1, 1); PG8_SCHED; PG8_LDA(At, 1, 0); PG8_STAGE(PG8_SA(0, 1), a2 + hstepA, voffA);
;             PG8_WAIT_V(8); PG8_WAIT_L(0); PG8_BAR; PG8_MMA(0, 0, At, B0); PG8_MMA(0, 1, At, B1); PG8_BAR; PG8_SCHED;
	s_setprio 1
	s_waitcnt lgkmcnt(0)
	v_mfma_f32_16x16x32_bf16 v[60:63], v[96:99], v[160:163], v[60:63]
	v_mfma_f32_16x16x32_bf16 v[60:63], v[100:103], v[164:167], v[60:63]
	v_mfma_f32_16x16x32_bf16 v[56:59], v[116:119], v[164:167], v[56:59]
	v_mfma_f32_16x16x32_bf16 v[56:59], v[104:107], v[160:163], v[56:59]
	v_mfma_f32_16x16x32_bf16 v[52:55], v[120:123], v[160:163], v[52:55]
	v_mfma_f32_16x16x32_bf16 v[52:55], v[124:127], v[164:167], v[52:55]
	v_mfma_f32_16x16x32_bf16 v[48:51], v[148:151], v[164:167], v[48:51]
	v_mfma_f32_16x16x32_bf16 v[48:51], v[136:139], v[160:163], v[48:51]
	v_mfma_f32_16x16x32_bf16 v[32:35], v[136:139], v[168:171], v[32:35]
	v_mfma_f32_16x16x32_bf16 v[32:35], v[148:151], v[172:175], v[32:35]
	v_mfma_f32_16x16x32_bf16 v[36:39], v[124:127], v[172:175], v[36:39]
	v_mfma_f32_16x16x32_bf16 v[36:39], v[120:123], v[168:171], v[36:39]
	v_mfma_f32_16x16x32_bf16 v[40:43], v[104:107], v[168:171], v[40:43]
	v_mfma_f32_16x16x32_bf16 v[40:43], v[116:119], v[172:175], v[40:43]
	v_mfma_f32_16x16x32_bf16 v[44:47], v[100:103], v[172:175], v[44:47]
	v_mfma_f32_16x16x32_bf16 v[44:47], v[96:99], v[168:171], v[44:47]
	v_mfma_f32_16x16x32_bf16 v[28:31], v[96:99], v[176:179], v[28:31]
	v_mfma_f32_16x16x32_bf16 v[28:31], v[100:103], v[180:183], v[28:31]
	v_mfma_f32_16x16x32_bf16 v[24:27], v[116:119], v[180:183], v[24:27]
	v_mfma_f32_16x16x32_bf16 v[24:27], v[104:107], v[176:179], v[24:27]
	v_mfma_f32_16x16x32_bf16 v[20:23], v[120:123], v[176:179], v[20:23]
	v_mfma_f32_16x16x32_bf16 v[20:23], v[124:127], v[180:183], v[20:23]
	v_mfma_f32_16x16x32_bf16 v[16:19], v[148:151], v[180:183], v[16:19]
	v_mfma_f32_16x16x32_bf16 v[16:19], v[136:139], v[176:179], v[16:19]
	v_mfma_f32_16x16x32_bf16 v[0:3], v[136:139], v[184:187], v[0:3]
	v_mfma_f32_16x16x32_bf16 v[0:3], v[148:151], v[188:191], v[0:3]
	v_mfma_f32_16x16x32_bf16 v[4:7], v[124:127], v[188:191], v[4:7]
	v_mfma_f32_16x16x32_bf16 v[4:7], v[120:123], v[184:187], v[4:7]
	v_mfma_f32_16x16x32_bf16 v[8:11], v[104:107], v[184:187], v[8:11]
	v_mfma_f32_16x16x32_bf16 v[8:11], v[116:119], v[188:191], v[8:11]
	v_mfma_f32_16x16x32_bf16 v[12:15], v[100:103], v[188:191], v[12:15]
	v_mfma_f32_16x16x32_bf16 v[12:15], v[96:99], v[184:187], v[12:15]
	s_setprio 0
	s_barrier
	s_add_i32 s57, 0, 0x18000
	s_add_i32 s58, 0, 0x1c000
	v_add_u32_e32 v116, s57, v229
	v_add_u32_e32 v148, s58, v229
	ds_read_b128 v[96:99], v116
	ds_read_b128 v[100:103], v116 offset:1024
	ds_read_b128 v[104:107], v116 offset:2048
	ds_read_b128 v[116:119], v116 offset:3072
	ds_read_b128 v[120:123], v148
	ds_read_b128 v[124:127], v148 offset:1024
	ds_read_b128 v[136:139], v148 offset:2048
	ds_read_b128 v[148:151], v148 offset:3072
	s_add_u32 s26, s26, 0x40000
	s_addc_u32 s27, s27, 0
	s_mov_b32 m0, s35
	v_lshl_add_u64 v[200:201], s[26:27], 0, v[208:209]
	ds_read_b128 v[160:163], v232 offset:32768
	ds_read_b128 v[164:167], v232 offset:33792
	ds_read_b128 v[168:171], v232 offset:34816
	ds_read_b128 v[172:175], v232 offset:35840
	ds_read_b128 v[176:179], v232 offset:36864
	ds_read_b128 v[180:183], v232 offset:37888
	ds_read_b128 v[184:187], v232 offset:38912
	ds_read_b128 v[188:191], v232 offset:39936
	global_load_lds_dwordx4 v[200:201], off
	v_lshl_add_u64 v[200:201], s[26:27], 0, v[212:213]
	s_mov_b32 m0, s36
	s_nop 0
	global_load_lds_dwordx4 v[200:201], off
	s_waitcnt vmcnt(8)
	s_waitcnt lgkmcnt(0)
	s_barrier
	s_setprio 1
	s_waitcnt lgkmcnt(0)
	v_mfma_f32_16x16x32_bf16 v[156:159], v[96:99], v[160:163], v[156:159]
	v_mfma_f32_16x16x32_bf16 v[156:159], v[100:103], v[164:167], v[156:159]
	v_mfma_f32_16x16x32_bf16 v[152:155], v[116:119], v[164:167], v[152:155]
	v_mfma_f32_16x16x32_bf16 v[152:155], v[104:107], v[160:163], v[152:155]
	v_mfma_f32_16x16x32_bf16 v[144:147], v[120:123], v[160:163], v[144:147]
	v_mfma_f32_16x16x32_bf16 v[144:147], v[124:127], v[164:167], v[144:147]
	v_mfma_f32_16x16x32_bf16 v[140:143], v[148:151], v[164:167], v[140:143]
	v_mfma_f32_16x16x32_bf16 v[140:143], v[136:139], v[160:163], v[140:143]
	v_mfma_f32_16x16x32_bf16 v[108:111], v[136:139], v[168:171], v[108:111]
	v_mfma_f32_16x16x32_bf16 v[108:111], v[148:151], v[172:175], v[108:111]
	v_mfma_f32_16x16x32_bf16 v[112:115], v[124:127], v[172:175], v[112:115]
	v_mfma_f32_16x16x32_bf16 v[112:115], v[120:123], v[168:171], v[112:115]
	v_mfma_f32_16x16x32_bf16 v[128:131], v[104:107], v[168:171], v[128:131]
	v_mfma_f32_16x16x32_bf16 v[128:131], v[116:119], v[172:175], v[128:131]
	v_mfma_f32_16x16x32_bf16 v[132:135], v[100:103], v[172:175], v[132:135]
	v_mfma_f32_16x16x32_bf16 v[132:135], v[96:99], v[168:171], v[132:135]
	v_mfma_f32_16x16x32_bf16 v[92:95], v[96:99], v[176:179], v[92:95]
	v_mfma_f32_16x16x32_bf16 v[92:95], v[100:103], v[180:183], v[92:95]
	v_mfma_f32_16x16x32_bf16 v[88:91], v[116:119], v[180:183], v[88:91]
	v_mfma_f32_16x16x32_bf16 v[88:91], v[104:107], v[176:179], v[88:91]
	v_mfma_f32_16x16x32_bf16 v[84:87], v[120:123], v[176:179], v[84:87]
	v_mfma_f32_16x16x32_bf16 v[84:87], v[124:127], v[180:183], v[84:87]
	v_mfma_f32_16x16x32_bf16 v[80:83], v[148:151], v[180:183], v[80:83]
	v_mfma_f32_16x16x32_bf16 v[80:83], v[136:139], v[176:179], v[80:83]
	v_mfma_f32_16x16x32_bf16 v[64:67], v[136:139], v[184:187], v[64:67]
	v_mfma_f32_16x16x32_bf16 v[64:67], v[148:151], v[188:191], v[64:67]
	v_mfma_f32_16x16x32_bf16 v[68:71], v[124:127], v[188:191], v[68:71]
	v_mfma_f32_16x16x32_bf16 v[68:71], v[120:123], v[184:187], v[68:71]
	v_mfma_f32_16x16x32_bf16 v[72:75], v[104:107], v[184:187], v[72:75]
	v_mfma_f32_16x16x32_bf16 v[72:75], v[116:119], v[188:191], v[72:75]
	v_mfma_f32_16x16x32_bf16 v[76:79], v[100:103], v[188:191], v[76:79]
	v_mfma_f32_16x16x32_bf16 v[76:79], v[96:99], v[184:187], v[76:79]
	s_setprio 0
	s_barrier
; #define PG8_STAGE(bufoff, gbase, voff) do { _Pragma("unroll") for (int _i = 0; _i < 2; ++_i) \
;         __builtin_amdgcn_global_load_lds((const unsigned*)((const char*)(gbase) + (voff)[_i]), (LAS unsigned*)(lds + (bufoff) + ldsw + _i * 8192), 16, 0, 0); } while (0)
; #define PG8_LDA(dst, b, h) do { _Pragma("unroll") for (int m = 0; m < 4; ++m) _Pragma("unroll") for (int k = 0; k < 2; ++k) dst[m][k] = *(const LAS bf16x8*)(lds + PG8_SA(b, h) + aoff + m * 2048 + k * 1024); } while (0)
; #define PG8_MMA(ai, bj, At, Bt) do { __builtin_amdgcn_s_setprio(1); _Pragma("unroll") for (int m = 0; m < 4; ++m) _Pragma("unroll") for (int n = 0; n < 2; ++n) _Pragma("unroll") for (int k = 0; k < 2; ++k) \
;         acc[ai][bj][m][n] = __builtin_amdgcn_mfma_f32_16x16x32_bf16(Bt[n][k], At[m][k], acc[ai][bj][m][n], 0, 0, 0); __builtin_amdgcn_s_setprio(0); } while (0)
; #define PG8_WAIT_V(n) asm volatile("s_waitcnt vmcnt(" #n ")" ::: "memory")
; #define PG8_WAIT_L(n) asm volatile("s_waitcnt lgkmcnt(" #n ")" ::: "memory")
; #define PG8_BAR __builtin_amdgcn_s_barrier()
; #define PG8_SCHED __builtin_amdgcn_sched_barrier(0)
; template <class Epi>
; __device__ __forceinline__ void gemm_phase(LAS unsigned char* lds, const Gemm g, const StaticOrder& S, const Epi& E) {
;     ...
;             PG8_LDA(At, 1, 1); PG8_STAGE(PG8_SB(1, 0), b3, voffB); PG8_STAGE(PG8_SB(1, 1), b3 + hstepB, voffB); PG8_STAGE(PG8_SA(1, 0), a3, voffA);
;             PG8_WAIT_V(8); PG8_WAIT_L(0); PG8_BAR; PG8_MMA(1, 0, At, B0); PG8_MMA(1, 1, At, B1); PG8_BAR; PG8_SCHED;
;         }
	s_add_i32 s26, s57, s30
	v_lshl_add_u64 v[192:193], v[192:193], 0, s[10:11]
	s_mov_b32 m0, s26
	ds_read_b128 v[160:163], v232 offset:49152
	ds_read_b128 v[164:167], v232 offset:50176
	ds_read_b128 v[168:171], v232 offset:51200
	ds_read_b128 v[172:175], v232 offset:52224
	ds_read_b128 v[176:179], v232 offset:53248
	ds_read_b128 v[180:183], v232 offset:54272
	ds_read_b128 v[184:187], v232 offset:55296
	ds_read_b128 v[188:191], v232 offset:56320
	global_load_lds_dwordx4 v[192:193], off
	s_add_i32 m0, s26, 0x2000
	s_add_u32 s24, s24, 0x40080
	v_lshl_add_u64 v[192:193], v[194:195], 0, s[10:11]
	s_addc_u32 s25, s25, 0
	s_add_i32 s26, s58, s30
	global_load_lds_dwordx4 v[192:193], off
	v_lshl_add_u64 v[192:193], s[24:25], 0, v[210:211]
	s_mov_b32 m0, s26
	s_nop 0
	global_load_lds_dwordx4 v[192:193], off
	v_lshl_add_u64 v[192:193], s[24:25], 0, v[214:215]
	s_add_i32 m0, s26, 0x2000
	s_nop 0
	global_load_lds_dwordx4 v[192:193], off
	v_lshl_add_u64 v[192:193], v[196:197], 0, s[10:11]
	s_mov_b32 m0, s40
	s_nop 0
	global_load_lds_dwordx4 v[192:193], off
	v_lshl_add_u64 v[192:193], v[198:199], 0, s[10:11]
	s_mov_b32 m0, s41
	s_nop 0
	global_load_lds_dwordx4 v[192:193], off
	s_waitcnt vmcnt(8)
	s_waitcnt lgkmcnt(0)
	s_barrier
	s_setprio 1
	s_waitcnt lgkmcnt(0)
	v_mfma_f32_16x16x32_bf16 v[60:63], v[96:99], v[160:163], v[60:63]
	v_mfma_f32_16x16x32_bf16 v[60:63], v[100:103], v[164:167], v[60:63]
	v_mfma_f32_16x16x32_bf16 v[56:59], v[116:119], v[164:167], v[56:59]
	v_mfma_f32_16x16x32_bf16 v[56:59], v[104:107], v[160:163], v[56:59]
	v_mfma_f32_16x16x32_bf16 v[52:55], v[120:123], v[160:163], v[52:55]
	v_mfma_f32_16x16x32_bf16 v[52:55], v[124:127], v[164:167], v[52:55]
	v_mfma_f32_16x16x32_bf16 v[48:51], v[148:151], v[164:167], v[48:51]
	v_mfma_f32_16x16x32_bf16 v[48:51], v[136:139], v[160:163], v[48:51]
	v_mfma_f32_16x16x32_bf16 v[32:35], v[136:139], v[168:171], v[32:35]
	v_mfma_f32_16x16x32_bf16 v[32:35], v[148:151], v[172:175], v[32:35]
	v_mfma_f32_16x16x32_bf16 v[36:39], v[124:127], v[172:175], v[36:39]
	v_mfma_f32_16x16x32_bf16 v[36:39], v[120:123], v[168:171], v[36:39]
	v_mfma_f32_16x16x32_bf16 v[40:43], v[104:107], v[168:171], v[40:43]
	v_mfma_f32_16x16x32_bf16 v[40:43], v[116:119], v[172:175], v[40:43]
	v_mfma_f32_16x16x32_bf16 v[44:47], v[100:103], v[172:175], v[44:47]
	v_mfma_f32_16x16x32_bf16 v[44:47], v[96:99], v[168:171], v[44:47]
	v_mfma_f32_16x16x32_bf16 v[28:31], v[96:99], v[176:179], v[28:31]
	v_mfma_f32_16x16x32_bf16 v[28:31], v[100:103], v[180:183], v[28:31]
	v_mfma_f32_16x16x32_bf16 v[24:27], v[116:119], v[180:183], v[24:27]
	v_mfma_f32_16x16x32_bf16 v[24:27], v[104:107], v[176:179], v[24:27]
	v_mfma_f32_16x16x32_bf16 v[20:23], v[120:123], v[176:179], v[20:23]
	v_mfma_f32_16x16x32_bf16 v[20:23], v[124:127], v[180:183], v[20:23]
	v_mfma_f32_16x16x32_bf16 v[16:19], v[148:151], v[180:183], v[16:19]
	v_mfma_f32_16x16x32_bf16 v[16:19], v[136:139], v[176:179], v[16:19]
	v_mfma_f32_16x16x32_bf16 v[0:3], v[136:139], v[184:187], v[0:3]
	v_mfma_f32_16x16x32_bf16 v[0:3], v[148:151], v[188:191], v[0:3]
	v_mfma_f32_16x16x32_bf16 v[4:7], v[124:127], v[188:191], v[4:7]
	v_mfma_f32_16x16x32_bf16 v[4:7], v[120:123], v[184:187], v[4:7]
	v_mfma_f32_16x16x32_bf16 v[8:11], v[104:107], v[184:187], v[8:11]
	v_mfma_f32_16x16x32_bf16 v[8:11], v[116:119], v[188:191], v[8:11]
	v_mfma_f32_16x16x32_bf16 v[12:15], v[100:103], v[188:191], v[12:15]
	v_mfma_f32_16x16x32_bf16 v[12:15], v[96:99], v[184:187], v[12:15]
	s_setprio 0
	s_barrier
	s_add_u32 s4, s4, 0x100
	s_addc_u32 s5, s5, 0
	s_add_u32 s54, s54, 0x100
	s_addc_u32 s55, s55, 0
	s_cmp_ge_i32 s56, s39
	s_mov_b32 s24, s56
	s_cbranch_scc0 .LBB0_912

; #define PG8_STAGE(bufoff, gbase, voff) do { _Pragma("unroll") for (int _i = 0; _i < 2; ++_i) \
;         __builtin_amdgcn_global_load_lds((const unsigned*)((const char*)(gbase) + (voff)[_i]), (LAS unsigned*)(lds + (bufoff) + ldsw + _i * 8192), 16, 0, 0); } while (0)
; #define PG8_LDA(dst, b, h) do { _Pragma("unroll") for (int m = 0; m < 4; ++m) _Pragma("unroll") for (int k = 0; k < 2; ++k) dst[m][k] = *(const LAS bf16x8*)(lds + PG8_SA(b, h) + aoff + m * 2048 + k * 1024); } while (0)
; #define PG8_LDB(dst, b, h) do { _Pragma("unroll") for (int n = 0; n < 2; ++n) _Pragma("unroll") for (int k = 0; k < 2; ++k) dst[n][k] = *(const LAS bf16x8*)(lds + PG8_SB(b, h) + boff + n * 2048 + k * 1024); } while (0)
; #define PG8_MMA(ai, bj, At, Bt) do { __builtin_amdgcn_s_setprio(1); _Pragma("unroll") for (int m = 0; m < 4; ++m) _Pragma("unroll") for (int n = 0; n < 2; ++n) _Pragma("unroll") for (int k = 0; k < 2; ++k) \
;         acc[ai][bj][m][n] = __builtin_amdgcn_mfma_f32_16x16x32_bf16(Bt[n][k], At[m][k], acc[ai][bj][m][n], 0, 0, 0); __builtin_amdgcn_s_setprio(0); } while (0)
; #define PG8_WAIT_V(n) asm volatile("s_waitcnt vmcnt(" #n ")" ::: "memory")
; #define PG8_WAIT_L(n) asm volatile("s_waitcnt lgkmcnt(" #n ")" ::: "memory")
; #define PG8_BAR __builtin_amdgcn_s_barrier()
; #define PG8_SCHED __builtin_amdgcn_sched_barrier(0)
; template <class Epi>
; __device__ __forceinline__ void gemm_phase(LAS unsigned char* lds, const Gemm g, const StaticOrder& S, const Epi& E) {
;     ...
;             PG8_LDB(B0, 0, 0); PG8_LDB(B1, 0, 1); PG8_SCHED; PG8_LDA(At, 0, 0); PG8_STAGE(PG8_SA(1, 1), a1 + hstepA, voffA);
;             PG8_WAIT_V(8); PG8_WAIT_L(0); PG8_BAR; PG8_MMA(0, 0, At, B0); PG8_MMA(0, 1, At, B1); PG8_BAR; PG8_SCHED;
;             PG8_LDA(At, 0, 1); PG8_STAGE(PG8_SB(0, 0), b2, voffB); PG8_STAGE(PG8_SB(0, 1), b2 + hstepB, voffB); PG8_STAGE(PG8_SA(0, 0), a2, voffA);
;             PG8_WAIT_V(8); PG8_WAIT_L(0); PG8_BAR; PG8_MMA(1, 0, At, B0); PG8_MMA(1, 1, At, B1); PG8_BAR; PG8_SCHED;
.LBB0_1046:
	ds_read_b128 v[128:131], v185
	ds_read_b128 v[132:135], v185 offset:1024
	ds_read_b128 v[136:139], v185 offset:2048
	ds_read_b128 v[140:143], v185 offset:3072
	ds_read_b128 v[144:147], v186
	ds_read_b128 v[148:151], v186 offset:1024
	ds_read_b128 v[152:155], v186 offset:2048
	ds_read_b128 v[156:159], v186 offset:3072
	s_add_i32 s73, s46, 2
	s_add_u32 s47, s12, 0xfff80080
	s_addc_u32 s48, s13, -1
	s_cmp_eq_u32 s62, s46
	s_cselect_b32 s46, s41, s71
	s_cselect_b32 s49, s1, s48
	s_cselect_b32 s48, s33, s47
	s_cselect_b32 s47, s39, s72
	v_lshl_add_u64 v[182:183], s[12:13], 0, v[174:175]
	s_add_i32 m0, s5, 0xc000
	ds_read_b128 v[190:193], v187
	ds_read_b128 v[194:197], v187 offset:1024
	ds_read_b128 v[198:201], v187 offset:2048
	ds_read_b128 v[208:211], v187 offset:3072
	ds_read_b128 v[212:215], v187 offset:4096
	ds_read_b128 v[216:219], v187 offset:5120
	ds_read_b128 v[220:223], v187 offset:6144
	ds_read_b128 v[224:227], v187 offset:7168
	global_load_lds_dwordx4 v[182:183], off
	v_lshl_add_u64 v[182:183], s[12:13], 0, v[176:177]
	s_add_i32 m0, s5, 0xe000
	s_nop 0
	global_load_lds_dwordx4 v[182:183], off
	s_waitcnt vmcnt(8)
	s_waitcnt lgkmcnt(0)
	s_barrier
	s_setprio 1
	s_waitcnt lgkmcnt(0)
	v_mfma_f32_16x16x32_bf16 v[120:123], v[128:131], v[190:193], v[120:123]
	v_mfma_f32_16x16x32_bf16 v[120:123], v[132:135], v[194:197], v[120:123]
	v_mfma_f32_16x16x32_bf16 v[124:127], v[140:143], v[194:197], v[124:127]
	v_mfma_f32_16x16x32_bf16 v[124:127], v[136:139], v[190:193], v[124:127]
	v_mfma_f32_16x16x32_bf16 v[116:119], v[144:147], v[190:193], v[116:119]
	v_mfma_f32_16x16x32_bf16 v[116:119], v[148:151], v[194:197], v[116:119]
	v_mfma_f32_16x16x32_bf16 v[112:115], v[156:159], v[194:197], v[112:115]
	v_mfma_f32_16x16x32_bf16 v[112:115], v[152:155], v[190:193], v[112:115]
	v_mfma_f32_16x16x32_bf16 v[96:99], v[152:155], v[198:201], v[96:99]
	v_mfma_f32_16x16x32_bf16 v[96:99], v[156:159], v[208:211], v[96:99]
	v_mfma_f32_16x16x32_bf16 v[100:103], v[148:151], v[208:211], v[100:103]
	v_mfma_f32_16x16x32_bf16 v[100:103], v[144:147], v[198:201], v[100:103]
	v_mfma_f32_16x16x32_bf16 v[104:107], v[136:139], v[198:201], v[104:107]
	v_mfma_f32_16x16x32_bf16 v[104:107], v[140:143], v[208:211], v[104:107]
	v_mfma_f32_16x16x32_bf16 v[108:111], v[132:135], v[208:211], v[108:111]
	v_mfma_f32_16x16x32_bf16 v[108:111], v[128:131], v[198:201], v[108:111]
	v_mfma_f32_16x16x32_bf16 v[92:95], v[128:131], v[212:215], v[92:95]
	v_mfma_f32_16x16x32_bf16 v[92:95], v[132:135], v[216:219], v[92:95]
	v_mfma_f32_16x16x32_bf16 v[88:91], v[140:143], v[216:219], v[88:91]
	v_mfma_f32_16x16x32_bf16 v[88:91], v[136:139], v[212:215], v[88:91]
	v_mfma_f32_16x16x32_bf16 v[84:87], v[144:147], v[212:215], v[84:87]
	v_mfma_f32_16x16x32_bf16 v[84:87], v[148:151], v[216:219], v[84:87]
	v_mfma_f32_16x16x32_bf16 v[80:83], v[156:159], v[216:219], v[80:83]
	v_mfma_f32_16x16x32_bf16 v[80:83], v[152:155], v[212:215], v[80:83]
	v_mfma_f32_16x16x32_bf16 v[64:67], v[152:155], v[220:223], v[64:67]
	v_mfma_f32_16x16x32_bf16 v[64:67], v[156:159], v[224:227], v[64:67]
	v_mfma_f32_16x16x32_bf16 v[68:71], v[148:151], v[224:227], v[68:71]
	v_mfma_f32_16x16x32_bf16 v[68:71], v[144:147], v[220:223], v[68:71]
	v_mfma_f32_16x16x32_bf16 v[72:75], v[136:139], v[220:223], v[72:75]
	v_mfma_f32_16x16x32_bf16 v[72:75], v[140:143], v[224:227], v[72:75]
	v_mfma_f32_16x16x32_bf16 v[76:79], v[132:135], v[224:227], v[76:79]
	v_mfma_f32_16x16x32_bf16 v[76:79], v[128:131], v[220:223], v[76:79]
	s_setprio 0
	s_barrier
	s_add_i32 s76, s65, s54
	v_lshl_add_u64 v[182:183], s[46:47], 0, v[162:163]
	s_mov_b32 m0, s76
	ds_read_b128 v[190:193], v187 offset:16384
	ds_read_b128 v[194:197], v187 offset:17408
	ds_read_b128 v[198:201], v187 offset:18432
	ds_read_b128 v[208:211], v187 offset:19456
	ds_read_b128 v[212:215], v187 offset:20480
	ds_read_b128 v[216:219], v187 offset:21504
	ds_read_b128 v[220:223], v187 offset:22528
	ds_read_b128 v[224:227], v187 offset:23552
	global_load_lds_dwordx4 v[182:183], off
	s_add_i32 m0, s76, 0x2000
	s_add_u32 s76, s46, 0x80000
	v_lshl_add_u64 v[202:203], s[46:47], 0, v[166:167]
	s_addc_u32 s77, s47, 0
	s_add_i32 s78, s66, s54
	global_load_lds_dwordx4 v[202:203], off
	v_lshl_add_u64 v[230:231], s[76:77], 0, v[162:163]
	s_mov_b32 m0, s78
	v_lshl_add_u64 v[232:233], s[48:49], 0, v[164:165]
	global_load_lds_dwordx4 v[230:231], off
	v_lshl_add_u64 v[230:231], s[76:77], 0, v[166:167]
	s_add_i32 m0, s78, 0x2000
	s_nop 0
	global_load_lds_dwordx4 v[230:231], off
	v_lshl_add_u64 v[230:231], s[48:49], 0, v[160:161]
	s_mov_b32 m0, s5
	s_nop 0
	global_load_lds_dwordx4 v[230:231], off
	s_mov_b32 m0, s55
	s_nop 0
	global_load_lds_dwordx4 v[232:233], off
	s_waitcnt vmcnt(8)
	s_waitcnt lgkmcnt(0)
	s_barrier
; #define PG8_STAGE(bufoff, gbase, voff) do { _Pragma("unroll") for (int _i = 0; _i < 2; ++_i) \
;         __builtin_amdgcn_global_load_lds((const unsigned*)((const char*)(gbase) + (voff)[_i]), (LAS unsigned*)(lds + (bufoff) + ldsw + _i * 8192), 16, 0, 0); } while (0)
; #define PG8_LDA(dst, b, h) do { _Pragma("unroll") for (int m = 0; m < 4; ++m) _Pragma("unroll") for (int k = 0; k < 2; ++k) dst[m][k] = *(const LAS bf16x8*)(lds + PG8_SA(b, h) + aoff + m * 2048 + k * 1024); } while (0)
; #define PG8_LDB(dst, b, h) do { _Pragma("unroll") for (int n = 0; n < 2; ++n) _Pragma("unroll") for (int k = 0; k < 2; ++k) dst[n][k] = *(const LAS bf16x8*)(lds + PG8_SB(b, h) + boff + n * 2048 + k * 1024); } while (0)
; #define PG8_MMA(ai, bj, At, Bt) do { __builtin_amdgcn_s_setprio(1); _Pragma("unroll") for (int m = 0; m < 4; ++m) _Pragma("unroll") for (int n = 0; n < 2; ++n) _Pragma("unroll") for (int k = 0; k < 2; ++k) \
;         acc[ai][bj][m][n] = __builtin_amdgcn_mfma_f32_16x16x32_bf16(Bt[n][k], At[m][k], acc[ai][bj][m][n], 0, 0, 0); __builtin_amdgcn_s_setprio(0); } while (0)
; #define PG8_WAIT_V(n) asm volatile("s_waitcnt vmcnt(" #n ")" ::: "memory")
; #define PG8_WAIT_L(n) asm volatile("s_waitcnt lgkmcnt(" #n ")" ::: "memory")
; #define PG8_BAR __builtin_amdgcn_s_barrier()
; #define PG8_SCHED __builtin_amdgcn_sched_barrier(0)
; template <class Epi>
; __device__ __forceinline__ void gemm_phase(LAS unsigned char* lds, const Gemm g, const StaticOrder& S, const Epi& E) {
;     ...
;             PG8_WAIT_V(8); PG8_WAIT_L(0); PG8_BAR; PG8_MMA(1, 0, At, B0); PG8_MMA(1, 1, At, B1); PG8_BAR; PG8_SCHED;
;             PG8_LDB(B0, 1, 0); PG8_LDB(B1, 1, 1); PG8_SCHED; PG8_LDA(At, 1, 0); PG8_STAGE(PG8_SA(0, 1), a2 + hstepA, voffA);
;             PG8_WAIT_V(8); PG8_WAIT_L(0); PG8_BAR; PG8_MMA(0, 0, At, B0); PG8_MMA(0, 1, At, B1); PG8_BAR; PG8_SCHED;
	s_setprio 1
	s_waitcnt lgkmcnt(0)
	v_mfma_f32_16x16x32_bf16 v[60:63], v[128:131], v[190:193], v[60:63]
	v_mfma_f32_16x16x32_bf16 v[60:63], v[132:135], v[194:197], v[60:63]
	v_mfma_f32_16x16x32_bf16 v[56:59], v[140:143], v[194:197], v[56:59]
	v_mfma_f32_16x16x32_bf16 v[56:59], v[136:139], v[190:193], v[56:59]
	v_mfma_f32_16x16x32_bf16 v[52:55], v[144:147], v[190:193], v[52:55]
	v_mfma_f32_16x16x32_bf16 v[52:55], v[148:151], v[194:197], v[52:55]
	v_mfma_f32_16x16x32_bf16 v[48:51], v[156:159], v[194:197], v[48:51]
	v_mfma_f32_16x16x32_bf16 v[48:51], v[152:155], v[190:193], v[48:51]
	v_mfma_f32_16x16x32_bf16 v[32:35], v[152:155], v[198:201], v[32:35]
	v_mfma_f32_16x16x32_bf16 v[32:35], v[156:159], v[208:211], v[32:35]
	v_mfma_f32_16x16x32_bf16 v[36:39], v[148:151], v[208:211], v[36:39]
	v_mfma_f32_16x16x32_bf16 v[36:39], v[144:147], v[198:201], v[36:39]
	v_mfma_f32_16x16x32_bf16 v[40:43], v[136:139], v[198:201], v[40:43]
	v_mfma_f32_16x16x32_bf16 v[40:43], v[140:143], v[208:211], v[40:43]
	v_mfma_f32_16x16x32_bf16 v[44:47], v[132:135], v[208:211], v[44:47]
	v_mfma_f32_16x16x32_bf16 v[44:47], v[128:131], v[198:201], v[44:47]
	v_mfma_f32_16x16x32_bf16 v[28:31], v[128:131], v[212:215], v[28:31]
	v_mfma_f32_16x16x32_bf16 v[28:31], v[132:135], v[216:219], v[28:31]
	v_mfma_f32_16x16x32_bf16 v[24:27], v[140:143], v[216:219], v[24:27]
	v_mfma_f32_16x16x32_bf16 v[24:27], v[136:139], v[212:215], v[24:27]
	v_mfma_f32_16x16x32_bf16 v[20:23], v[144:147], v[212:215], v[20:23]
	v_mfma_f32_16x16x32_bf16 v[20:23], v[148:151], v[216:219], v[20:23]
	v_mfma_f32_16x16x32_bf16 v[16:19], v[156:159], v[216:219], v[16:19]
	v_mfma_f32_16x16x32_bf16 v[16:19], v[152:155], v[212:215], v[16:19]
	v_mfma_f32_16x16x32_bf16 v[0:3], v[152:155], v[220:223], v[0:3]
	v_mfma_f32_16x16x32_bf16 v[0:3], v[156:159], v[224:227], v[0:3]
	v_mfma_f32_16x16x32_bf16 v[4:7], v[148:151], v[224:227], v[4:7]
	v_mfma_f32_16x16x32_bf16 v[4:7], v[144:147], v[220:223], v[4:7]
	v_mfma_f32_16x16x32_bf16 v[8:11], v[136:139], v[220:223], v[8:11]
	v_mfma_f32_16x16x32_bf16 v[8:11], v[140:143], v[224:227], v[8:11]
	v_mfma_f32_16x16x32_bf16 v[12:15], v[132:135], v[224:227], v[12:15]
	v_mfma_f32_16x16x32_bf16 v[12:15], v[128:131], v[220:223], v[12:15]
	s_setprio 0
	s_barrier
	s_add_i32 s76, 0, 0x18000
	s_add_i32 s77, 0, 0x1c000
	v_add_u32_e32 v140, s76, v184
	v_add_u32_e32 v156, s77, v184
	ds_read_b128 v[128:131], v140
	ds_read_b128 v[132:135], v140 offset:1024
	ds_read_b128 v[136:139], v140 offset:2048
	ds_read_b128 v[140:143], v140 offset:3072
	ds_read_b128 v[144:147], v156
	ds_read_b128 v[148:151], v156 offset:1024
	ds_read_b128 v[152:155], v156 offset:2048
	ds_read_b128 v[156:159], v156 offset:3072
	s_add_u32 s48, s48, 0x80000
	s_addc_u32 s49, s49, 0
	s_mov_b32 m0, s56
	v_lshl_add_u64 v[234:235], s[48:49], 0, v[160:161]
	ds_read_b128 v[190:193], v187 offset:32768
	ds_read_b128 v[194:197], v187 offset:33792
	ds_read_b128 v[198:201], v187 offset:34816
	ds_read_b128 v[208:211], v187 offset:35840
	ds_read_b128 v[212:215], v187 offset:36864
	ds_read_b128 v[216:219], v187 offset:37888
	ds_read_b128 v[220:223], v187 offset:38912
	ds_read_b128 v[224:227], v187 offset:39936
	global_load_lds_dwordx4 v[234:235], off
	v_lshl_add_u64 v[234:235], s[48:49], 0, v[164:165]
	s_mov_b32 m0, s57
	s_nop 0
	global_load_lds_dwordx4 v[234:235], off
	s_waitcnt vmcnt(8)
	s_waitcnt lgkmcnt(0)
	s_barrier
	s_setprio 1
	s_waitcnt lgkmcnt(0)
	v_mfma_f32_16x16x32_bf16 v[120:123], v[128:131], v[190:193], v[120:123]
	v_mfma_f32_16x16x32_bf16 v[120:123], v[132:135], v[194:197], v[120:123]
	v_mfma_f32_16x16x32_bf16 v[124:127], v[140:143], v[194:197], v[124:127]
	v_mfma_f32_16x16x32_bf16 v[124:127], v[136:139], v[190:193], v[124:127]
	v_mfma_f32_16x16x32_bf16 v[116:119], v[144:147], v[190:193], v[116:119]
	v_mfma_f32_16x16x32_bf16 v[116:119], v[148:151], v[194:197], v[116:119]
	v_mfma_f32_16x16x32_bf16 v[112:115], v[156:159], v[194:197], v[112:115]
	v_mfma_f32_16x16x32_bf16 v[112:115], v[152:155], v[190:193], v[112:115]
	v_mfma_f32_16x16x32_bf16 v[96:99], v[152:155], v[198:201], v[96:99]
	v_mfma_f32_16x16x32_bf16 v[96:99], v[156:159], v[208:211], v[96:99]
	v_mfma_f32_16x16x32_bf16 v[100:103], v[148:151], v[208:211], v[100:103]
	v_mfma_f32_16x16x32_bf16 v[100:103], v[144:147], v[198:201], v[100:103]
	v_mfma_f32_16x16x32_bf16 v[104:107], v[136:139], v[198:201], v[104:107]
	v_mfma_f32_16x16x32_bf16 v[104:107], v[140:143], v[208:211], v[104:107]
	v_mfma_f32_16x16x32_bf16 v[108:111], v[132:135], v[208:211], v[108:111]
	v_mfma_f32_16x16x32_bf16 v[108:111], v[128:131], v[198:201], v[108:111]
	v_mfma_f32_16x16x32_bf16 v[92:95], v[128:131], v[212:215], v[92:95]
	v_mfma_f32_16x16x32_bf16 v[92:95], v[132:135], v[216:219], v[92:95]
	v_mfma_f32_16x16x32_bf16 v[88:91], v[140:143], v[216:219], v[88:91]
	v_mfma_f32_16x16x32_bf16 v[88:91], v[136:139], v[212:215], v[88:91]
	v_mfma_f32_16x16x32_bf16 v[84:87], v[144:147], v[212:215], v[84:87]
	v_mfma_f32_16x16x32_bf16 v[84:87], v[148:151], v[216:219], v[84:87]
	v_mfma_f32_16x16x32_bf16 v[80:83], v[156:159], v[216:219], v[80:83]
	v_mfma_f32_16x16x32_bf16 v[80:83], v[152:155], v[212:215], v[80:83]
	v_mfma_f32_16x16x32_bf16 v[64:67], v[152:155], v[220:223], v[64:67]
	v_mfma_f32_16x16x32_bf16 v[64:67], v[156:159], v[224:227], v[64:67]
	v_mfma_f32_16x16x32_bf16 v[68:71], v[148:151], v[224:227], v[68:71]
	v_mfma_f32_16x16x32_bf16 v[68:71], v[144:147], v[220:223], v[68:71]
	v_mfma_f32_16x16x32_bf16 v[72:75], v[136:139], v[220:223], v[72:75]
	v_mfma_f32_16x16x32_bf16 v[72:75], v[140:143], v[224:227], v[72:75]
	v_mfma_f32_16x16x32_bf16 v[76:79], v[132:135], v[224:227], v[76:79]
	v_mfma_f32_16x16x32_bf16 v[76:79], v[128:131], v[220:223], v[76:79]
	s_setprio 0
	s_barrier
; #define PG8_STAGE(bufoff, gbase, voff) do { _Pragma("unroll") for (int _i = 0; _i < 2; ++_i) \
;         __builtin_amdgcn_global_load_lds((const unsigned*)((const char*)(gbase) + (voff)[_i]), (LAS unsigned*)(lds + (bufoff) + ldsw + _i * 8192), 16, 0, 0); } while (0)
; #define PG8_LDA(dst, b, h) do { _Pragma("unroll") for (int m = 0; m < 4; ++m) _Pragma("unroll") for (int k = 0; k < 2; ++k) dst[m][k] = *(const LAS bf16x8*)(lds + PG8_SA(b, h) + aoff + m * 2048 + k * 1024); } while (0)
; #define PG8_MMA(ai, bj, At, Bt) do { __builtin_amdgcn_s_setprio(1); _Pragma("unroll") for (int m = 0; m < 4; ++m) _Pragma("unroll") for (int n = 0; n < 2; ++n) _Pragma("unroll") for (int k = 0; k < 2; ++k) \
;         acc[ai][bj][m][n] = __builtin_amdgcn_mfma_f32_16x16x32_bf16(Bt[n][k], At[m][k], acc[ai][bj][m][n], 0, 0, 0); __builtin_amdgcn_s_setprio(0); } while (0)
; #define PG8_WAIT_V(n) asm volatile("s_waitcnt vmcnt(" #n ")" ::: "memory")
; #define PG8_WAIT_L(n) asm volatile("s_waitcnt lgkmcnt(" #n ")" ::: "memory")
; #define PG8_BAR __builtin_amdgcn_s_barrier()
; #define PG8_SCHED __builtin_amdgcn_sched_barrier(0)
; template <class Epi>
; __device__ __forceinline__ void gemm_phase(LAS unsigned char* lds, const Gemm g, const StaticOrder& S, const Epi& E) {
;     ...
;             PG8_LDA(At, 1, 1); PG8_STAGE(PG8_SB(1, 0), b3, voffB); PG8_STAGE(PG8_SB(1, 1), b3 + hstepB, voffB); PG8_STAGE(PG8_SA(1, 0), a3, voffA);
;             PG8_WAIT_V(8); PG8_WAIT_L(0); PG8_BAR; PG8_MMA(1, 0, At, B0); PG8_MMA(1, 1, At, B1); PG8_BAR; PG8_SCHED;
;         }
	s_add_i32 s48, s76, s54
	v_lshl_add_u64 v[182:183], v[182:183], 0, s[16:17]
	s_mov_b32 m0, s48
	ds_read_b128 v[190:193], v187 offset:49152
	ds_read_b128 v[194:197], v187 offset:50176
	ds_read_b128 v[198:201], v187 offset:51200
	ds_read_b128 v[208:211], v187 offset:52224
	ds_read_b128 v[212:215], v187 offset:53248
	ds_read_b128 v[216:219], v187 offset:54272
	ds_read_b128 v[220:223], v187 offset:55296
	ds_read_b128 v[224:227], v187 offset:56320
	global_load_lds_dwordx4 v[182:183], off
	s_add_i32 m0, s48, 0x2000
	s_add_u32 s46, s46, 0x80080
	v_lshl_add_u64 v[182:183], v[202:203], 0, s[16:17]
	s_addc_u32 s47, s47, 0
	s_add_i32 s48, s77, s54
	global_load_lds_dwordx4 v[182:183], off
	v_lshl_add_u64 v[182:183], s[46:47], 0, v[162:163]
	s_mov_b32 m0, s48
	s_nop 0
	global_load_lds_dwordx4 v[182:183], off
	v_lshl_add_u64 v[182:183], s[46:47], 0, v[166:167]
	s_add_i32 m0, s48, 0x2000
	s_nop 0
	global_load_lds_dwordx4 v[182:183], off
	v_lshl_add_u64 v[182:183], v[230:231], 0, s[16:17]
	s_mov_b32 m0, s60
	s_nop 0
	global_load_lds_dwordx4 v[182:183], off
	v_lshl_add_u64 v[182:183], v[232:233], 0, s[16:17]
	s_mov_b32 m0, s61
	s_nop 0
	global_load_lds_dwordx4 v[182:183], off
	s_waitcnt vmcnt(8)
	s_waitcnt lgkmcnt(0)
	s_barrier
	s_setprio 1
	s_waitcnt lgkmcnt(0)
	v_mfma_f32_16x16x32_bf16 v[60:63], v[128:131], v[190:193], v[60:63]
	v_mfma_f32_16x16x32_bf16 v[60:63], v[132:135], v[194:197], v[60:63]
	v_mfma_f32_16x16x32_bf16 v[56:59], v[140:143], v[194:197], v[56:59]
	v_mfma_f32_16x16x32_bf16 v[56:59], v[136:139], v[190:193], v[56:59]
	v_mfma_f32_16x16x32_bf16 v[52:55], v[144:147], v[190:193], v[52:55]
	v_mfma_f32_16x16x32_bf16 v[52:55], v[148:151], v[194:197], v[52:55]
	v_mfma_f32_16x16x32_bf16 v[48:51], v[156:159], v[194:197], v[48:51]
	v_mfma_f32_16x16x32_bf16 v[48:51], v[152:155], v[190:193], v[48:51]
	v_mfma_f32_16x16x32_bf16 v[32:35], v[152:155], v[198:201], v[32:35]
	v_mfma_f32_16x16x32_bf16 v[32:35], v[156:159], v[208:211], v[32:35]
	v_mfma_f32_16x16x32_bf16 v[36:39], v[148:151], v[208:211], v[36:39]
	v_mfma_f32_16x16x32_bf16 v[36:39], v[144:147], v[198:201], v[36:39]
	v_mfma_f32_16x16x32_bf16 v[40:43], v[136:139], v[198:201], v[40:43]
	v_mfma_f32_16x16x32_bf16 v[40:43], v[140:143], v[208:211], v[40:43]
	v_mfma_f32_16x16x32_bf16 v[44:47], v[132:135], v[208:211], v[44:47]
	v_mfma_f32_16x16x32_bf16 v[44:47], v[128:131], v[198:201], v[44:47]
	v_mfma_f32_16x16x32_bf16 v[28:31], v[128:131], v[212:215], v[28:31]
	v_mfma_f32_16x16x32_bf16 v[28:31], v[132:135], v[216:219], v[28:31]
	v_mfma_f32_16x16x32_bf16 v[24:27], v[140:143], v[216:219], v[24:27]
	v_mfma_f32_16x16x32_bf16 v[24:27], v[136:139], v[212:215], v[24:27]
	v_mfma_f32_16x16x32_bf16 v[20:23], v[144:147], v[212:215], v[20:23]
	v_mfma_f32_16x16x32_bf16 v[20:23], v[148:151], v[216:219], v[20:23]
	v_mfma_f32_16x16x32_bf16 v[16:19], v[156:159], v[216:219], v[16:19]
	v_mfma_f32_16x16x32_bf16 v[16:19], v[152:155], v[212:215], v[16:19]
	v_mfma_f32_16x16x32_bf16 v[0:3], v[152:155], v[220:223], v[0:3]
	v_mfma_f32_16x16x32_bf16 v[0:3], v[156:159], v[224:227], v[0:3]
	v_mfma_f32_16x16x32_bf16 v[4:7], v[148:151], v[224:227], v[4:7]
	v_mfma_f32_16x16x32_bf16 v[4:7], v[144:147], v[220:223], v[4:7]
	v_mfma_f32_16x16x32_bf16 v[8:11], v[136:139], v[220:223], v[8:11]
	v_mfma_f32_16x16x32_bf16 v[8:11], v[140:143], v[224:227], v[8:11]
	v_mfma_f32_16x16x32_bf16 v[12:15], v[132:135], v[224:227], v[12:15]
	v_mfma_f32_16x16x32_bf16 v[12:15], v[128:131], v[220:223], v[12:15]
	s_setprio 0
	s_barrier
	s_add_u32 s12, s12, 0x100
	s_addc_u32 s13, s13, 0
	s_add_u32 s71, s71, 0x100
	s_addc_u32 s72, s72, 0
	s_cmp_ge_i32 s73, s59
	s_mov_b32 s46, s73
	s_cbranch_scc0 .LBB0_1046

; #define PG8_STAGE(bufoff, gbase, voff) do { _Pragma("unroll") for (int _i = 0; _i < 2; ++_i) \
;         __builtin_amdgcn_global_load_lds((const unsigned*)((const char*)(gbase) + (voff)[_i]), (LAS unsigned*)(lds + (bufoff) + ldsw + _i * 8192), 16, 0, 0); } while (0)
; #define PG8_LDA(dst, b, h) do { _Pragma("unroll") for (int m = 0; m < 4; ++m) _Pragma("unroll") for (int k = 0; k < 2; ++k) dst[m][k] = *(const LAS bf16x8*)(lds + PG8_SA(b, h) + aoff + m * 2048 + k * 1024); } while (0)
; #define PG8_LDB(dst, b, h) do { _Pragma("unroll") for (int n = 0; n < 2; ++n) _Pragma("unroll") for (int k = 0; k < 2; ++k) dst[n][k] = *(const LAS bf16x8*)(lds + PG8_SB(b, h) + boff + n * 2048 + k * 1024); } while (0)
; #define PG8_MMA(ai, bj, At, Bt) do { __builtin_amdgcn_s_setprio(1); _Pragma("unroll") for (int m = 0; m < 4; ++m) _Pragma("unroll") for (int n = 0; n < 2; ++n) _Pragma("unroll") for (int k = 0; k < 2; ++k) \
;         acc[ai][bj][m][n] = __builtin_amdgcn_mfma_f32_16x16x32_bf16(Bt[n][k], At[m][k], acc[ai][bj][m][n], 0, 0, 0); __builtin_amdgcn_s_setprio(0); } while (0)
; #define PG8_WAIT_V(n) asm volatile("s_waitcnt vmcnt(" #n ")" ::: "memory")
; #define PG8_WAIT_L(n) asm volatile("s_waitcnt lgkmcnt(" #n ")" ::: "memory")
; #define PG8_BAR __builtin_amdgcn_s_barrier()
; #define PG8_SCHED __builtin_amdgcn_sched_barrier(0)
; template <class Epi>
; __device__ __forceinline__ void gemm_phase(LAS unsigned char* lds, const Gemm g, const StaticOrder& S, const Epi& E) {
;     ...
;             PG8_LDB(B0, 0, 0); PG8_LDB(B1, 0, 1); PG8_SCHED; PG8_LDA(At, 0, 0); PG8_STAGE(PG8_SA(1, 1), a1 + hstepA, voffA);
;             PG8_WAIT_V(8); PG8_WAIT_L(0); PG8_BAR; PG8_MMA(0, 0, At, B0); PG8_MMA(0, 1, At, B1); PG8_BAR; PG8_SCHED;
;             PG8_LDA(At, 0, 1); PG8_STAGE(PG8_SB(0, 0), b2, voffB); PG8_STAGE(PG8_SB(0, 1), b2 + hstepB, voffB); PG8_STAGE(PG8_SA(0, 0), a2, voffA);
;             PG8_WAIT_V(8); PG8_WAIT_L(0); PG8_BAR; PG8_MMA(1, 0, At, B0); PG8_MMA(1, 1, At, B1); PG8_BAR; PG8_SCHED;
.LBB0_1131:
	ds_read_b128 v[164:167], v182
	ds_read_b128 v[168:171], v182 offset:1024
	ds_read_b128 v[172:175], v182 offset:2048
	ds_read_b128 v[176:179], v182 offset:3072
	ds_read_b128 v[186:189], v183
	ds_read_b128 v[190:193], v183 offset:1024
	ds_read_b128 v[194:197], v183 offset:2048
	ds_read_b128 v[198:201], v183 offset:3072
	s_add_i32 s22, s12, 2
	s_add_u32 s13, s10, 0xfff80080
	s_addc_u32 s14, s11, -1
	s_cmp_eq_u32 s58, s12
	s_cselect_b32 s12, s19, s20
	s_cselect_b32 s15, s16, s14
	s_cselect_b32 s14, s17, s13
	s_cselect_b32 s13, s18, s21
	v_lshl_add_u64 v[202:203], s[10:11], 0, v[140:141]
	s_add_i32 m0, s33, 0xc000
	ds_read_b128 v[208:211], v184
	ds_read_b128 v[212:215], v184 offset:1024
	ds_read_b128 v[216:219], v184 offset:2048
	ds_read_b128 v[220:223], v184 offset:3072
	ds_read_b128 v[224:227], v184 offset:4096
	ds_read_b128 v[230:233], v184 offset:5120
	ds_read_b128 v[234:237], v184 offset:6144
	ds_read_b128 v[238:241], v184 offset:7168
	global_load_lds_dwordx4 v[202:203], off
	v_lshl_add_u64 v[202:203], s[10:11], 0, v[142:143]
	s_add_i32 m0, s33, 0xe000
	s_nop 0
	global_load_lds_dwordx4 v[202:203], off
	s_waitcnt vmcnt(8)
	s_waitcnt lgkmcnt(0)
	s_barrier
	s_setprio 1
	s_waitcnt lgkmcnt(0)
	v_mfma_f32_16x16x32_bf16 v[120:123], v[164:167], v[208:211], v[120:123]
	v_mfma_f32_16x16x32_bf16 v[120:123], v[168:171], v[212:215], v[120:123]
	v_mfma_f32_16x16x32_bf16 v[116:119], v[176:179], v[212:215], v[116:119]
	v_mfma_f32_16x16x32_bf16 v[116:119], v[172:175], v[208:211], v[116:119]
	v_mfma_f32_16x16x32_bf16 v[124:127], v[186:189], v[208:211], v[124:127]
	v_mfma_f32_16x16x32_bf16 v[124:127], v[190:193], v[212:215], v[124:127]
	v_mfma_f32_16x16x32_bf16 v[112:115], v[198:201], v[212:215], v[112:115]
	v_mfma_f32_16x16x32_bf16 v[112:115], v[194:197], v[208:211], v[112:115]
	v_mfma_f32_16x16x32_bf16 v[96:99], v[194:197], v[216:219], v[96:99]
	v_mfma_f32_16x16x32_bf16 v[96:99], v[198:201], v[220:223], v[96:99]
	v_mfma_f32_16x16x32_bf16 v[104:107], v[190:193], v[220:223], v[104:107]
	v_mfma_f32_16x16x32_bf16 v[104:107], v[186:189], v[216:219], v[104:107]
	v_mfma_f32_16x16x32_bf16 v[100:103], v[172:175], v[216:219], v[100:103]
	v_mfma_f32_16x16x32_bf16 v[100:103], v[176:179], v[220:223], v[100:103]
	v_mfma_f32_16x16x32_bf16 v[108:111], v[168:171], v[220:223], v[108:111]
	v_mfma_f32_16x16x32_bf16 v[108:111], v[164:167], v[216:219], v[108:111]
	v_mfma_f32_16x16x32_bf16 v[92:95], v[164:167], v[224:227], v[92:95]
	v_mfma_f32_16x16x32_bf16 v[92:95], v[168:171], v[230:233], v[92:95]
	v_mfma_f32_16x16x32_bf16 v[84:87], v[176:179], v[230:233], v[84:87]
	v_mfma_f32_16x16x32_bf16 v[84:87], v[172:175], v[224:227], v[84:87]
	v_mfma_f32_16x16x32_bf16 v[88:91], v[186:189], v[224:227], v[88:91]
	v_mfma_f32_16x16x32_bf16 v[88:91], v[190:193], v[230:233], v[88:91]
	v_mfma_f32_16x16x32_bf16 v[80:83], v[198:201], v[230:233], v[80:83]
	v_mfma_f32_16x16x32_bf16 v[80:83], v[194:197], v[224:227], v[80:83]
	v_mfma_f32_16x16x32_bf16 v[64:67], v[194:197], v[234:237], v[64:67]
	v_mfma_f32_16x16x32_bf16 v[64:67], v[198:201], v[238:241], v[64:67]
	v_mfma_f32_16x16x32_bf16 v[72:75], v[190:193], v[238:241], v[72:75]
	v_mfma_f32_16x16x32_bf16 v[72:75], v[186:189], v[234:237], v[72:75]
	v_mfma_f32_16x16x32_bf16 v[68:71], v[172:175], v[234:237], v[68:71]
	v_mfma_f32_16x16x32_bf16 v[68:71], v[176:179], v[238:241], v[68:71]
	v_mfma_f32_16x16x32_bf16 v[76:79], v[168:171], v[238:241], v[76:79]
	v_mfma_f32_16x16x32_bf16 v[76:79], v[164:167], v[234:237], v[76:79]
	s_setprio 0
	s_barrier
	s_add_i32 s23, s62, s37
	v_lshl_add_u64 v[202:203], s[12:13], 0, v[132:133]
	s_mov_b32 m0, s23
	ds_read_b128 v[208:211], v184 offset:16384
	ds_read_b128 v[212:215], v184 offset:17408
	ds_read_b128 v[216:219], v184 offset:18432
	ds_read_b128 v[220:223], v184 offset:19456
	ds_read_b128 v[224:227], v184 offset:20480
	ds_read_b128 v[230:233], v184 offset:21504
	ds_read_b128 v[234:237], v184 offset:22528
	ds_read_b128 v[238:241], v184 offset:23552
	global_load_lds_dwordx4 v[202:203], off
	s_add_i32 m0, s23, 0x2000
	s_add_u32 s50, s12, 0x80000
	v_lshl_add_u64 v[242:243], s[12:13], 0, v[128:129]
	s_addc_u32 s51, s13, 0
	s_add_i32 s23, s63, s37
	global_load_lds_dwordx4 v[242:243], off
	v_lshl_add_u64 v[244:245], s[50:51], 0, v[132:133]
	s_mov_b32 m0, s23
	v_lshl_add_u64 v[246:247], s[14:15], 0, v[130:131]
	global_load_lds_dwordx4 v[244:245], off
	v_lshl_add_u64 v[244:245], s[50:51], 0, v[128:129]
	s_add_i32 m0, s23, 0x2000
	s_nop 0
	global_load_lds_dwordx4 v[244:245], off
	v_lshl_add_u64 v[244:245], s[14:15], 0, v[134:135]
	s_mov_b32 m0, s33
	s_nop 0
	global_load_lds_dwordx4 v[244:245], off
	s_mov_b32 m0, s52
	s_nop 0
	global_load_lds_dwordx4 v[246:247], off
	s_waitcnt vmcnt(8)
	s_waitcnt lgkmcnt(0)
	s_barrier
; #define PG8_STAGE(bufoff, gbase, voff) do { _Pragma("unroll") for (int _i = 0; _i < 2; ++_i) \
;         __builtin_amdgcn_global_load_lds((const unsigned*)((const char*)(gbase) + (voff)[_i]), (LAS unsigned*)(lds + (bufoff) + ldsw + _i * 8192), 16, 0, 0); } while (0)
; #define PG8_LDA(dst, b, h) do { _Pragma("unroll") for (int m = 0; m < 4; ++m) _Pragma("unroll") for (int k = 0; k < 2; ++k) dst[m][k] = *(const LAS bf16x8*)(lds + PG8_SA(b, h) + aoff + m * 2048 + k * 1024); } while (0)
; #define PG8_LDB(dst, b, h) do { _Pragma("unroll") for (int n = 0; n < 2; ++n) _Pragma("unroll") for (int k = 0; k < 2; ++k) dst[n][k] = *(const LAS bf16x8*)(lds + PG8_SB(b, h) + boff + n * 2048 + k * 1024); } while (0)
; #define PG8_MMA(ai, bj, At, Bt) do { __builtin_amdgcn_s_setprio(1); _Pragma("unroll") for (int m = 0; m < 4; ++m) _Pragma("unroll") for (int n = 0; n < 2; ++n) _Pragma("unroll") for (int k = 0; k < 2; ++k) \
;         acc[ai][bj][m][n] = __builtin_amdgcn_mfma_f32_16x16x32_bf16(Bt[n][k], At[m][k], acc[ai][bj][m][n], 0, 0, 0); __builtin_amdgcn_s_setprio(0); } while (0)
; #define PG8_WAIT_V(n) asm volatile("s_waitcnt vmcnt(" #n ")" ::: "memory")
; #define PG8_WAIT_L(n) asm volatile("s_waitcnt lgkmcnt(" #n ")" ::: "memory")
; #define PG8_BAR __builtin_amdgcn_s_barrier()
; #define PG8_SCHED __builtin_amdgcn_sched_barrier(0)
; template <class Epi>
; __device__ __forceinline__ void gemm_phase(LAS unsigned char* lds, const Gemm g, const StaticOrder& S, const Epi& E) {
;     ...
;             PG8_WAIT_V(8); PG8_WAIT_L(0); PG8_BAR; PG8_MMA(1, 0, At, B0); PG8_MMA(1, 1, At, B1); PG8_BAR; PG8_SCHED;
;             PG8_LDB(B0, 1, 0); PG8_LDB(B1, 1, 1); PG8_SCHED; PG8_LDA(At, 1, 0); PG8_STAGE(PG8_SA(0, 1), a2 + hstepA, voffA);
;             PG8_WAIT_V(8); PG8_WAIT_L(0); PG8_BAR; PG8_MMA(0, 0, At, B0); PG8_MMA(0, 1, At, B1); PG8_BAR; PG8_SCHED;
	s_setprio 1
	s_waitcnt lgkmcnt(0)
	v_mfma_f32_16x16x32_bf16 v[60:63], v[164:167], v[208:211], v[60:63]
	v_mfma_f32_16x16x32_bf16 v[60:63], v[168:171], v[212:215], v[60:63]
	v_mfma_f32_16x16x32_bf16 v[52:55], v[176:179], v[212:215], v[52:55]
	v_mfma_f32_16x16x32_bf16 v[52:55], v[172:175], v[208:211], v[52:55]
	v_mfma_f32_16x16x32_bf16 v[56:59], v[186:189], v[208:211], v[56:59]
	v_mfma_f32_16x16x32_bf16 v[56:59], v[190:193], v[212:215], v[56:59]
	v_mfma_f32_16x16x32_bf16 v[48:51], v[198:201], v[212:215], v[48:51]
	v_mfma_f32_16x16x32_bf16 v[48:51], v[194:197], v[208:211], v[48:51]
	v_mfma_f32_16x16x32_bf16 v[32:35], v[194:197], v[216:219], v[32:35]
	v_mfma_f32_16x16x32_bf16 v[32:35], v[198:201], v[220:223], v[32:35]
	v_mfma_f32_16x16x32_bf16 v[40:43], v[190:193], v[220:223], v[40:43]
	v_mfma_f32_16x16x32_bf16 v[40:43], v[186:189], v[216:219], v[40:43]
	v_mfma_f32_16x16x32_bf16 v[36:39], v[172:175], v[216:219], v[36:39]
	v_mfma_f32_16x16x32_bf16 v[36:39], v[176:179], v[220:223], v[36:39]
	v_mfma_f32_16x16x32_bf16 v[44:47], v[168:171], v[220:223], v[44:47]
	v_mfma_f32_16x16x32_bf16 v[44:47], v[164:167], v[216:219], v[44:47]
	v_mfma_f32_16x16x32_bf16 v[28:31], v[164:167], v[224:227], v[28:31]
	v_mfma_f32_16x16x32_bf16 v[28:31], v[168:171], v[230:233], v[28:31]
	v_mfma_f32_16x16x32_bf16 v[20:23], v[176:179], v[230:233], v[20:23]
	v_mfma_f32_16x16x32_bf16 v[20:23], v[172:175], v[224:227], v[20:23]
	v_mfma_f32_16x16x32_bf16 v[24:27], v[186:189], v[224:227], v[24:27]
	v_mfma_f32_16x16x32_bf16 v[24:27], v[190:193], v[230:233], v[24:27]
	v_mfma_f32_16x16x32_bf16 v[16:19], v[198:201], v[230:233], v[16:19]
	v_mfma_f32_16x16x32_bf16 v[16:19], v[194:197], v[224:227], v[16:19]
	v_mfma_f32_16x16x32_bf16 v[0:3], v[194:197], v[234:237], v[0:3]
	v_mfma_f32_16x16x32_bf16 v[0:3], v[198:201], v[238:241], v[0:3]
	v_mfma_f32_16x16x32_bf16 v[8:11], v[190:193], v[238:241], v[8:11]
	v_mfma_f32_16x16x32_bf16 v[8:11], v[186:189], v[234:237], v[8:11]
	v_mfma_f32_16x16x32_bf16 v[4:7], v[172:175], v[234:237], v[4:7]
	v_mfma_f32_16x16x32_bf16 v[4:7], v[176:179], v[238:241], v[4:7]
	v_mfma_f32_16x16x32_bf16 v[12:15], v[168:171], v[238:241], v[12:15]
	v_mfma_f32_16x16x32_bf16 v[12:15], v[164:167], v[234:237], v[12:15]
	s_setprio 0
	s_barrier
	s_add_i32 s23, 0, 0x18000
	s_add_i32 s25, 0, 0x1c000
	v_add_u32_e32 v176, s23, v180
	v_add_u32_e32 v185, s25, v180
	ds_read_b128 v[164:167], v176
	ds_read_b128 v[168:171], v176 offset:1024
	ds_read_b128 v[172:175], v176 offset:2048
	ds_read_b128 v[176:179], v176 offset:3072
	ds_read_b128 v[186:189], v185
	ds_read_b128 v[190:193], v185 offset:1024
	ds_read_b128 v[194:197], v185 offset:2048
	ds_read_b128 v[198:201], v185 offset:3072
	s_add_u32 s14, s14, 0x80000
	s_addc_u32 s15, s15, 0
	s_mov_b32 m0, s53
	v_lshl_add_u64 v[248:249], s[14:15], 0, v[134:135]
	ds_read_b128 v[208:211], v184 offset:32768
	ds_read_b128 v[212:215], v184 offset:33792
	ds_read_b128 v[216:219], v184 offset:34816
	ds_read_b128 v[220:223], v184 offset:35840
	ds_read_b128 v[224:227], v184 offset:36864
	ds_read_b128 v[230:233], v184 offset:37888
	ds_read_b128 v[234:237], v184 offset:38912
	ds_read_b128 v[238:241], v184 offset:39936
	global_load_lds_dwordx4 v[248:249], off
	v_lshl_add_u64 v[248:249], s[14:15], 0, v[130:131]
	s_mov_b32 m0, s54
	s_nop 0
	global_load_lds_dwordx4 v[248:249], off
	s_waitcnt vmcnt(8)
	s_waitcnt lgkmcnt(0)
	s_barrier
	s_setprio 1
	s_waitcnt lgkmcnt(0)
	v_mfma_f32_16x16x32_bf16 v[120:123], v[164:167], v[208:211], v[120:123]
	v_mfma_f32_16x16x32_bf16 v[120:123], v[168:171], v[212:215], v[120:123]
	v_mfma_f32_16x16x32_bf16 v[116:119], v[176:179], v[212:215], v[116:119]
	v_mfma_f32_16x16x32_bf16 v[116:119], v[172:175], v[208:211], v[116:119]
	v_mfma_f32_16x16x32_bf16 v[124:127], v[186:189], v[208:211], v[124:127]
	v_mfma_f32_16x16x32_bf16 v[124:127], v[190:193], v[212:215], v[124:127]
	v_mfma_f32_16x16x32_bf16 v[112:115], v[198:201], v[212:215], v[112:115]
	v_mfma_f32_16x16x32_bf16 v[112:115], v[194:197], v[208:211], v[112:115]
	v_mfma_f32_16x16x32_bf16 v[96:99], v[194:197], v[216:219], v[96:99]
	v_mfma_f32_16x16x32_bf16 v[96:99], v[198:201], v[220:223], v[96:99]
	v_mfma_f32_16x16x32_bf16 v[104:107], v[190:193], v[220:223], v[104:107]
	v_mfma_f32_16x16x32_bf16 v[104:107], v[186:189], v[216:219], v[104:107]
	v_mfma_f32_16x16x32_bf16 v[100:103], v[172:175], v[216:219], v[100:103]
	v_mfma_f32_16x16x32_bf16 v[100:103], v[176:179], v[220:223], v[100:103]
	v_mfma_f32_16x16x32_bf16 v[108:111], v[168:171], v[220:223], v[108:111]
	v_mfma_f32_16x16x32_bf16 v[108:111], v[164:167], v[216:219], v[108:111]
	v_mfma_f32_16x16x32_bf16 v[92:95], v[164:167], v[224:227], v[92:95]
	v_mfma_f32_16x16x32_bf16 v[92:95], v[168:171], v[230:233], v[92:95]
	v_mfma_f32_16x16x32_bf16 v[84:87], v[176:179], v[230:233], v[84:87]
	v_mfma_f32_16x16x32_bf16 v[84:87], v[172:175], v[224:227], v[84:87]
	v_mfma_f32_16x16x32_bf16 v[88:91], v[186:189], v[224:227], v[88:91]
	v_mfma_f32_16x16x32_bf16 v[88:91], v[190:193], v[230:233], v[88:91]
	v_mfma_f32_16x16x32_bf16 v[80:83], v[198:201], v[230:233], v[80:83]
	v_mfma_f32_16x16x32_bf16 v[80:83], v[194:197], v[224:227], v[80:83]
	v_mfma_f32_16x16x32_bf16 v[64:67], v[194:197], v[234:237], v[64:67]
	v_mfma_f32_16x16x32_bf16 v[64:67], v[198:201], v[238:241], v[64:67]
	v_mfma_f32_16x16x32_bf16 v[72:75], v[190:193], v[238:241], v[72:75]
	v_mfma_f32_16x16x32_bf16 v[72:75], v[186:189], v[234:237], v[72:75]
	v_mfma_f32_16x16x32_bf16 v[68:71], v[172:175], v[234:237], v[68:71]
	v_mfma_f32_16x16x32_bf16 v[68:71], v[176:179], v[238:241], v[68:71]
	v_mfma_f32_16x16x32_bf16 v[76:79], v[168:171], v[238:241], v[76:79]
	v_mfma_f32_16x16x32_bf16 v[76:79], v[164:167], v[234:237], v[76:79]
	s_setprio 0
	s_barrier
; #define PG8_STAGE(bufoff, gbase, voff) do { _Pragma("unroll") for (int _i = 0; _i < 2; ++_i) \
;         __builtin_amdgcn_global_load_lds((const unsigned*)((const char*)(gbase) + (voff)[_i]), (LAS unsigned*)(lds + (bufoff) + ldsw + _i * 8192), 16, 0, 0); } while (0)
; #define PG8_LDA(dst, b, h) do { _Pragma("unroll") for (int m = 0; m < 4; ++m) _Pragma("unroll") for (int k = 0; k < 2; ++k) dst[m][k] = *(const LAS bf16x8*)(lds + PG8_SA(b, h) + aoff + m * 2048 + k * 1024); } while (0)
; #define PG8_MMA(ai, bj, At, Bt) do { __builtin_amdgcn_s_setprio(1); _Pragma("unroll") for (int m = 0; m < 4; ++m) _Pragma("unroll") for (int n = 0; n < 2; ++n) _Pragma("unroll") for (int k = 0; k < 2; ++k) \
;         acc[ai][bj][m][n] = __builtin_amdgcn_mfma_f32_16x16x32_bf16(Bt[n][k], At[m][k], acc[ai][bj][m][n], 0, 0, 0); __builtin_amdgcn_s_setprio(0); } while (0)
; #define PG8_WAIT_V(n) asm volatile("s_waitcnt vmcnt(" #n ")" ::: "memory")
; #define PG8_WAIT_L(n) asm volatile("s_waitcnt lgkmcnt(" #n ")" ::: "memory")
; #define PG8_BAR __builtin_amdgcn_s_barrier()
; #define PG8_SCHED __builtin_amdgcn_sched_barrier(0)
; template <class Epi>
; __device__ __forceinline__ void gemm_phase(LAS unsigned char* lds, const Gemm g, const StaticOrder& S, const Epi& E) {
;     ...
;             PG8_LDA(At, 1, 1); PG8_STAGE(PG8_SB(1, 0), b3, voffB); PG8_STAGE(PG8_SB(1, 1), b3 + hstepB, voffB); PG8_STAGE(PG8_SA(1, 0), a3, voffA);
;             PG8_WAIT_V(8); PG8_WAIT_L(0); PG8_BAR; PG8_MMA(1, 0, At, B0); PG8_MMA(1, 1, At, B1); PG8_BAR; PG8_SCHED;
;         }
	s_add_i32 s14, s23, s37
	v_lshl_add_u64 v[202:203], v[202:203], 0, s[4:5]
	s_mov_b32 m0, s14
	ds_read_b128 v[208:211], v184 offset:49152
	ds_read_b128 v[212:215], v184 offset:50176
	ds_read_b128 v[216:219], v184 offset:51200
	ds_read_b128 v[220:223], v184 offset:52224
	ds_read_b128 v[224:227], v184 offset:53248
	ds_read_b128 v[230:233], v184 offset:54272
	ds_read_b128 v[234:237], v184 offset:55296
	ds_read_b128 v[238:241], v184 offset:56320
	global_load_lds_dwordx4 v[202:203], off
	s_add_i32 m0, s14, 0x2000
	s_add_u32 s12, s12, 0x80080
	v_lshl_add_u64 v[202:203], v[242:243], 0, s[4:5]
	s_addc_u32 s13, s13, 0
	s_add_i32 s14, s25, s37
	global_load_lds_dwordx4 v[202:203], off
	v_lshl_add_u64 v[202:203], s[12:13], 0, v[132:133]
	s_mov_b32 m0, s14
	s_nop 0
	global_load_lds_dwordx4 v[202:203], off
	v_lshl_add_u64 v[202:203], s[12:13], 0, v[128:129]
	s_add_i32 m0, s14, 0x2000
	s_nop 0
	global_load_lds_dwordx4 v[202:203], off
	v_lshl_add_u64 v[202:203], v[244:245], 0, s[4:5]
	s_mov_b32 m0, s56
	s_nop 0
	global_load_lds_dwordx4 v[202:203], off
	v_lshl_add_u64 v[202:203], v[246:247], 0, s[4:5]
	s_mov_b32 m0, s57
	s_nop 0
	global_load_lds_dwordx4 v[202:203], off
	s_waitcnt vmcnt(8)
	s_waitcnt lgkmcnt(0)
	s_barrier
	s_setprio 1
	s_waitcnt lgkmcnt(0)
	v_mfma_f32_16x16x32_bf16 v[60:63], v[164:167], v[208:211], v[60:63]
	v_mfma_f32_16x16x32_bf16 v[60:63], v[168:171], v[212:215], v[60:63]
	v_mfma_f32_16x16x32_bf16 v[52:55], v[176:179], v[212:215], v[52:55]
	v_mfma_f32_16x16x32_bf16 v[52:55], v[172:175], v[208:211], v[52:55]
	v_mfma_f32_16x16x32_bf16 v[56:59], v[186:189], v[208:211], v[56:59]
	v_mfma_f32_16x16x32_bf16 v[56:59], v[190:193], v[212:215], v[56:59]
	v_mfma_f32_16x16x32_bf16 v[48:51], v[198:201], v[212:215], v[48:51]
	v_mfma_f32_16x16x32_bf16 v[48:51], v[194:197], v[208:211], v[48:51]
	v_mfma_f32_16x16x32_bf16 v[32:35], v[194:197], v[216:219], v[32:35]
	v_mfma_f32_16x16x32_bf16 v[32:35], v[198:201], v[220:223], v[32:35]
	v_mfma_f32_16x16x32_bf16 v[40:43], v[190:193], v[220:223], v[40:43]
	v_mfma_f32_16x16x32_bf16 v[40:43], v[186:189], v[216:219], v[40:43]
	v_mfma_f32_16x16x32_bf16 v[36:39], v[172:175], v[216:219], v[36:39]
	v_mfma_f32_16x16x32_bf16 v[36:39], v[176:179], v[220:223], v[36:39]
	v_mfma_f32_16x16x32_bf16 v[44:47], v[168:171], v[220:223], v[44:47]
	v_mfma_f32_16x16x32_bf16 v[44:47], v[164:167], v[216:219], v[44:47]
	v_mfma_f32_16x16x32_bf16 v[28:31], v[164:167], v[224:227], v[28:31]
	v_mfma_f32_16x16x32_bf16 v[28:31], v[168:171], v[230:233], v[28:31]
	v_mfma_f32_16x16x32_bf16 v[20:23], v[176:179], v[230:233], v[20:23]
	v_mfma_f32_16x16x32_bf16 v[20:23], v[172:175], v[224:227], v[20:23]
	v_mfma_f32_16x16x32_bf16 v[24:27], v[186:189], v[224:227], v[24:27]
	v_mfma_f32_16x16x32_bf16 v[24:27], v[190:193], v[230:233], v[24:27]
	v_mfma_f32_16x16x32_bf16 v[16:19], v[198:201], v[230:233], v[16:19]
	v_mfma_f32_16x16x32_bf16 v[16:19], v[194:197], v[224:227], v[16:19]
	v_mfma_f32_16x16x32_bf16 v[0:3], v[194:197], v[234:237], v[0:3]
	v_mfma_f32_16x16x32_bf16 v[0:3], v[198:201], v[238:241], v[0:3]
	v_mfma_f32_16x16x32_bf16 v[8:11], v[190:193], v[238:241], v[8:11]
	v_mfma_f32_16x16x32_bf16 v[8:11], v[186:189], v[234:237], v[8:11]
	v_mfma_f32_16x16x32_bf16 v[4:7], v[172:175], v[234:237], v[4:7]
	v_mfma_f32_16x16x32_bf16 v[4:7], v[176:179], v[238:241], v[4:7]
	v_mfma_f32_16x16x32_bf16 v[12:15], v[168:171], v[238:241], v[12:15]
	v_mfma_f32_16x16x32_bf16 v[12:15], v[164:167], v[234:237], v[12:15]
	s_setprio 0
	s_barrier
	s_add_u32 s10, s10, 0x100
	s_addc_u32 s11, s11, 0
	s_add_u32 s20, s20, 0x100
	s_addc_u32 s21, s21, 0
	s_cmp_ge_i32 s22, s55
	s_mov_b32 s12, s22
	s_cbranch_scc0 .LBB0_1131

; #define PG8_STAGE(bufoff, gbase, voff) do { _Pragma("unroll") for (int _i = 0; _i < 2; ++_i) \
;         __builtin_amdgcn_global_load_lds((const unsigned*)((const char*)(gbase) + (voff)[_i]), (LAS unsigned*)(lds + (bufoff) + ldsw + _i * 8192), 16, 0, 0); } while (0)
; #define PG8_LDA(dst, b, h) do { _Pragma("unroll") for (int m = 0; m < 4; ++m) _Pragma("unroll") for (int k = 0; k < 2; ++k) dst[m][k] = *(const LAS bf16x8*)(lds + PG8_SA(b, h) + aoff + m * 2048 + k * 1024); } while (0)
; #define PG8_LDB(dst, b, h) do { _Pragma("unroll") for (int n = 0; n < 2; ++n) _Pragma("unroll") for (int k = 0; k < 2; ++k) dst[n][k] = *(const LAS bf16x8*)(lds + PG8_SB(b, h) + boff + n * 2048 + k * 1024); } while (0)
; #define PG8_MMA(ai, bj, At, Bt) do { __builtin_amdgcn_s_setprio(1); _Pragma("unroll") for (int m = 0; m < 4; ++m) _Pragma("unroll") for (int n = 0; n < 2; ++n) _Pragma("unroll") for (int k = 0; k < 2; ++k) \
;         acc[ai][bj][m][n] = __builtin_amdgcn_mfma_f32_16x16x32_bf16(Bt[n][k], At[m][k], acc[ai][bj][m][n], 0, 0, 0); __builtin_amdgcn_s_setprio(0); } while (0)
; #define PG8_WAIT_V(n) asm volatile("s_waitcnt vmcnt(" #n ")" ::: "memory")
; #define PG8_WAIT_L(n) asm volatile("s_waitcnt lgkmcnt(" #n ")" ::: "memory")
; #define PG8_BAR __builtin_amdgcn_s_barrier()
; #define PG8_SCHED __builtin_amdgcn_sched_barrier(0)
; template <class Epi>
; __device__ __forceinline__ void gemm_phase(LAS unsigned char* lds, const Gemm g, const StaticOrder& S, const Epi& E) {
;     ...
;             PG8_LDB(B0, 0, 0); PG8_LDB(B1, 0, 1); PG8_SCHED; PG8_LDA(At, 0, 0); PG8_STAGE(PG8_SA(1, 1), a1 + hstepA, voffA);
;             PG8_WAIT_V(8); PG8_WAIT_L(0); PG8_BAR; PG8_MMA(0, 0, At, B0); PG8_MMA(0, 1, At, B1); PG8_BAR; PG8_SCHED;
;             PG8_LDA(At, 0, 1); PG8_STAGE(PG8_SB(0, 0), b2, voffB); PG8_STAGE(PG8_SB(0, 1), b2 + hstepB, voffB); PG8_STAGE(PG8_SA(0, 0), a2, voffA);
;             PG8_WAIT_V(8); PG8_WAIT_L(0); PG8_BAR; PG8_MMA(1, 0, At, B0); PG8_MMA(1, 1, At, B1); PG8_BAR; PG8_SCHED;
.LBB0_1161:
	ds_read_b128 v[152:155], v149
	ds_read_b128 v[156:159], v149 offset:1024
	ds_read_b128 v[160:163], v149 offset:2048
	ds_read_b128 v[164:167], v149 offset:3072
	ds_read_b128 v[168:171], v150
	ds_read_b128 v[172:175], v150 offset:1024
	ds_read_b128 v[176:179], v150 offset:2048
	ds_read_b128 v[180:183], v150 offset:3072
	s_add_i32 s83, s46, 2
	s_add_u32 s47, s44, 0xffff0080
	s_addc_u32 s48, s45, -1
	s_cmp_eq_u32 s65, s46
	s_cselect_b32 s46, s78, s79
	s_cselect_b32 s49, s35, s48
	s_cselect_b32 s48, s37, s47
	s_cselect_b32 s47, s39, s82
	v_lshl_add_u64 v[220:221], s[44:45], 0, v[140:141]
	s_add_i32 m0, s56, 0xc000
	ds_read_b128 v[184:187], v151
	ds_read_b128 v[188:191], v151 offset:1024
	ds_read_b128 v[192:195], v151 offset:2048
	ds_read_b128 v[196:199], v151 offset:3072
	ds_read_b128 v[200:203], v151 offset:4096
	ds_read_b128 v[208:211], v151 offset:5120
	ds_read_b128 v[212:215], v151 offset:6144
	ds_read_b128 v[216:219], v151 offset:7168
	global_load_lds_dwordx4 v[220:221], off
	v_lshl_add_u64 v[220:221], s[44:45], 0, v[142:143]
	s_add_i32 m0, s56, 0xe000
	s_nop 0
	global_load_lds_dwordx4 v[220:221], off
	s_waitcnt vmcnt(8)
	s_waitcnt lgkmcnt(0)
	s_barrier
	s_setprio 1
	s_waitcnt lgkmcnt(0)
	v_mfma_f32_16x16x32_bf16 v[120:123], v[152:155], v[184:187], v[120:123]
	v_mfma_f32_16x16x32_bf16 v[120:123], v[156:159], v[188:191], v[120:123]
	v_mfma_f32_16x16x32_bf16 v[124:127], v[164:167], v[188:191], v[124:127]
	v_mfma_f32_16x16x32_bf16 v[124:127], v[160:163], v[184:187], v[124:127]
	v_mfma_f32_16x16x32_bf16 v[116:119], v[168:171], v[184:187], v[116:119]
	v_mfma_f32_16x16x32_bf16 v[116:119], v[172:175], v[188:191], v[116:119]
	v_mfma_f32_16x16x32_bf16 v[112:115], v[180:183], v[188:191], v[112:115]
	v_mfma_f32_16x16x32_bf16 v[112:115], v[176:179], v[184:187], v[112:115]
	v_mfma_f32_16x16x32_bf16 v[96:99], v[176:179], v[192:195], v[96:99]
	v_mfma_f32_16x16x32_bf16 v[96:99], v[180:183], v[196:199], v[96:99]
	v_mfma_f32_16x16x32_bf16 v[100:103], v[172:175], v[196:199], v[100:103]
	v_mfma_f32_16x16x32_bf16 v[100:103], v[168:171], v[192:195], v[100:103]
	v_mfma_f32_16x16x32_bf16 v[104:107], v[160:163], v[192:195], v[104:107]
	v_mfma_f32_16x16x32_bf16 v[104:107], v[164:167], v[196:199], v[104:107]
	v_mfma_f32_16x16x32_bf16 v[108:111], v[156:159], v[196:199], v[108:111]
	v_mfma_f32_16x16x32_bf16 v[108:111], v[152:155], v[192:195], v[108:111]
	v_mfma_f32_16x16x32_bf16 v[92:95], v[152:155], v[200:203], v[92:95]
	v_mfma_f32_16x16x32_bf16 v[92:95], v[156:159], v[208:211], v[92:95]
	v_mfma_f32_16x16x32_bf16 v[88:91], v[164:167], v[208:211], v[88:91]
	v_mfma_f32_16x16x32_bf16 v[88:91], v[160:163], v[200:203], v[88:91]
	v_mfma_f32_16x16x32_bf16 v[84:87], v[168:171], v[200:203], v[84:87]
	v_mfma_f32_16x16x32_bf16 v[84:87], v[172:175], v[208:211], v[84:87]
	v_mfma_f32_16x16x32_bf16 v[80:83], v[180:183], v[208:211], v[80:83]
	v_mfma_f32_16x16x32_bf16 v[80:83], v[176:179], v[200:203], v[80:83]
	v_mfma_f32_16x16x32_bf16 v[64:67], v[176:179], v[212:215], v[64:67]
	v_mfma_f32_16x16x32_bf16 v[64:67], v[180:183], v[216:219], v[64:67]
	v_mfma_f32_16x16x32_bf16 v[68:71], v[172:175], v[216:219], v[68:71]
	v_mfma_f32_16x16x32_bf16 v[68:71], v[168:171], v[212:215], v[68:71]
	v_mfma_f32_16x16x32_bf16 v[72:75], v[160:163], v[212:215], v[72:75]
	v_mfma_f32_16x16x32_bf16 v[72:75], v[164:167], v[216:219], v[72:75]
	v_mfma_f32_16x16x32_bf16 v[76:79], v[156:159], v[216:219], v[76:79]
	v_mfma_f32_16x16x32_bf16 v[76:79], v[152:155], v[212:215], v[76:79]
	s_setprio 0
	s_barrier
	s_add_i32 s84, s67, s51
	v_lshl_add_u64 v[220:221], s[46:47], 0, v[130:131]
	s_mov_b32 m0, s84
	ds_read_b128 v[184:187], v151 offset:16384
	ds_read_b128 v[188:191], v151 offset:17408
	ds_read_b128 v[192:195], v151 offset:18432
	ds_read_b128 v[196:199], v151 offset:19456
	ds_read_b128 v[200:203], v151 offset:20480
	ds_read_b128 v[208:211], v151 offset:21504
	ds_read_b128 v[212:215], v151 offset:22528
	ds_read_b128 v[216:219], v151 offset:23552
	global_load_lds_dwordx4 v[220:221], off
	s_add_i32 m0, s84, 0x2000
	s_add_u32 s84, s46, 0x10000
	v_lshl_add_u64 v[222:223], s[46:47], 0, v[134:135]
	s_addc_u32 s85, s47, 0
	s_add_i32 s86, s68, s51
	global_load_lds_dwordx4 v[222:223], off
	v_lshl_add_u64 v[224:225], s[84:85], 0, v[130:131]
	s_mov_b32 m0, s86
	v_lshl_add_u64 v[226:227], s[48:49], 0, v[132:133]
	global_load_lds_dwordx4 v[224:225], off
	v_lshl_add_u64 v[224:225], s[84:85], 0, v[134:135]
	s_add_i32 m0, s86, 0x2000
	s_nop 0
	global_load_lds_dwordx4 v[224:225], off
	v_lshl_add_u64 v[224:225], s[48:49], 0, v[128:129]
	s_mov_b32 m0, s56
	s_nop 0
	global_load_lds_dwordx4 v[224:225], off
	s_mov_b32 m0, s57
	s_nop 0
	global_load_lds_dwordx4 v[226:227], off
	s_waitcnt vmcnt(8)
	s_waitcnt lgkmcnt(0)
	s_barrier
; #define PG8_STAGE(bufoff, gbase, voff) do { _Pragma("unroll") for (int _i = 0; _i < 2; ++_i) \
;         __builtin_amdgcn_global_load_lds((const unsigned*)((const char*)(gbase) + (voff)[_i]), (LAS unsigned*)(lds + (bufoff) + ldsw + _i * 8192), 16, 0, 0); } while (0)
; #define PG8_LDA(dst, b, h) do { _Pragma("unroll") for (int m = 0; m < 4; ++m) _Pragma("unroll") for (int k = 0; k < 2; ++k) dst[m][k] = *(const LAS bf16x8*)(lds + PG8_SA(b, h) + aoff + m * 2048 + k * 1024); } while (0)
; #define PG8_LDB(dst, b, h) do { _Pragma("unroll") for (int n = 0; n < 2; ++n) _Pragma("unroll") for (int k = 0; k < 2; ++k) dst[n][k] = *(const LAS bf16x8*)(lds + PG8_SB(b, h) + boff + n * 2048 + k * 1024); } while (0)
; #define PG8_MMA(ai, bj, At, Bt) do { __builtin_amdgcn_s_setprio(1); _Pragma("unroll") for (int m = 0; m < 4; ++m) _Pragma("unroll") for (int n = 0; n < 2; ++n) _Pragma("unroll") for (int k = 0; k < 2; ++k) \
;         acc[ai][bj][m][n] = __builtin_amdgcn_mfma_f32_16x16x32_bf16(Bt[n][k], At[m][k], acc[ai][bj][m][n], 0, 0, 0); __builtin_amdgcn_s_setprio(0); } while (0)
; #define PG8_WAIT_V(n) asm volatile("s_waitcnt vmcnt(" #n ")" ::: "memory")
; #define PG8_WAIT_L(n) asm volatile("s_waitcnt lgkmcnt(" #n ")" ::: "memory")
; #define PG8_BAR __builtin_amdgcn_s_barrier()
; #define PG8_SCHED __builtin_amdgcn_sched_barrier(0)
; template <class Epi>
; __device__ __forceinline__ void gemm_phase(LAS unsigned char* lds, const Gemm g, const StaticOrder& S, const Epi& E) {
;     ...
;             PG8_WAIT_V(8); PG8_WAIT_L(0); PG8_BAR; PG8_MMA(1, 0, At, B0); PG8_MMA(1, 1, At, B1); PG8_BAR; PG8_SCHED;
;             PG8_LDB(B0, 1, 0); PG8_LDB(B1, 1, 1); PG8_SCHED; PG8_LDA(At, 1, 0); PG8_STAGE(PG8_SA(0, 1), a2 + hstepA, voffA);
;             PG8_WAIT_V(8); PG8_WAIT_L(0); PG8_BAR; PG8_MMA(0, 0, At, B0); PG8_MMA(0, 1, At, B1); PG8_BAR; PG8_SCHED;
	s_setprio 1
	s_waitcnt lgkmcnt(0)
	v_mfma_f32_16x16x32_bf16 v[60:63], v[152:155], v[184:187], v[60:63]
	v_mfma_f32_16x16x32_bf16 v[60:63], v[156:159], v[188:191], v[60:63]
	v_mfma_f32_16x16x32_bf16 v[56:59], v[164:167], v[188:191], v[56:59]
	v_mfma_f32_16x16x32_bf16 v[56:59], v[160:163], v[184:187], v[56:59]
	v_mfma_f32_16x16x32_bf16 v[52:55], v[168:171], v[184:187], v[52:55]
	v_mfma_f32_16x16x32_bf16 v[52:55], v[172:175], v[188:191], v[52:55]
	v_mfma_f32_16x16x32_bf16 v[48:51], v[180:183], v[188:191], v[48:51]
	v_mfma_f32_16x16x32_bf16 v[48:51], v[176:179], v[184:187], v[48:51]
	v_mfma_f32_16x16x32_bf16 v[32:35], v[176:179], v[192:195], v[32:35]
	v_mfma_f32_16x16x32_bf16 v[32:35], v[180:183], v[196:199], v[32:35]
	v_mfma_f32_16x16x32_bf16 v[36:39], v[172:175], v[196:199], v[36:39]
	v_mfma_f32_16x16x32_bf16 v[36:39], v[168:171], v[192:195], v[36:39]
	v_mfma_f32_16x16x32_bf16 v[40:43], v[160:163], v[192:195], v[40:43]
	v_mfma_f32_16x16x32_bf16 v[40:43], v[164:167], v[196:199], v[40:43]
	v_mfma_f32_16x16x32_bf16 v[44:47], v[156:159], v[196:199], v[44:47]
	v_mfma_f32_16x16x32_bf16 v[44:47], v[152:155], v[192:195], v[44:47]
	v_mfma_f32_16x16x32_bf16 v[28:31], v[152:155], v[200:203], v[28:31]
	v_mfma_f32_16x16x32_bf16 v[28:31], v[156:159], v[208:211], v[28:31]
	v_mfma_f32_16x16x32_bf16 v[24:27], v[164:167], v[208:211], v[24:27]
	v_mfma_f32_16x16x32_bf16 v[24:27], v[160:163], v[200:203], v[24:27]
	v_mfma_f32_16x16x32_bf16 v[20:23], v[168:171], v[200:203], v[20:23]
	v_mfma_f32_16x16x32_bf16 v[20:23], v[172:175], v[208:211], v[20:23]
	v_mfma_f32_16x16x32_bf16 v[16:19], v[180:183], v[208:211], v[16:19]
	v_mfma_f32_16x16x32_bf16 v[16:19], v[176:179], v[200:203], v[16:19]
	v_mfma_f32_16x16x32_bf16 v[0:3], v[176:179], v[212:215], v[0:3]
	v_mfma_f32_16x16x32_bf16 v[0:3], v[180:183], v[216:219], v[0:3]
	v_mfma_f32_16x16x32_bf16 v[4:7], v[172:175], v[216:219], v[4:7]
	v_mfma_f32_16x16x32_bf16 v[4:7], v[168:171], v[212:215], v[4:7]
	v_mfma_f32_16x16x32_bf16 v[8:11], v[160:163], v[212:215], v[8:11]
	v_mfma_f32_16x16x32_bf16 v[8:11], v[164:167], v[216:219], v[8:11]
	v_mfma_f32_16x16x32_bf16 v[12:15], v[156:159], v[216:219], v[12:15]
	v_mfma_f32_16x16x32_bf16 v[12:15], v[152:155], v[212:215], v[12:15]
	s_setprio 0
	s_barrier
	s_add_i32 s84, 0, 0x18000
	s_add_i32 s85, 0, 0x1c000
	v_add_u32_e32 v164, s84, v148
	v_add_u32_e32 v180, s85, v148
	ds_read_b128 v[152:155], v164
	ds_read_b128 v[156:159], v164 offset:1024
	ds_read_b128 v[160:163], v164 offset:2048
	ds_read_b128 v[164:167], v164 offset:3072
	ds_read_b128 v[168:171], v180
	ds_read_b128 v[172:175], v180 offset:1024
	ds_read_b128 v[176:179], v180 offset:2048
	ds_read_b128 v[180:183], v180 offset:3072
	s_add_u32 s48, s48, 0x10000
	s_addc_u32 s49, s49, 0
	s_mov_b32 m0, s58
	v_lshl_add_u64 v[230:231], s[48:49], 0, v[128:129]
	ds_read_b128 v[184:187], v151 offset:32768
	ds_read_b128 v[188:191], v151 offset:33792
	ds_read_b128 v[192:195], v151 offset:34816
	ds_read_b128 v[196:199], v151 offset:35840
	ds_read_b128 v[200:203], v151 offset:36864
	ds_read_b128 v[208:211], v151 offset:37888
	ds_read_b128 v[212:215], v151 offset:38912
	ds_read_b128 v[216:219], v151 offset:39936
	global_load_lds_dwordx4 v[230:231], off
	v_lshl_add_u64 v[230:231], s[48:49], 0, v[132:133]
	s_mov_b32 m0, s59
	s_nop 0
	global_load_lds_dwordx4 v[230:231], off
	s_waitcnt vmcnt(8)
	s_waitcnt lgkmcnt(0)
	s_barrier
	s_setprio 1
	s_waitcnt lgkmcnt(0)
	v_mfma_f32_16x16x32_bf16 v[120:123], v[152:155], v[184:187], v[120:123]
	v_mfma_f32_16x16x32_bf16 v[120:123], v[156:159], v[188:191], v[120:123]
	v_mfma_f32_16x16x32_bf16 v[124:127], v[164:167], v[188:191], v[124:127]
	v_mfma_f32_16x16x32_bf16 v[124:127], v[160:163], v[184:187], v[124:127]
	v_mfma_f32_16x16x32_bf16 v[116:119], v[168:171], v[184:187], v[116:119]
	v_mfma_f32_16x16x32_bf16 v[116:119], v[172:175], v[188:191], v[116:119]
	v_mfma_f32_16x16x32_bf16 v[112:115], v[180:183], v[188:191], v[112:115]
	v_mfma_f32_16x16x32_bf16 v[112:115], v[176:179], v[184:187], v[112:115]
	v_mfma_f32_16x16x32_bf16 v[96:99], v[176:179], v[192:195], v[96:99]
	v_mfma_f32_16x16x32_bf16 v[96:99], v[180:183], v[196:199], v[96:99]
	v_mfma_f32_16x16x32_bf16 v[100:103], v[172:175], v[196:199], v[100:103]
	v_mfma_f32_16x16x32_bf16 v[100:103], v[168:171], v[192:195], v[100:103]
	v_mfma_f32_16x16x32_bf16 v[104:107], v[160:163], v[192:195], v[104:107]
	v_mfma_f32_16x16x32_bf16 v[104:107], v[164:167], v[196:199], v[104:107]
	v_mfma_f32_16x16x32_bf16 v[108:111], v[156:159], v[196:199], v[108:111]
	v_mfma_f32_16x16x32_bf16 v[108:111], v[152:155], v[192:195], v[108:111]
	v_mfma_f32_16x16x32_bf16 v[92:95], v[152:155], v[200:203], v[92:95]
	v_mfma_f32_16x16x32_bf16 v[92:95], v[156:159], v[208:211], v[92:95]
	v_mfma_f32_16x16x32_bf16 v[88:91], v[164:167], v[208:211], v[88:91]
	v_mfma_f32_16x16x32_bf16 v[88:91], v[160:163], v[200:203], v[88:91]
	v_mfma_f32_16x16x32_bf16 v[84:87], v[168:171], v[200:203], v[84:87]
	v_mfma_f32_16x16x32_bf16 v[84:87], v[172:175], v[208:211], v[84:87]
	v_mfma_f32_16x16x32_bf16 v[80:83], v[180:183], v[208:211], v[80:83]
	v_mfma_f32_16x16x32_bf16 v[80:83], v[176:179], v[200:203], v[80:83]
	v_mfma_f32_16x16x32_bf16 v[64:67], v[176:179], v[212:215], v[64:67]
	v_mfma_f32_16x16x32_bf16 v[64:67], v[180:183], v[216:219], v[64:67]
	v_mfma_f32_16x16x32_bf16 v[68:71], v[172:175], v[216:219], v[68:71]
	v_mfma_f32_16x16x32_bf16 v[68:71], v[168:171], v[212:215], v[68:71]
	v_mfma_f32_16x16x32_bf16 v[72:75], v[160:163], v[212:215], v[72:75]
	v_mfma_f32_16x16x32_bf16 v[72:75], v[164:167], v[216:219], v[72:75]
	v_mfma_f32_16x16x32_bf16 v[76:79], v[156:159], v[216:219], v[76:79]
	v_mfma_f32_16x16x32_bf16 v[76:79], v[152:155], v[212:215], v[76:79]
	s_setprio 0
	s_barrier
; #define PG8_STAGE(bufoff, gbase, voff) do { _Pragma("unroll") for (int _i = 0; _i < 2; ++_i) \
;         __builtin_amdgcn_global_load_lds((const unsigned*)((const char*)(gbase) + (voff)[_i]), (LAS unsigned*)(lds + (bufoff) + ldsw + _i * 8192), 16, 0, 0); } while (0)
; #define PG8_LDA(dst, b, h) do { _Pragma("unroll") for (int m = 0; m < 4; ++m) _Pragma("unroll") for (int k = 0; k < 2; ++k) dst[m][k] = *(const LAS bf16x8*)(lds + PG8_SA(b, h) + aoff + m * 2048 + k * 1024); } while (0)
; #define PG8_MMA(ai, bj, At, Bt) do { __builtin_amdgcn_s_setprio(1); _Pragma("unroll") for (int m = 0; m < 4; ++m) _Pragma("unroll") for (int n = 0; n < 2; ++n) _Pragma("unroll") for (int k = 0; k < 2; ++k) \
;         acc[ai][bj][m][n] = __builtin_amdgcn_mfma_f32_16x16x32_bf16(Bt[n][k], At[m][k], acc[ai][bj][m][n], 0, 0, 0); __builtin_amdgcn_s_setprio(0); } while (0)
; #define PG8_WAIT_V(n) asm volatile("s_waitcnt vmcnt(" #n ")" ::: "memory")
; #define PG8_WAIT_L(n) asm volatile("s_waitcnt lgkmcnt(" #n ")" ::: "memory")
; #define PG8_BAR __builtin_amdgcn_s_barrier()
; #define PG8_SCHED __builtin_amdgcn_sched_barrier(0)
; template <class Epi>
; __device__ __forceinline__ void gemm_phase(LAS unsigned char* lds, const Gemm g, const StaticOrder& S, const Epi& E) {
;     ...
;             PG8_LDA(At, 1, 1); PG8_STAGE(PG8_SB(1, 0), b3, voffB); PG8_STAGE(PG8_SB(1, 1), b3 + hstepB, voffB); PG8_STAGE(PG8_SA(1, 0), a3, voffA);
;             PG8_WAIT_V(8); PG8_WAIT_L(0); PG8_BAR; PG8_MMA(1, 0, At, B0); PG8_MMA(1, 1, At, B1); PG8_BAR; PG8_SCHED;
;         }
	s_add_i32 s48, s84, s51
	v_lshl_add_u64 v[220:221], v[220:221], 0, s[12:13]
	s_mov_b32 m0, s48
	ds_read_b128 v[184:187], v151 offset:49152
	ds_read_b128 v[188:191], v151 offset:50176
	ds_read_b128 v[192:195], v151 offset:51200
	ds_read_b128 v[196:199], v151 offset:52224
	ds_read_b128 v[200:203], v151 offset:53248
	ds_read_b128 v[208:211], v151 offset:54272
	ds_read_b128 v[212:215], v151 offset:55296
	ds_read_b128 v[216:219], v151 offset:56320
	global_load_lds_dwordx4 v[220:221], off
	s_add_i32 m0, s48, 0x2000
	s_add_u32 s46, s46, 0x10080
	v_lshl_add_u64 v[220:221], v[222:223], 0, s[12:13]
	s_addc_u32 s47, s47, 0
	s_add_i32 s48, s85, s51
	global_load_lds_dwordx4 v[220:221], off
	v_lshl_add_u64 v[220:221], s[46:47], 0, v[130:131]
	s_mov_b32 m0, s48
	s_nop 0
	global_load_lds_dwordx4 v[220:221], off
	v_lshl_add_u64 v[220:221], s[46:47], 0, v[134:135]
	s_add_i32 m0, s48, 0x2000
	s_nop 0
	global_load_lds_dwordx4 v[220:221], off
	v_lshl_add_u64 v[220:221], v[224:225], 0, s[12:13]
	s_mov_b32 m0, s63
	s_nop 0
	global_load_lds_dwordx4 v[220:221], off
	v_lshl_add_u64 v[220:221], v[226:227], 0, s[12:13]
	s_mov_b32 m0, s64
	s_nop 0
	global_load_lds_dwordx4 v[220:221], off
	s_waitcnt vmcnt(8)
	s_waitcnt lgkmcnt(0)
	s_barrier
	s_setprio 1
	s_waitcnt lgkmcnt(0)
	v_mfma_f32_16x16x32_bf16 v[60:63], v[152:155], v[184:187], v[60:63]
	v_mfma_f32_16x16x32_bf16 v[60:63], v[156:159], v[188:191], v[60:63]
	v_mfma_f32_16x16x32_bf16 v[56:59], v[164:167], v[188:191], v[56:59]
	v_mfma_f32_16x16x32_bf16 v[56:59], v[160:163], v[184:187], v[56:59]
	v_mfma_f32_16x16x32_bf16 v[52:55], v[168:171], v[184:187], v[52:55]
	v_mfma_f32_16x16x32_bf16 v[52:55], v[172:175], v[188:191], v[52:55]
	v_mfma_f32_16x16x32_bf16 v[48:51], v[180:183], v[188:191], v[48:51]
	v_mfma_f32_16x16x32_bf16 v[48:51], v[176:179], v[184:187], v[48:51]
	v_mfma_f32_16x16x32_bf16 v[32:35], v[176:179], v[192:195], v[32:35]
	v_mfma_f32_16x16x32_bf16 v[32:35], v[180:183], v[196:199], v[32:35]
	v_mfma_f32_16x16x32_bf16 v[36:39], v[172:175], v[196:199], v[36:39]
	v_mfma_f32_16x16x32_bf16 v[36:39], v[168:171], v[192:195], v[36:39]
	v_mfma_f32_16x16x32_bf16 v[40:43], v[160:163], v[192:195], v[40:43]
	v_mfma_f32_16x16x32_bf16 v[40:43], v[164:167], v[196:199], v[40:43]
	v_mfma_f32_16x16x32_bf16 v[44:47], v[156:159], v[196:199], v[44:47]
	v_mfma_f32_16x16x32_bf16 v[44:47], v[152:155], v[192:195], v[44:47]
	v_mfma_f32_16x16x32_bf16 v[28:31], v[152:155], v[200:203], v[28:31]
	v_mfma_f32_16x16x32_bf16 v[28:31], v[156:159], v[208:211], v[28:31]
	v_mfma_f32_16x16x32_bf16 v[24:27], v[164:167], v[208:211], v[24:27]
	v_mfma_f32_16x16x32_bf16 v[24:27], v[160:163], v[200:203], v[24:27]
	v_mfma_f32_16x16x32_bf16 v[20:23], v[168:171], v[200:203], v[20:23]
	v_mfma_f32_16x16x32_bf16 v[20:23], v[172:175], v[208:211], v[20:23]
	v_mfma_f32_16x16x32_bf16 v[16:19], v[180:183], v[208:211], v[16:19]
	v_mfma_f32_16x16x32_bf16 v[16:19], v[176:179], v[200:203], v[16:19]
	v_mfma_f32_16x16x32_bf16 v[0:3], v[176:179], v[212:215], v[0:3]
	v_mfma_f32_16x16x32_bf16 v[0:3], v[180:183], v[216:219], v[0:3]
	v_mfma_f32_16x16x32_bf16 v[4:7], v[172:175], v[216:219], v[4:7]
	v_mfma_f32_16x16x32_bf16 v[4:7], v[168:171], v[212:215], v[4:7]
	v_mfma_f32_16x16x32_bf16 v[8:11], v[160:163], v[212:215], v[8:11]
	v_mfma_f32_16x16x32_bf16 v[8:11], v[164:167], v[216:219], v[8:11]
	v_mfma_f32_16x16x32_bf16 v[12:15], v[156:159], v[216:219], v[12:15]
	v_mfma_f32_16x16x32_bf16 v[12:15], v[152:155], v[212:215], v[12:15]
	s_setprio 0
	s_barrier
	s_add_u32 s44, s44, 0x100
	s_addc_u32 s45, s45, 0
	s_add_u32 s79, s79, 0x100
	s_addc_u32 s82, s82, 0
	s_cmp_ge_i32 s83, s61
	s_mov_b32 s46, s83
	s_cbranch_scc0 .LBB0_1161

; #define PG8_STAGE(bufoff, gbase, voff) do { _Pragma("unroll") for (int _i = 0; _i < 2; ++_i) \
;         __builtin_amdgcn_global_load_lds((const unsigned*)((const char*)(gbase) + (voff)[_i]), (LAS unsigned*)(lds + (bufoff) + ldsw + _i * 8192), 16, 0, 0); } while (0)
; #define PG8_LDA(dst, b, h) do { _Pragma("unroll") for (int m = 0; m < 4; ++m) _Pragma("unroll") for (int k = 0; k < 2; ++k) dst[m][k] = *(const LAS bf16x8*)(lds + PG8_SA(b, h) + aoff + m * 2048 + k * 1024); } while (0)
; #define PG8_LDB(dst, b, h) do { _Pragma("unroll") for (int n = 0; n < 2; ++n) _Pragma("unroll") for (int k = 0; k < 2; ++k) dst[n][k] = *(const LAS bf16x8*)(lds + PG8_SB(b, h) + boff + n * 2048 + k * 1024); } while (0)
; #define PG8_MMA(ai, bj, At, Bt) do { __builtin_amdgcn_s_setprio(1); _Pragma("unroll") for (int m = 0; m < 4; ++m) _Pragma("unroll") for (int n = 0; n < 2; ++n) _Pragma("unroll") for (int k = 0; k < 2; ++k) \
;         acc[ai][bj][m][n] = __builtin_amdgcn_mfma_f32_16x16x32_bf16(Bt[n][k], At[m][k], acc[ai][bj][m][n], 0, 0, 0); __builtin_amdgcn_s_setprio(0); } while (0)
; #define PG8_WAIT_V(n) asm volatile("s_waitcnt vmcnt(" #n ")" ::: "memory")
; #define PG8_WAIT_L(n) asm volatile("s_waitcnt lgkmcnt(" #n ")" ::: "memory")
; #define PG8_BAR __builtin_amdgcn_s_barrier()
; #define PG8_SCHED __builtin_amdgcn_sched_barrier(0)
; template <class Epi>
; __device__ __forceinline__ void gemm_phase(LAS unsigned char* lds, const Gemm g, const StaticOrder& S, const Epi& E) {
;     ...
;             PG8_LDB(B0, 0, 0); PG8_LDB(B1, 0, 1); PG8_SCHED; PG8_LDA(At, 0, 0); PG8_STAGE(PG8_SA(1, 1), a1 + hstepA, voffA);
;             PG8_WAIT_V(8); PG8_WAIT_L(0); PG8_BAR; PG8_MMA(0, 0, At, B0); PG8_MMA(0, 1, At, B1); PG8_BAR; PG8_SCHED;
;             PG8_LDA(At, 0, 1); PG8_STAGE(PG8_SB(0, 0), b2, voffB); PG8_STAGE(PG8_SB(0, 1), b2 + hstepB, voffB); PG8_STAGE(PG8_SA(0, 0), a2, voffA);
;             PG8_WAIT_V(8); PG8_WAIT_L(0); PG8_BAR; PG8_MMA(1, 0, At, B0); PG8_MMA(1, 1, At, B1); PG8_BAR; PG8_SCHED;
.LBB0_1244:
	ds_read_b128 v[150:153], v187
	ds_read_b128 v[154:157], v187 offset:1024
	ds_read_b128 v[158:161], v187 offset:2048
	ds_read_b128 v[162:165], v187 offset:3072
	ds_read_b128 v[166:169], v188
	ds_read_b128 v[170:173], v188 offset:1024
	ds_read_b128 v[174:177], v188 offset:2048
	ds_read_b128 v[178:181], v188 offset:3072
	s_add_i32 s84, s52, 2
	s_add_u32 s12, s4, 0x100
	s_addc_u32 s13, s5, 0
	s_cmp_eq_u32 s67, s52
	s_cselect_b32 s52, s50, s1
	s_cselect_b32 s55, s49, s13
	s_cselect_b32 s54, s48, s12
	s_cselect_b32 s53, s51, s77
	v_lshl_add_u64 v[224:225], s[4:5], 0, v[142:143]
	s_add_i32 m0, s59, 0xc000
	ds_read_b128 v[182:185], v189
	ds_read_b128 v[192:195], v189 offset:1024
	ds_read_b128 v[196:199], v189 offset:2048
	ds_read_b128 v[200:203], v189 offset:3072
	ds_read_b128 v[208:211], v189 offset:4096
	ds_read_b128 v[212:215], v189 offset:5120
	ds_read_b128 v[216:219], v189 offset:6144
	ds_read_b128 v[220:223], v189 offset:7168
	global_load_lds_dwordx4 v[224:225], off
	v_lshl_add_u64 v[224:225], s[4:5], 0, v[144:145]
	s_add_i32 m0, s59, 0xe000
	s_nop 0
	global_load_lds_dwordx4 v[224:225], off
	s_waitcnt vmcnt(8)
	s_waitcnt lgkmcnt(0)
	s_barrier
	s_setprio 1
	s_waitcnt lgkmcnt(0)
	v_mfma_f32_16x16x32_bf16 v[124:127], v[150:153], v[182:185], v[124:127]
	v_mfma_f32_16x16x32_bf16 v[124:127], v[154:157], v[192:195], v[124:127]
	v_mfma_f32_16x16x32_bf16 v[120:123], v[162:165], v[192:195], v[120:123]
	v_mfma_f32_16x16x32_bf16 v[120:123], v[158:161], v[182:185], v[120:123]
	v_mfma_f32_16x16x32_bf16 v[108:111], v[166:169], v[182:185], v[108:111]
	v_mfma_f32_16x16x32_bf16 v[108:111], v[170:173], v[192:195], v[108:111]
	v_mfma_f32_16x16x32_bf16 v[100:103], v[178:181], v[192:195], v[100:103]
	v_mfma_f32_16x16x32_bf16 v[100:103], v[174:177], v[182:185], v[100:103]
	v_mfma_f32_16x16x32_bf16 v[84:87], v[174:177], v[196:199], v[84:87]
	v_mfma_f32_16x16x32_bf16 v[84:87], v[178:181], v[200:203], v[84:87]
	v_mfma_f32_16x16x32_bf16 v[92:95], v[170:173], v[200:203], v[92:95]
	v_mfma_f32_16x16x32_bf16 v[92:95], v[166:169], v[196:199], v[92:95]
	v_mfma_f32_16x16x32_bf16 v[112:115], v[158:161], v[196:199], v[112:115]
	v_mfma_f32_16x16x32_bf16 v[112:115], v[162:165], v[200:203], v[112:115]
	v_mfma_f32_16x16x32_bf16 v[116:119], v[154:157], v[200:203], v[116:119]
	v_mfma_f32_16x16x32_bf16 v[116:119], v[150:153], v[196:199], v[116:119]
	v_mfma_f32_16x16x32_bf16 v[104:107], v[150:153], v[208:211], v[104:107]
	v_mfma_f32_16x16x32_bf16 v[104:107], v[154:157], v[212:215], v[104:107]
	v_mfma_f32_16x16x32_bf16 v[96:99], v[162:165], v[212:215], v[96:99]
	v_mfma_f32_16x16x32_bf16 v[96:99], v[158:161], v[208:211], v[96:99]
	v_mfma_f32_16x16x32_bf16 v[76:79], v[166:169], v[208:211], v[76:79]
	v_mfma_f32_16x16x32_bf16 v[76:79], v[170:173], v[212:215], v[76:79]
	v_mfma_f32_16x16x32_bf16 v[72:75], v[178:181], v[212:215], v[72:75]
	v_mfma_f32_16x16x32_bf16 v[72:75], v[174:177], v[208:211], v[72:75]
	v_mfma_f32_16x16x32_bf16 v[64:67], v[174:177], v[216:219], v[64:67]
	v_mfma_f32_16x16x32_bf16 v[64:67], v[178:181], v[220:223], v[64:67]
	v_mfma_f32_16x16x32_bf16 v[68:71], v[170:173], v[220:223], v[68:71]
	v_mfma_f32_16x16x32_bf16 v[68:71], v[166:169], v[216:219], v[68:71]
	v_mfma_f32_16x16x32_bf16 v[80:83], v[158:161], v[216:219], v[80:83]
	v_mfma_f32_16x16x32_bf16 v[80:83], v[162:165], v[220:223], v[80:83]
	v_mfma_f32_16x16x32_bf16 v[88:91], v[154:157], v[220:223], v[88:91]
	v_mfma_f32_16x16x32_bf16 v[88:91], v[150:153], v[216:219], v[88:91]
	s_setprio 0
	s_barrier
	s_add_i32 s4, s70, s58
	v_lshl_add_u64 v[224:225], s[52:53], 0, v[130:131]
	s_mov_b32 m0, s4
	ds_read_b128 v[182:185], v189 offset:16384
	ds_read_b128 v[192:195], v189 offset:17408
	ds_read_b128 v[196:199], v189 offset:18432
	ds_read_b128 v[200:203], v189 offset:19456
	ds_read_b128 v[208:211], v189 offset:20480
	ds_read_b128 v[212:215], v189 offset:21504
	ds_read_b128 v[216:219], v189 offset:22528
	ds_read_b128 v[220:223], v189 offset:23552
	global_load_lds_dwordx4 v[224:225], off
	s_add_i32 m0, s4, 0x2000
	s_add_u32 s4, s52, 0x158000
	v_lshl_add_u64 v[226:227], s[52:53], 0, v[134:135]
	s_addc_u32 s5, s53, 0
	s_add_i32 s85, s71, s58
	global_load_lds_dwordx4 v[226:227], off
	v_lshl_add_u64 v[230:231], s[4:5], 0, v[130:131]
	s_mov_b32 m0, s85
	v_lshl_add_u64 v[232:233], s[54:55], 0, v[132:133]
	global_load_lds_dwordx4 v[230:231], off
	v_lshl_add_u64 v[230:231], s[4:5], 0, v[134:135]
	s_add_i32 m0, s85, 0x2000
	s_nop 0
	global_load_lds_dwordx4 v[230:231], off
	v_lshl_add_u64 v[230:231], s[54:55], 0, v[128:129]
	s_mov_b32 m0, s59
	s_nop 0
	global_load_lds_dwordx4 v[230:231], off
	s_mov_b32 m0, s60
	s_nop 0
	global_load_lds_dwordx4 v[232:233], off
	s_waitcnt vmcnt(8)
	s_waitcnt lgkmcnt(0)
	s_barrier
; #define PG8_STAGE(bufoff, gbase, voff) do { _Pragma("unroll") for (int _i = 0; _i < 2; ++_i) \
;         __builtin_amdgcn_global_load_lds((const unsigned*)((const char*)(gbase) + (voff)[_i]), (LAS unsigned*)(lds + (bufoff) + ldsw + _i * 8192), 16, 0, 0); } while (0)
; #define PG8_LDA(dst, b, h) do { _Pragma("unroll") for (int m = 0; m < 4; ++m) _Pragma("unroll") for (int k = 0; k < 2; ++k) dst[m][k] = *(const LAS bf16x8*)(lds + PG8_SA(b, h) + aoff + m * 2048 + k * 1024); } while (0)
; #define PG8_LDB(dst, b, h) do { _Pragma("unroll") for (int n = 0; n < 2; ++n) _Pragma("unroll") for (int k = 0; k < 2; ++k) dst[n][k] = *(const LAS bf16x8*)(lds + PG8_SB(b, h) + boff + n * 2048 + k * 1024); } while (0)
; #define PG8_MMA(ai, bj, At, Bt) do { __builtin_amdgcn_s_setprio(1); _Pragma("unroll") for (int m = 0; m < 4; ++m) _Pragma("unroll") for (int n = 0; n < 2; ++n) _Pragma("unroll") for (int k = 0; k < 2; ++k) \
;         acc[ai][bj][m][n] = __builtin_amdgcn_mfma_f32_16x16x32_bf16(Bt[n][k], At[m][k], acc[ai][bj][m][n], 0, 0, 0); __builtin_amdgcn_s_setprio(0); } while (0)
; #define PG8_WAIT_V(n) asm volatile("s_waitcnt vmcnt(" #n ")" ::: "memory")
; #define PG8_WAIT_L(n) asm volatile("s_waitcnt lgkmcnt(" #n ")" ::: "memory")
; #define PG8_BAR __builtin_amdgcn_s_barrier()
; #define PG8_SCHED __builtin_amdgcn_sched_barrier(0)
; template <class Epi>
; __device__ __forceinline__ void gemm_phase(LAS unsigned char* lds, const Gemm g, const StaticOrder& S, const Epi& E) {
;     ...
;             PG8_WAIT_V(8); PG8_WAIT_L(0); PG8_BAR; PG8_MMA(1, 0, At, B0); PG8_MMA(1, 1, At, B1); PG8_BAR; PG8_SCHED;
;             PG8_LDB(B0, 1, 0); PG8_LDB(B1, 1, 1); PG8_SCHED; PG8_LDA(At, 1, 0); PG8_STAGE(PG8_SA(0, 1), a2 + hstepA, voffA);
;             PG8_WAIT_V(8); PG8_WAIT_L(0); PG8_BAR; PG8_MMA(0, 0, At, B0); PG8_MMA(0, 1, At, B1); PG8_BAR; PG8_SCHED;
	s_setprio 1
	s_waitcnt lgkmcnt(0)
	v_mfma_f32_16x16x32_bf16 v[60:63], v[150:153], v[182:185], v[60:63]
	v_mfma_f32_16x16x32_bf16 v[60:63], v[154:157], v[192:195], v[60:63]
	v_mfma_f32_16x16x32_bf16 v[56:59], v[162:165], v[192:195], v[56:59]
	v_mfma_f32_16x16x32_bf16 v[56:59], v[158:161], v[182:185], v[56:59]
	v_mfma_f32_16x16x32_bf16 v[44:47], v[166:169], v[182:185], v[44:47]
	v_mfma_f32_16x16x32_bf16 v[44:47], v[170:173], v[192:195], v[44:47]
	v_mfma_f32_16x16x32_bf16 v[36:39], v[178:181], v[192:195], v[36:39]
	v_mfma_f32_16x16x32_bf16 v[36:39], v[174:177], v[182:185], v[36:39]
	v_mfma_f32_16x16x32_bf16 v[20:23], v[174:177], v[196:199], v[20:23]
	v_mfma_f32_16x16x32_bf16 v[20:23], v[178:181], v[200:203], v[20:23]
	v_mfma_f32_16x16x32_bf16 v[28:31], v[170:173], v[200:203], v[28:31]
	v_mfma_f32_16x16x32_bf16 v[28:31], v[166:169], v[196:199], v[28:31]
	v_mfma_f32_16x16x32_bf16 v[48:51], v[158:161], v[196:199], v[48:51]
	v_mfma_f32_16x16x32_bf16 v[48:51], v[162:165], v[200:203], v[48:51]
	v_mfma_f32_16x16x32_bf16 v[52:55], v[154:157], v[200:203], v[52:55]
	v_mfma_f32_16x16x32_bf16 v[52:55], v[150:153], v[196:199], v[52:55]
	v_mfma_f32_16x16x32_bf16 v[40:43], v[150:153], v[208:211], v[40:43]
	v_mfma_f32_16x16x32_bf16 v[40:43], v[154:157], v[212:215], v[40:43]
	v_mfma_f32_16x16x32_bf16 v[32:35], v[162:165], v[212:215], v[32:35]
	v_mfma_f32_16x16x32_bf16 v[32:35], v[158:161], v[208:211], v[32:35]
	v_mfma_f32_16x16x32_bf16 v[12:15], v[166:169], v[208:211], v[12:15]
	v_mfma_f32_16x16x32_bf16 v[12:15], v[170:173], v[212:215], v[12:15]
	v_mfma_f32_16x16x32_bf16 v[8:11], v[178:181], v[212:215], v[8:11]
	v_mfma_f32_16x16x32_bf16 v[8:11], v[174:177], v[208:211], v[8:11]
	v_mfma_f32_16x16x32_bf16 v[0:3], v[174:177], v[216:219], v[0:3]
	v_mfma_f32_16x16x32_bf16 v[0:3], v[178:181], v[220:223], v[0:3]
	v_mfma_f32_16x16x32_bf16 v[4:7], v[170:173], v[220:223], v[4:7]
	v_mfma_f32_16x16x32_bf16 v[4:7], v[166:169], v[216:219], v[4:7]
	v_mfma_f32_16x16x32_bf16 v[16:19], v[158:161], v[216:219], v[16:19]
	v_mfma_f32_16x16x32_bf16 v[16:19], v[162:165], v[220:223], v[16:19]
	v_mfma_f32_16x16x32_bf16 v[24:27], v[154:157], v[220:223], v[24:27]
	v_mfma_f32_16x16x32_bf16 v[24:27], v[150:153], v[216:219], v[24:27]
	s_setprio 0
	s_barrier
	s_add_i32 s85, 0, 0x18000
	s_add_i32 s86, 0, 0x1c000
	v_add_u32_e32 v162, s85, v186
	v_add_u32_e32 v178, s86, v186
	ds_read_b128 v[150:153], v162
	ds_read_b128 v[154:157], v162 offset:1024
	ds_read_b128 v[158:161], v162 offset:2048
	ds_read_b128 v[162:165], v162 offset:3072
	ds_read_b128 v[166:169], v178
	ds_read_b128 v[170:173], v178 offset:1024
	ds_read_b128 v[174:177], v178 offset:2048
	ds_read_b128 v[178:181], v178 offset:3072
	s_add_u32 s4, s54, 0x158000
	s_addc_u32 s5, s55, 0
	s_mov_b32 m0, s61
	v_lshl_add_u64 v[234:235], s[4:5], 0, v[128:129]
	ds_read_b128 v[182:185], v189 offset:32768
	ds_read_b128 v[192:195], v189 offset:33792
	ds_read_b128 v[196:199], v189 offset:34816
	ds_read_b128 v[200:203], v189 offset:35840
	ds_read_b128 v[208:211], v189 offset:36864
	ds_read_b128 v[212:215], v189 offset:37888
	ds_read_b128 v[216:219], v189 offset:38912
	ds_read_b128 v[220:223], v189 offset:39936
	global_load_lds_dwordx4 v[234:235], off
	v_lshl_add_u64 v[234:235], s[4:5], 0, v[132:133]
	s_mov_b32 m0, s62
	s_nop 0
	global_load_lds_dwordx4 v[234:235], off
	s_waitcnt vmcnt(8)
	s_waitcnt lgkmcnt(0)
	s_barrier
	s_setprio 1
	s_waitcnt lgkmcnt(0)
	v_mfma_f32_16x16x32_bf16 v[124:127], v[150:153], v[182:185], v[124:127]
	v_mfma_f32_16x16x32_bf16 v[124:127], v[154:157], v[192:195], v[124:127]
	v_mfma_f32_16x16x32_bf16 v[120:123], v[162:165], v[192:195], v[120:123]
	v_mfma_f32_16x16x32_bf16 v[120:123], v[158:161], v[182:185], v[120:123]
	v_mfma_f32_16x16x32_bf16 v[108:111], v[166:169], v[182:185], v[108:111]
	v_mfma_f32_16x16x32_bf16 v[108:111], v[170:173], v[192:195], v[108:111]
	v_mfma_f32_16x16x32_bf16 v[100:103], v[178:181], v[192:195], v[100:103]
	v_mfma_f32_16x16x32_bf16 v[100:103], v[174:177], v[182:185], v[100:103]
	v_mfma_f32_16x16x32_bf16 v[84:87], v[174:177], v[196:199], v[84:87]
	v_mfma_f32_16x16x32_bf16 v[84:87], v[178:181], v[200:203], v[84:87]
	v_mfma_f32_16x16x32_bf16 v[92:95], v[170:173], v[200:203], v[92:95]
	v_mfma_f32_16x16x32_bf16 v[92:95], v[166:169], v[196:199], v[92:95]
	v_mfma_f32_16x16x32_bf16 v[112:115], v[158:161], v[196:199], v[112:115]
	v_mfma_f32_16x16x32_bf16 v[112:115], v[162:165], v[200:203], v[112:115]
	v_mfma_f32_16x16x32_bf16 v[116:119], v[154:157], v[200:203], v[116:119]
	v_mfma_f32_16x16x32_bf16 v[116:119], v[150:153], v[196:199], v[116:119]
	v_mfma_f32_16x16x32_bf16 v[104:107], v[150:153], v[208:211], v[104:107]
	v_mfma_f32_16x16x32_bf16 v[104:107], v[154:157], v[212:215], v[104:107]
	v_mfma_f32_16x16x32_bf16 v[96:99], v[162:165], v[212:215], v[96:99]
	v_mfma_f32_16x16x32_bf16 v[96:99], v[158:161], v[208:211], v[96:99]
	v_mfma_f32_16x16x32_bf16 v[76:79], v[166:169], v[208:211], v[76:79]
	v_mfma_f32_16x16x32_bf16 v[76:79], v[170:173], v[212:215], v[76:79]
	v_mfma_f32_16x16x32_bf16 v[72:75], v[178:181], v[212:215], v[72:75]
	v_mfma_f32_16x16x32_bf16 v[72:75], v[174:177], v[208:211], v[72:75]
	v_mfma_f32_16x16x32_bf16 v[64:67], v[174:177], v[216:219], v[64:67]
	v_mfma_f32_16x16x32_bf16 v[64:67], v[178:181], v[220:223], v[64:67]
	v_mfma_f32_16x16x32_bf16 v[68:71], v[170:173], v[220:223], v[68:71]
	v_mfma_f32_16x16x32_bf16 v[68:71], v[166:169], v[216:219], v[68:71]
	v_mfma_f32_16x16x32_bf16 v[80:83], v[158:161], v[216:219], v[80:83]
	v_mfma_f32_16x16x32_bf16 v[80:83], v[162:165], v[220:223], v[80:83]
	v_mfma_f32_16x16x32_bf16 v[88:91], v[154:157], v[220:223], v[88:91]
	v_mfma_f32_16x16x32_bf16 v[88:91], v[150:153], v[216:219], v[88:91]
	s_setprio 0
	s_barrier
; #define PG8_STAGE(bufoff, gbase, voff) do { _Pragma("unroll") for (int _i = 0; _i < 2; ++_i) \
;         __builtin_amdgcn_global_load_lds((const unsigned*)((const char*)(gbase) + (voff)[_i]), (LAS unsigned*)(lds + (bufoff) + ldsw + _i * 8192), 16, 0, 0); } while (0)
; #define PG8_LDA(dst, b, h) do { _Pragma("unroll") for (int m = 0; m < 4; ++m) _Pragma("unroll") for (int k = 0; k < 2; ++k) dst[m][k] = *(const LAS bf16x8*)(lds + PG8_SA(b, h) + aoff + m * 2048 + k * 1024); } while (0)
; #define PG8_MMA(ai, bj, At, Bt) do { __builtin_amdgcn_s_setprio(1); _Pragma("unroll") for (int m = 0; m < 4; ++m) _Pragma("unroll") for (int n = 0; n < 2; ++n) _Pragma("unroll") for (int k = 0; k < 2; ++k) \
;         acc[ai][bj][m][n] = __builtin_amdgcn_mfma_f32_16x16x32_bf16(Bt[n][k], At[m][k], acc[ai][bj][m][n], 0, 0, 0); __builtin_amdgcn_s_setprio(0); } while (0)
; #define PG8_WAIT_V(n) asm volatile("s_waitcnt vmcnt(" #n ")" ::: "memory")
; #define PG8_WAIT_L(n) asm volatile("s_waitcnt lgkmcnt(" #n ")" ::: "memory")
; #define PG8_BAR __builtin_amdgcn_s_barrier()
; #define PG8_SCHED __builtin_amdgcn_sched_barrier(0)
; template <class Epi>
; __device__ __forceinline__ void gemm_phase(LAS unsigned char* lds, const Gemm g, const StaticOrder& S, const Epi& E) {
;     ...
;             PG8_LDA(At, 1, 1); PG8_STAGE(PG8_SB(1, 0), b3, voffB); PG8_STAGE(PG8_SB(1, 1), b3 + hstepB, voffB); PG8_STAGE(PG8_SA(1, 0), a3, voffA);
;             PG8_WAIT_V(8); PG8_WAIT_L(0); PG8_BAR; PG8_MMA(1, 0, At, B0); PG8_MMA(1, 1, At, B1); PG8_BAR; PG8_SCHED;
;         }
	s_add_i32 s4, s85, s58
	v_lshl_add_u64 v[224:225], v[224:225], 0, s[16:17]
	s_mov_b32 m0, s4
	ds_read_b128 v[182:185], v189 offset:49152
	ds_read_b128 v[192:195], v189 offset:50176
	ds_read_b128 v[196:199], v189 offset:51200
	ds_read_b128 v[200:203], v189 offset:52224
	ds_read_b128 v[208:211], v189 offset:53248
	ds_read_b128 v[212:215], v189 offset:54272
	ds_read_b128 v[216:219], v189 offset:55296
	ds_read_b128 v[220:223], v189 offset:56320
	global_load_lds_dwordx4 v[224:225], off
	s_add_i32 m0, s4, 0x2000
	s_add_u32 s4, s52, 0x158080
	v_lshl_add_u64 v[224:225], v[226:227], 0, s[16:17]
	s_addc_u32 s5, s53, 0
	s_add_i32 s52, s86, s58
	global_load_lds_dwordx4 v[224:225], off
	v_lshl_add_u64 v[224:225], s[4:5], 0, v[130:131]
	s_mov_b32 m0, s52
	s_nop 0
	global_load_lds_dwordx4 v[224:225], off
	v_lshl_add_u64 v[224:225], s[4:5], 0, v[134:135]
	s_add_i32 m0, s52, 0x2000
	s_nop 0
	global_load_lds_dwordx4 v[224:225], off
	v_lshl_add_u64 v[224:225], v[230:231], 0, s[16:17]
	s_mov_b32 m0, s65
	s_nop 0
	global_load_lds_dwordx4 v[224:225], off
	v_lshl_add_u64 v[224:225], v[232:233], 0, s[16:17]
	s_mov_b32 m0, s66
	s_nop 0
	global_load_lds_dwordx4 v[224:225], off
	s_waitcnt vmcnt(8)
	s_waitcnt lgkmcnt(0)
	s_barrier
	s_setprio 1
	s_waitcnt lgkmcnt(0)
	v_mfma_f32_16x16x32_bf16 v[60:63], v[150:153], v[182:185], v[60:63]
	v_mfma_f32_16x16x32_bf16 v[60:63], v[154:157], v[192:195], v[60:63]
	v_mfma_f32_16x16x32_bf16 v[56:59], v[162:165], v[192:195], v[56:59]
	v_mfma_f32_16x16x32_bf16 v[56:59], v[158:161], v[182:185], v[56:59]
	v_mfma_f32_16x16x32_bf16 v[44:47], v[166:169], v[182:185], v[44:47]
	v_mfma_f32_16x16x32_bf16 v[44:47], v[170:173], v[192:195], v[44:47]
	v_mfma_f32_16x16x32_bf16 v[36:39], v[178:181], v[192:195], v[36:39]
	v_mfma_f32_16x16x32_bf16 v[36:39], v[174:177], v[182:185], v[36:39]
	v_mfma_f32_16x16x32_bf16 v[20:23], v[174:177], v[196:199], v[20:23]
	v_mfma_f32_16x16x32_bf16 v[20:23], v[178:181], v[200:203], v[20:23]
	v_mfma_f32_16x16x32_bf16 v[28:31], v[170:173], v[200:203], v[28:31]
	v_mfma_f32_16x16x32_bf16 v[28:31], v[166:169], v[196:199], v[28:31]
	v_mfma_f32_16x16x32_bf16 v[48:51], v[158:161], v[196:199], v[48:51]
	v_mfma_f32_16x16x32_bf16 v[48:51], v[162:165], v[200:203], v[48:51]
	v_mfma_f32_16x16x32_bf16 v[52:55], v[154:157], v[200:203], v[52:55]
	v_mfma_f32_16x16x32_bf16 v[52:55], v[150:153], v[196:199], v[52:55]
	v_mfma_f32_16x16x32_bf16 v[40:43], v[150:153], v[208:211], v[40:43]
	v_mfma_f32_16x16x32_bf16 v[40:43], v[154:157], v[212:215], v[40:43]
	v_mfma_f32_16x16x32_bf16 v[32:35], v[162:165], v[212:215], v[32:35]
	v_mfma_f32_16x16x32_bf16 v[32:35], v[158:161], v[208:211], v[32:35]
	v_mfma_f32_16x16x32_bf16 v[12:15], v[166:169], v[208:211], v[12:15]
	v_mfma_f32_16x16x32_bf16 v[12:15], v[170:173], v[212:215], v[12:15]
	v_mfma_f32_16x16x32_bf16 v[8:11], v[178:181], v[212:215], v[8:11]
	v_mfma_f32_16x16x32_bf16 v[8:11], v[174:177], v[208:211], v[8:11]
	v_mfma_f32_16x16x32_bf16 v[0:3], v[174:177], v[216:219], v[0:3]
	v_mfma_f32_16x16x32_bf16 v[0:3], v[178:181], v[220:223], v[0:3]
	v_mfma_f32_16x16x32_bf16 v[4:7], v[170:173], v[220:223], v[4:7]
	v_mfma_f32_16x16x32_bf16 v[4:7], v[166:169], v[216:219], v[4:7]
	v_mfma_f32_16x16x32_bf16 v[16:19], v[158:161], v[216:219], v[16:19]
	v_mfma_f32_16x16x32_bf16 v[16:19], v[162:165], v[220:223], v[16:19]
	v_mfma_f32_16x16x32_bf16 v[24:27], v[154:157], v[220:223], v[24:27]
	v_mfma_f32_16x16x32_bf16 v[24:27], v[150:153], v[216:219], v[24:27]
	s_setprio 0
	s_barrier
	s_add_u32 s1, s1, 0x100
	s_addc_u32 s77, s77, 0
	s_cmp_ge_i32 s84, s64
	s_mov_b64 s[4:5], s[12:13]
	s_mov_b32 s52, s84
	s_cbranch_scc0 .LBB0_1244
	v_pk_mul_f32 v[170:171], v[126:127], 0.5 op_sel_hi:[1,0]
	v_pk_mul_f32 v[172:173], v[124:125], 0.5 op_sel_hi:[1,0]
	v_pk_mul_f32 v[174:175], v[122:123], 0.5 op_sel_hi:[1,0]
	v_pk_mul_f32 v[176:177], v[120:121], 0.5 op_sel_hi:[1,0]
	v_pk_mul_f32 v[178:179], v[110:111], 0.5 op_sel_hi:[1,0]
	v_pk_mul_f32 v[180:181], v[108:109], 0.5 op_sel_hi:[1,0]
	v_pk_mul_f32 v[182:183], v[102:103], 0.5 op_sel_hi:[1,0]
	v_pk_mul_f32 v[184:185], v[100:101], 0.5 op_sel_hi:[1,0]
	v_pk_mul_f32 v[160:161], v[118:119], 0.5 op_sel_hi:[1,0]
	v_pk_mul_f32 v[158:159], v[116:117], 0.5 op_sel_hi:[1,0]
	v_pk_mul_f32 v[156:157], v[114:115], 0.5 op_sel_hi:[1,0]
	v_pk_mul_f32 v[154:155], v[112:113], 0.5 op_sel_hi:[1,0]
	v_pk_mul_f32 v[168:169], v[94:95], 0.5 op_sel_hi:[1,0]
	v_pk_mul_f32 v[166:167], v[92:93], 0.5 op_sel_hi:[1,0]
	v_pk_mul_f32 v[164:165], v[86:87], 0.5 op_sel_hi:[1,0]
	v_pk_mul_f32 v[162:163], v[84:85], 0.5 op_sel_hi:[1,0]
	v_pk_mul_f32 v[116:117], v[106:107], 0.5 op_sel_hi:[1,0]
	v_pk_mul_f32 v[118:119], v[104:105], 0.5 op_sel_hi:[1,0]
	v_pk_mul_f32 v[120:121], v[98:99], 0.5 op_sel_hi:[1,0]
	v_pk_mul_f32 v[122:123], v[96:97], 0.5 op_sel_hi:[1,0]
	v_pk_mul_f32 v[124:125], v[78:79], 0.5 op_sel_hi:[1,0]
	v_pk_mul_f32 v[126:127], v[76:77], 0.5 op_sel_hi:[1,0]
	v_pk_mul_f32 v[150:151], v[74:75], 0.5 op_sel_hi:[1,0]
	v_pk_mul_f32 v[152:153], v[72:73], 0.5 op_sel_hi:[1,0]
	v_pk_mul_f32 v[104:105], v[90:91], 0.5 op_sel_hi:[1,0]
	v_pk_mul_f32 v[102:103], v[88:89], 0.5 op_sel_hi:[1,0]
	v_pk_mul_f32 v[100:101], v[82:83], 0.5 op_sel_hi:[1,0]
	v_pk_mul_f32 v[98:99], v[80:81], 0.5 op_sel_hi:[1,0]
	v_pk_mul_f32 v[112:113], v[70:71], 0.5 op_sel_hi:[1,0]
	v_pk_mul_f32 v[110:111], v[68:69], 0.5 op_sel_hi:[1,0]
	v_pk_mul_f32 v[108:109], v[66:67], 0.5 op_sel_hi:[1,0]
	v_pk_mul_f32 v[106:107], v[64:65], 0.5 op_sel_hi:[1,0]
	v_pk_mul_f32 v[80:81], v[62:63], 0.5 op_sel_hi:[1,0]
	v_pk_mul_f32 v[82:83], v[60:61], 0.5 op_sel_hi:[1,0]
	v_pk_mul_f32 v[84:85], v[58:59], 0.5 op_sel_hi:[1,0]
	v_pk_mul_f32 v[86:87], v[56:57], 0.5 op_sel_hi:[1,0]
	v_pk_mul_f32 v[88:89], v[46:47], 0.5 op_sel_hi:[1,0]
	v_pk_mul_f32 v[90:91], v[44:45], 0.5 op_sel_hi:[1,0]
	v_pk_mul_f32 v[92:93], v[38:39], 0.5 op_sel_hi:[1,0]
	v_pk_mul_f32 v[94:95], v[36:37], 0.5 op_sel_hi:[1,0]
	v_pk_mul_f32 v[70:71], v[54:55], 0.5 op_sel_hi:[1,0]
	v_pk_mul_f32 v[68:69], v[52:53], 0.5 op_sel_hi:[1,0]
	v_pk_mul_f32 v[66:67], v[50:51], 0.5 op_sel_hi:[1,0]
	v_pk_mul_f32 v[64:65], v[48:49], 0.5 op_sel_hi:[1,0]
	v_pk_mul_f32 v[78:79], v[30:31], 0.5 op_sel_hi:[1,0]
	v_pk_mul_f32 v[76:77], v[28:29], 0.5 op_sel_hi:[1,0]
	v_pk_mul_f32 v[74:75], v[22:23], 0.5 op_sel_hi:[1,0]
	v_pk_mul_f32 v[72:73], v[20:21], 0.5 op_sel_hi:[1,0]
	v_pk_mul_f32 v[54:55], v[42:43], 0.5 op_sel_hi:[1,0]
	v_pk_mul_f32 v[52:53], v[40:41], 0.5 op_sel_hi:[1,0]
	v_pk_mul_f32 v[50:51], v[34:35], 0.5 op_sel_hi:[1,0]
	v_pk_mul_f32 v[48:49], v[32:33], 0.5 op_sel_hi:[1,0]
	v_pk_mul_f32 v[62:63], v[14:15], 0.5 op_sel_hi:[1,0]
	v_pk_mul_f32 v[60:61], v[12:13], 0.5 op_sel_hi:[1,0]
	v_pk_mul_f32 v[58:59], v[10:11], 0.5 op_sel_hi:[1,0]
	v_pk_mul_f32 v[56:57], v[8:9], 0.5 op_sel_hi:[1,0]
	v_pk_mul_f32 v[38:39], v[26:27], 0.5 op_sel_hi:[1,0]
	v_pk_mul_f32 v[36:37], v[24:25], 0.5 op_sel_hi:[1,0]
	v_pk_mul_f32 v[34:35], v[18:19], 0.5 op_sel_hi:[1,0]
	v_pk_mul_f32 v[32:33], v[16:17], 0.5 op_sel_hi:[1,0]
	v_pk_mul_f32 v[46:47], v[6:7], 0.5 op_sel_hi:[1,0]
	v_pk_mul_f32 v[44:45], v[4:5], 0.5 op_sel_hi:[1,0]
	v_pk_mul_f32 v[42:43], v[2:3], 0.5 op_sel_hi:[1,0]
	v_pk_mul_f32 v[40:41], v[0:1], 0.5 op_sel_hi:[1,0]

; #define PG8_STAGE(bufoff, gbase, voff) do { _Pragma("unroll") for (int _i = 0; _i < 2; ++_i) \
;         __builtin_amdgcn_global_load_lds((const unsigned*)((const char*)(gbase) + (voff)[_i]), (LAS unsigned*)(lds + (bufoff) + ldsw + _i * 8192), 16, 0, 0); } while (0)
; #define PG8_LDA(dst, b, h) do { _Pragma("unroll") for (int m = 0; m < 4; ++m) _Pragma("unroll") for (int k = 0; k < 2; ++k) dst[m][k] = *(const LAS bf16x8*)(lds + PG8_SA(b, h) + aoff + m * 2048 + k * 1024); } while (0)
; #define PG8_LDB(dst, b, h) do { _Pragma("unroll") for (int n = 0; n < 2; ++n) _Pragma("unroll") for (int k = 0; k < 2; ++k) dst[n][k] = *(const LAS bf16x8*)(lds + PG8_SB(b, h) + boff + n * 2048 + k * 1024); } while (0)
; #define PG8_MMA(ai, bj, At, Bt) do { __builtin_amdgcn_s_setprio(1); _Pragma("unroll") for (int m = 0; m < 4; ++m) _Pragma("unroll") for (int n = 0; n < 2; ++n) _Pragma("unroll") for (int k = 0; k < 2; ++k) \
;         acc[ai][bj][m][n] = __builtin_amdgcn_mfma_f32_16x16x32_bf16(Bt[n][k], At[m][k], acc[ai][bj][m][n], 0, 0, 0); __builtin_amdgcn_s_setprio(0); } while (0)
; #define PG8_WAIT_V(n) asm volatile("s_waitcnt vmcnt(" #n ")" ::: "memory")
; #define PG8_WAIT_L(n) asm volatile("s_waitcnt lgkmcnt(" #n ")" ::: "memory")
; #define PG8_BAR __builtin_amdgcn_s_barrier()
; #define PG8_SCHED __builtin_amdgcn_sched_barrier(0)
; template <class Epi>
; __device__ __forceinline__ void gemm_phase(LAS unsigned char* lds, const Gemm g, const StaticOrder& S, const Epi& E) {
;     ...
;             PG8_LDB(B0, 0, 0); PG8_LDB(B1, 0, 1); PG8_SCHED; PG8_LDA(At, 0, 0); PG8_STAGE(PG8_SA(1, 1), a1 + hstepA, voffA);
;             PG8_WAIT_V(8); PG8_WAIT_L(0); PG8_BAR; PG8_MMA(0, 0, At, B0); PG8_MMA(0, 1, At, B1); PG8_BAR; PG8_SCHED;
;             PG8_LDA(At, 0, 1); PG8_STAGE(PG8_SB(0, 0), b2, voffB); PG8_STAGE(PG8_SB(0, 1), b2 + hstepB, voffB); PG8_STAGE(PG8_SA(0, 0), a2, voffA);
;             PG8_WAIT_V(8); PG8_WAIT_L(0); PG8_BAR; PG8_MMA(1, 0, At, B0); PG8_MMA(1, 1, At, B1); PG8_BAR; PG8_SCHED;
.LBB0_1338:
	ds_read_b128 v[128:131], v173
	ds_read_b128 v[132:135], v173 offset:1024
	ds_read_b128 v[136:139], v173 offset:2048
	ds_read_b128 v[140:143], v173 offset:3072
	ds_read_b128 v[144:147], v175
	ds_read_b128 v[148:151], v175 offset:1024
	ds_read_b128 v[176:179], v175 offset:2048
	ds_read_b128 v[184:187], v175 offset:3072
	s_add_i32 s20, s10, 2
	s_add_u32 s11, s8, 0xfff80080
	s_addc_u32 s12, s9, -1
	s_cmp_eq_u32 s56, s10
	s_cselect_b32 s10, s17, s18
	s_cselect_b32 s13, s1, s12
	s_cselect_b32 s12, s15, s11
	s_cselect_b32 s11, s16, s19
	v_lshl_add_u64 v[224:225], s[8:9], 0, v[164:165]
	s_add_i32 m0, s47, 0xc000
	ds_read_b128 v[188:191], v181
	ds_read_b128 v[192:195], v181 offset:1024
	ds_read_b128 v[196:199], v181 offset:2048
	ds_read_b128 v[200:203], v181 offset:3072
	ds_read_b128 v[208:211], v181 offset:4096
	ds_read_b128 v[212:215], v181 offset:5120
	ds_read_b128 v[216:219], v181 offset:6144
	ds_read_b128 v[220:223], v181 offset:7168
	global_load_lds_dwordx4 v[224:225], off
	v_lshl_add_u64 v[224:225], s[8:9], 0, v[166:167]
	s_add_i32 m0, s47, 0xe000
	s_nop 0
	global_load_lds_dwordx4 v[224:225], off
	s_waitcnt vmcnt(8)
	s_waitcnt lgkmcnt(0)
	s_barrier
	s_setprio 1
	s_waitcnt lgkmcnt(0)
	v_mfma_f32_16x16x32_bf16 v[124:127], v[128:131], v[188:191], v[124:127]
	v_mfma_f32_16x16x32_bf16 v[124:127], v[132:135], v[192:195], v[124:127]
	v_mfma_f32_16x16x32_bf16 v[120:123], v[140:143], v[192:195], v[120:123]
	v_mfma_f32_16x16x32_bf16 v[120:123], v[136:139], v[188:191], v[120:123]
	v_mfma_f32_16x16x32_bf16 v[116:119], v[144:147], v[188:191], v[116:119]
	v_mfma_f32_16x16x32_bf16 v[116:119], v[148:151], v[192:195], v[116:119]
	v_mfma_f32_16x16x32_bf16 v[112:115], v[184:187], v[192:195], v[112:115]
	v_mfma_f32_16x16x32_bf16 v[112:115], v[176:179], v[188:191], v[112:115]
	v_mfma_f32_16x16x32_bf16 v[96:99], v[176:179], v[196:199], v[96:99]
	v_mfma_f32_16x16x32_bf16 v[96:99], v[184:187], v[200:203], v[96:99]
	v_mfma_f32_16x16x32_bf16 v[100:103], v[148:151], v[200:203], v[100:103]
	v_mfma_f32_16x16x32_bf16 v[100:103], v[144:147], v[196:199], v[100:103]
	v_mfma_f32_16x16x32_bf16 v[104:107], v[136:139], v[196:199], v[104:107]
	v_mfma_f32_16x16x32_bf16 v[104:107], v[140:143], v[200:203], v[104:107]
	v_mfma_f32_16x16x32_bf16 v[108:111], v[132:135], v[200:203], v[108:111]
	v_mfma_f32_16x16x32_bf16 v[108:111], v[128:131], v[196:199], v[108:111]
	v_mfma_f32_16x16x32_bf16 v[92:95], v[128:131], v[208:211], v[92:95]
	v_mfma_f32_16x16x32_bf16 v[92:95], v[132:135], v[212:215], v[92:95]
	v_mfma_f32_16x16x32_bf16 v[88:91], v[140:143], v[212:215], v[88:91]
	v_mfma_f32_16x16x32_bf16 v[88:91], v[136:139], v[208:211], v[88:91]
	v_mfma_f32_16x16x32_bf16 v[84:87], v[144:147], v[208:211], v[84:87]
	v_mfma_f32_16x16x32_bf16 v[84:87], v[148:151], v[212:215], v[84:87]
	v_mfma_f32_16x16x32_bf16 v[80:83], v[184:187], v[212:215], v[80:83]
	v_mfma_f32_16x16x32_bf16 v[80:83], v[176:179], v[208:211], v[80:83]
	v_mfma_f32_16x16x32_bf16 v[64:67], v[176:179], v[216:219], v[64:67]
	v_mfma_f32_16x16x32_bf16 v[64:67], v[184:187], v[220:223], v[64:67]
	v_mfma_f32_16x16x32_bf16 v[68:71], v[148:151], v[220:223], v[68:71]
	v_mfma_f32_16x16x32_bf16 v[68:71], v[144:147], v[216:219], v[68:71]
	v_mfma_f32_16x16x32_bf16 v[72:75], v[136:139], v[216:219], v[72:75]
	v_mfma_f32_16x16x32_bf16 v[72:75], v[140:143], v[220:223], v[72:75]
	v_mfma_f32_16x16x32_bf16 v[76:79], v[132:135], v[220:223], v[76:79]
	v_mfma_f32_16x16x32_bf16 v[76:79], v[128:131], v[216:219], v[76:79]
	s_setprio 0
	s_barrier
	s_add_i32 s21, s59, s46
	v_lshl_add_u64 v[224:225], s[10:11], 0, v[154:155]
	s_mov_b32 m0, s21
	ds_read_b128 v[188:191], v181 offset:16384
	ds_read_b128 v[192:195], v181 offset:17408
	ds_read_b128 v[196:199], v181 offset:18432
	ds_read_b128 v[200:203], v181 offset:19456
	ds_read_b128 v[208:211], v181 offset:20480
	ds_read_b128 v[212:215], v181 offset:21504
	ds_read_b128 v[216:219], v181 offset:22528
	ds_read_b128 v[220:223], v181 offset:23552
	global_load_lds_dwordx4 v[224:225], off
	s_add_i32 m0, s21, 0x2000
	s_add_u32 s68, s10, 0x80000
	v_lshl_add_u64 v[226:227], s[10:11], 0, v[158:159]
	s_addc_u32 s69, s11, 0
	s_add_i32 s21, s60, s46
	global_load_lds_dwordx4 v[226:227], off
	v_lshl_add_u64 v[230:231], s[68:69], 0, v[154:155]
	s_mov_b32 m0, s21
	v_lshl_add_u64 v[232:233], s[12:13], 0, v[156:157]
	global_load_lds_dwordx4 v[230:231], off
	v_lshl_add_u64 v[230:231], s[68:69], 0, v[158:159]
	s_add_i32 m0, s21, 0x2000
	s_nop 0
	global_load_lds_dwordx4 v[230:231], off
	v_lshl_add_u64 v[230:231], s[12:13], 0, v[152:153]
	s_mov_b32 m0, s47
	s_nop 0
	global_load_lds_dwordx4 v[230:231], off
	s_mov_b32 m0, s48
	s_nop 0
	global_load_lds_dwordx4 v[232:233], off
	s_waitcnt vmcnt(8)
	s_waitcnt lgkmcnt(0)
	s_barrier
; #define PG8_STAGE(bufoff, gbase, voff) do { _Pragma("unroll") for (int _i = 0; _i < 2; ++_i) \
;         __builtin_amdgcn_global_load_lds((const unsigned*)((const char*)(gbase) + (voff)[_i]), (LAS unsigned*)(lds + (bufoff) + ldsw + _i * 8192), 16, 0, 0); } while (0)
; #define PG8_LDA(dst, b, h) do { _Pragma("unroll") for (int m = 0; m < 4; ++m) _Pragma("unroll") for (int k = 0; k < 2; ++k) dst[m][k] = *(const LAS bf16x8*)(lds + PG8_SA(b, h) + aoff + m * 2048 + k * 1024); } while (0)
; #define PG8_LDB(dst, b, h) do { _Pragma("unroll") for (int n = 0; n < 2; ++n) _Pragma("unroll") for (int k = 0; k < 2; ++k) dst[n][k] = *(const LAS bf16x8*)(lds + PG8_SB(b, h) + boff + n * 2048 + k * 1024); } while (0)
; #define PG8_MMA(ai, bj, At, Bt) do { __builtin_amdgcn_s_setprio(1); _Pragma("unroll") for (int m = 0; m < 4; ++m) _Pragma("unroll") for (int n = 0; n < 2; ++n) _Pragma("unroll") for (int k = 0; k < 2; ++k) \
;         acc[ai][bj][m][n] = __builtin_amdgcn_mfma_f32_16x16x32_bf16(Bt[n][k], At[m][k], acc[ai][bj][m][n], 0, 0, 0); __builtin_amdgcn_s_setprio(0); } while (0)
; #define PG8_WAIT_V(n) asm volatile("s_waitcnt vmcnt(" #n ")" ::: "memory")
; #define PG8_WAIT_L(n) asm volatile("s_waitcnt lgkmcnt(" #n ")" ::: "memory")
; #define PG8_BAR __builtin_amdgcn_s_barrier()
; #define PG8_SCHED __builtin_amdgcn_sched_barrier(0)
; template <class Epi>
; __device__ __forceinline__ void gemm_phase(LAS unsigned char* lds, const Gemm g, const StaticOrder& S, const Epi& E) {
;     ...
;             PG8_WAIT_V(8); PG8_WAIT_L(0); PG8_BAR; PG8_MMA(1, 0, At, B0); PG8_MMA(1, 1, At, B1); PG8_BAR; PG8_SCHED;
;             PG8_LDB(B0, 1, 0); PG8_LDB(B1, 1, 1); PG8_SCHED; PG8_LDA(At, 1, 0); PG8_STAGE(PG8_SA(0, 1), a2 + hstepA, voffA);
;             PG8_WAIT_V(8); PG8_WAIT_L(0); PG8_BAR; PG8_MMA(0, 0, At, B0); PG8_MMA(0, 1, At, B1); PG8_BAR; PG8_SCHED;
	s_setprio 1
	s_waitcnt lgkmcnt(0)
	v_mfma_f32_16x16x32_bf16 v[60:63], v[128:131], v[188:191], v[60:63]
	v_mfma_f32_16x16x32_bf16 v[60:63], v[132:135], v[192:195], v[60:63]
	v_mfma_f32_16x16x32_bf16 v[56:59], v[140:143], v[192:195], v[56:59]
	v_mfma_f32_16x16x32_bf16 v[56:59], v[136:139], v[188:191], v[56:59]
	v_mfma_f32_16x16x32_bf16 v[52:55], v[144:147], v[188:191], v[52:55]
	v_mfma_f32_16x16x32_bf16 v[52:55], v[148:151], v[192:195], v[52:55]
	v_mfma_f32_16x16x32_bf16 v[48:51], v[184:187], v[192:195], v[48:51]
	v_mfma_f32_16x16x32_bf16 v[48:51], v[176:179], v[188:191], v[48:51]
	v_mfma_f32_16x16x32_bf16 v[32:35], v[176:179], v[196:199], v[32:35]
	v_mfma_f32_16x16x32_bf16 v[32:35], v[184:187], v[200:203], v[32:35]
	v_mfma_f32_16x16x32_bf16 v[36:39], v[148:151], v[200:203], v[36:39]
	v_mfma_f32_16x16x32_bf16 v[36:39], v[144:147], v[196:199], v[36:39]
	v_mfma_f32_16x16x32_bf16 v[40:43], v[136:139], v[196:199], v[40:43]
	v_mfma_f32_16x16x32_bf16 v[40:43], v[140:143], v[200:203], v[40:43]
	v_mfma_f32_16x16x32_bf16 v[44:47], v[132:135], v[200:203], v[44:47]
	v_mfma_f32_16x16x32_bf16 v[44:47], v[128:131], v[196:199], v[44:47]
	v_mfma_f32_16x16x32_bf16 v[28:31], v[128:131], v[208:211], v[28:31]
	v_mfma_f32_16x16x32_bf16 v[28:31], v[132:135], v[212:215], v[28:31]
	v_mfma_f32_16x16x32_bf16 v[24:27], v[140:143], v[212:215], v[24:27]
	v_mfma_f32_16x16x32_bf16 v[24:27], v[136:139], v[208:211], v[24:27]
	v_mfma_f32_16x16x32_bf16 v[20:23], v[144:147], v[208:211], v[20:23]
	v_mfma_f32_16x16x32_bf16 v[20:23], v[148:151], v[212:215], v[20:23]
	v_mfma_f32_16x16x32_bf16 v[16:19], v[184:187], v[212:215], v[16:19]
	v_mfma_f32_16x16x32_bf16 v[16:19], v[176:179], v[208:211], v[16:19]
	v_mfma_f32_16x16x32_bf16 v[0:3], v[176:179], v[216:219], v[0:3]
	v_mfma_f32_16x16x32_bf16 v[0:3], v[184:187], v[220:223], v[0:3]
	v_mfma_f32_16x16x32_bf16 v[4:7], v[148:151], v[220:223], v[4:7]
	v_mfma_f32_16x16x32_bf16 v[4:7], v[144:147], v[216:219], v[4:7]
	v_mfma_f32_16x16x32_bf16 v[8:11], v[136:139], v[216:219], v[8:11]
	v_mfma_f32_16x16x32_bf16 v[8:11], v[140:143], v[220:223], v[8:11]
	v_mfma_f32_16x16x32_bf16 v[12:15], v[132:135], v[220:223], v[12:15]
	v_mfma_f32_16x16x32_bf16 v[12:15], v[128:131], v[216:219], v[12:15]
	s_setprio 0
	s_barrier
	s_add_i32 s21, 0, 0x18000
	s_add_i32 s33, 0, 0x1c000
	v_add_u32_e32 v140, s21, v163
	v_add_u32_e32 v172, s33, v163
	ds_read_b128 v[128:131], v140
	ds_read_b128 v[132:135], v140 offset:1024
	ds_read_b128 v[136:139], v140 offset:2048
	ds_read_b128 v[140:143], v140 offset:3072
	ds_read_b128 v[144:147], v172
	ds_read_b128 v[148:151], v172 offset:1024
	ds_read_b128 v[176:179], v172 offset:2048
	ds_read_b128 v[184:187], v172 offset:3072
	s_add_u32 s12, s12, 0x80000
	s_addc_u32 s13, s13, 0
	s_mov_b32 m0, s49
	v_lshl_add_u64 v[234:235], s[12:13], 0, v[152:153]
	ds_read_b128 v[188:191], v181 offset:32768
	ds_read_b128 v[192:195], v181 offset:33792
	ds_read_b128 v[196:199], v181 offset:34816
	ds_read_b128 v[200:203], v181 offset:35840
	ds_read_b128 v[208:211], v181 offset:36864
	ds_read_b128 v[212:215], v181 offset:37888
	ds_read_b128 v[216:219], v181 offset:38912
	ds_read_b128 v[220:223], v181 offset:39936
	global_load_lds_dwordx4 v[234:235], off
	v_lshl_add_u64 v[234:235], s[12:13], 0, v[156:157]
	s_mov_b32 m0, s50
	s_nop 0
	global_load_lds_dwordx4 v[234:235], off
	s_waitcnt vmcnt(8)
	s_waitcnt lgkmcnt(0)
	s_barrier
	s_setprio 1
	s_waitcnt lgkmcnt(0)
	v_mfma_f32_16x16x32_bf16 v[124:127], v[128:131], v[188:191], v[124:127]
	v_mfma_f32_16x16x32_bf16 v[124:127], v[132:135], v[192:195], v[124:127]
	v_mfma_f32_16x16x32_bf16 v[120:123], v[140:143], v[192:195], v[120:123]
	v_mfma_f32_16x16x32_bf16 v[120:123], v[136:139], v[188:191], v[120:123]
	v_mfma_f32_16x16x32_bf16 v[116:119], v[144:147], v[188:191], v[116:119]
	v_mfma_f32_16x16x32_bf16 v[116:119], v[148:151], v[192:195], v[116:119]
	v_mfma_f32_16x16x32_bf16 v[112:115], v[184:187], v[192:195], v[112:115]
	v_mfma_f32_16x16x32_bf16 v[112:115], v[176:179], v[188:191], v[112:115]
	v_mfma_f32_16x16x32_bf16 v[96:99], v[176:179], v[196:199], v[96:99]
	v_mfma_f32_16x16x32_bf16 v[96:99], v[184:187], v[200:203], v[96:99]
	v_mfma_f32_16x16x32_bf16 v[100:103], v[148:151], v[200:203], v[100:103]
	v_mfma_f32_16x16x32_bf16 v[100:103], v[144:147], v[196:199], v[100:103]
	v_mfma_f32_16x16x32_bf16 v[104:107], v[136:139], v[196:199], v[104:107]
	v_mfma_f32_16x16x32_bf16 v[104:107], v[140:143], v[200:203], v[104:107]
	v_mfma_f32_16x16x32_bf16 v[108:111], v[132:135], v[200:203], v[108:111]
	v_mfma_f32_16x16x32_bf16 v[108:111], v[128:131], v[196:199], v[108:111]
	v_mfma_f32_16x16x32_bf16 v[92:95], v[128:131], v[208:211], v[92:95]
	v_mfma_f32_16x16x32_bf16 v[92:95], v[132:135], v[212:215], v[92:95]
	v_mfma_f32_16x16x32_bf16 v[88:91], v[140:143], v[212:215], v[88:91]
	v_mfma_f32_16x16x32_bf16 v[88:91], v[136:139], v[208:211], v[88:91]
	v_mfma_f32_16x16x32_bf16 v[84:87], v[144:147], v[208:211], v[84:87]
	v_mfma_f32_16x16x32_bf16 v[84:87], v[148:151], v[212:215], v[84:87]
	v_mfma_f32_16x16x32_bf16 v[80:83], v[184:187], v[212:215], v[80:83]
	v_mfma_f32_16x16x32_bf16 v[80:83], v[176:179], v[208:211], v[80:83]
	v_mfma_f32_16x16x32_bf16 v[64:67], v[176:179], v[216:219], v[64:67]
	v_mfma_f32_16x16x32_bf16 v[64:67], v[184:187], v[220:223], v[64:67]
	v_mfma_f32_16x16x32_bf16 v[68:71], v[148:151], v[220:223], v[68:71]
	v_mfma_f32_16x16x32_bf16 v[68:71], v[144:147], v[216:219], v[68:71]
	v_mfma_f32_16x16x32_bf16 v[72:75], v[136:139], v[216:219], v[72:75]
	v_mfma_f32_16x16x32_bf16 v[72:75], v[140:143], v[220:223], v[72:75]
	v_mfma_f32_16x16x32_bf16 v[76:79], v[132:135], v[220:223], v[76:79]
	v_mfma_f32_16x16x32_bf16 v[76:79], v[128:131], v[216:219], v[76:79]
	s_setprio 0
	s_barrier
; #define PG8_STAGE(bufoff, gbase, voff) do { _Pragma("unroll") for (int _i = 0; _i < 2; ++_i) \
;         __builtin_amdgcn_global_load_lds((const unsigned*)((const char*)(gbase) + (voff)[_i]), (LAS unsigned*)(lds + (bufoff) + ldsw + _i * 8192), 16, 0, 0); } while (0)
; #define PG8_LDA(dst, b, h) do { _Pragma("unroll") for (int m = 0; m < 4; ++m) _Pragma("unroll") for (int k = 0; k < 2; ++k) dst[m][k] = *(const LAS bf16x8*)(lds + PG8_SA(b, h) + aoff + m * 2048 + k * 1024); } while (0)
; #define PG8_MMA(ai, bj, At, Bt) do { __builtin_amdgcn_s_setprio(1); _Pragma("unroll") for (int m = 0; m < 4; ++m) _Pragma("unroll") for (int n = 0; n < 2; ++n) _Pragma("unroll") for (int k = 0; k < 2; ++k) \
;         acc[ai][bj][m][n] = __builtin_amdgcn_mfma_f32_16x16x32_bf16(Bt[n][k], At[m][k], acc[ai][bj][m][n], 0, 0, 0); __builtin_amdgcn_s_setprio(0); } while (0)
; #define PG8_WAIT_V(n) asm volatile("s_waitcnt vmcnt(" #n ")" ::: "memory")
; #define PG8_WAIT_L(n) asm volatile("s_waitcnt lgkmcnt(" #n ")" ::: "memory")
; #define PG8_BAR __builtin_amdgcn_s_barrier()
; #define PG8_SCHED __builtin_amdgcn_sched_barrier(0)
; template <class Epi>
; __device__ __forceinline__ void gemm_phase(LAS unsigned char* lds, const Gemm g, const StaticOrder& S, const Epi& E) {
;     ...
;             PG8_LDA(At, 1, 1); PG8_STAGE(PG8_SB(1, 0), b3, voffB); PG8_STAGE(PG8_SB(1, 1), b3 + hstepB, voffB); PG8_STAGE(PG8_SA(1, 0), a3, voffA);
;             PG8_WAIT_V(8); PG8_WAIT_L(0); PG8_BAR; PG8_MMA(1, 0, At, B0); PG8_MMA(1, 1, At, B1); PG8_BAR; PG8_SCHED;
;         }
	s_add_i32 s12, s21, s46
	v_lshl_add_u64 v[224:225], v[224:225], 0, s[28:29]
	s_mov_b32 m0, s12
	ds_read_b128 v[188:191], v181 offset:49152
	ds_read_b128 v[192:195], v181 offset:50176
	ds_read_b128 v[196:199], v181 offset:51200
	ds_read_b128 v[200:203], v181 offset:52224
	ds_read_b128 v[208:211], v181 offset:53248
	ds_read_b128 v[212:215], v181 offset:54272
	ds_read_b128 v[216:219], v181 offset:55296
	ds_read_b128 v[220:223], v181 offset:56320
	global_load_lds_dwordx4 v[224:225], off
	s_add_i32 m0, s12, 0x2000
	s_add_u32 s10, s10, 0x80080
	v_lshl_add_u64 v[224:225], v[226:227], 0, s[28:29]
	s_addc_u32 s11, s11, 0
	s_add_i32 s12, s33, s46
	global_load_lds_dwordx4 v[224:225], off
	v_lshl_add_u64 v[224:225], s[10:11], 0, v[154:155]
	s_mov_b32 m0, s12
	s_nop 0
	global_load_lds_dwordx4 v[224:225], off
	v_lshl_add_u64 v[224:225], s[10:11], 0, v[158:159]
	s_add_i32 m0, s12, 0x2000
	s_nop 0
	global_load_lds_dwordx4 v[224:225], off
	v_lshl_add_u64 v[224:225], v[230:231], 0, s[28:29]
	s_mov_b32 m0, s54
	s_nop 0
	global_load_lds_dwordx4 v[224:225], off
	v_lshl_add_u64 v[224:225], v[232:233], 0, s[28:29]
	s_mov_b32 m0, s55
	s_nop 0
	global_load_lds_dwordx4 v[224:225], off
	s_waitcnt vmcnt(8)
	s_waitcnt lgkmcnt(0)
	s_barrier
	s_setprio 1
	s_waitcnt lgkmcnt(0)
	v_mfma_f32_16x16x32_bf16 v[60:63], v[128:131], v[188:191], v[60:63]
	v_mfma_f32_16x16x32_bf16 v[60:63], v[132:135], v[192:195], v[60:63]
	v_mfma_f32_16x16x32_bf16 v[56:59], v[140:143], v[192:195], v[56:59]
	v_mfma_f32_16x16x32_bf16 v[56:59], v[136:139], v[188:191], v[56:59]
	v_mfma_f32_16x16x32_bf16 v[52:55], v[144:147], v[188:191], v[52:55]
	v_mfma_f32_16x16x32_bf16 v[52:55], v[148:151], v[192:195], v[52:55]
	v_mfma_f32_16x16x32_bf16 v[48:51], v[184:187], v[192:195], v[48:51]
	v_mfma_f32_16x16x32_bf16 v[48:51], v[176:179], v[188:191], v[48:51]
	v_mfma_f32_16x16x32_bf16 v[32:35], v[176:179], v[196:199], v[32:35]
	v_mfma_f32_16x16x32_bf16 v[32:35], v[184:187], v[200:203], v[32:35]
	v_mfma_f32_16x16x32_bf16 v[36:39], v[148:151], v[200:203], v[36:39]
	v_mfma_f32_16x16x32_bf16 v[36:39], v[144:147], v[196:199], v[36:39]
	v_mfma_f32_16x16x32_bf16 v[40:43], v[136:139], v[196:199], v[40:43]
	v_mfma_f32_16x16x32_bf16 v[40:43], v[140:143], v[200:203], v[40:43]
	v_mfma_f32_16x16x32_bf16 v[44:47], v[132:135], v[200:203], v[44:47]
	v_mfma_f32_16x16x32_bf16 v[44:47], v[128:131], v[196:199], v[44:47]
	v_mfma_f32_16x16x32_bf16 v[28:31], v[128:131], v[208:211], v[28:31]
	v_mfma_f32_16x16x32_bf16 v[28:31], v[132:135], v[212:215], v[28:31]
	v_mfma_f32_16x16x32_bf16 v[24:27], v[140:143], v[212:215], v[24:27]
	v_mfma_f32_16x16x32_bf16 v[24:27], v[136:139], v[208:211], v[24:27]
	v_mfma_f32_16x16x32_bf16 v[20:23], v[144:147], v[208:211], v[20:23]
	v_mfma_f32_16x16x32_bf16 v[20:23], v[148:151], v[212:215], v[20:23]
	v_mfma_f32_16x16x32_bf16 v[16:19], v[184:187], v[212:215], v[16:19]
	v_mfma_f32_16x16x32_bf16 v[16:19], v[176:179], v[208:211], v[16:19]
	v_mfma_f32_16x16x32_bf16 v[0:3], v[176:179], v[216:219], v[0:3]
	v_mfma_f32_16x16x32_bf16 v[0:3], v[184:187], v[220:223], v[0:3]
	v_mfma_f32_16x16x32_bf16 v[4:7], v[148:151], v[220:223], v[4:7]
	v_mfma_f32_16x16x32_bf16 v[4:7], v[144:147], v[216:219], v[4:7]
	v_mfma_f32_16x16x32_bf16 v[8:11], v[136:139], v[216:219], v[8:11]
	v_mfma_f32_16x16x32_bf16 v[8:11], v[140:143], v[220:223], v[8:11]
	v_mfma_f32_16x16x32_bf16 v[12:15], v[132:135], v[220:223], v[12:15]
	v_mfma_f32_16x16x32_bf16 v[12:15], v[128:131], v[216:219], v[12:15]
	s_setprio 0
	s_barrier
	s_add_u32 s8, s8, 0x100
	s_addc_u32 s9, s9, 0
	s_add_u32 s18, s18, 0x100
	s_addc_u32 s19, s19, 0
	s_cmp_ge_i32 s20, s53
	s_mov_b32 s10, s20
	s_cbranch_scc0 .LBB0_1338
